# grid barrier: L1 invalidate issued by wave 1 right after the workgroup's arrival (own vmcnt queue) instead of by the leader wave
# speedup vs baseline: 1.0011x; 1.0011x over previous
.LBB0_90:
	v_readlane_b32 s4, v254, 5
	s_lshl_b32 s4, s4, 8
	v_readlane_b32 s6, v254, 3
	v_readlane_b32 s7, v254, 4
	s_add_u32 s4, s6, s4
	s_addc_u32 s5, s7, 0
	v_mov_b32_e32 v1, 0x1000
	v_mov_b32_e32 v3, 1
	global_atomic_add v3, v1, v3, s[4:5] offset:1024 sc0
	v_cvt_f32_u32_e32 v1, v2
	v_sub_u32_e32 v4, 0, v2
	v_rcp_iflag_f32_e32 v1, v1
	s_nop 0
	v_mul_f32_e32 v1, 0x4f7ffffe, v1
	v_cvt_u32_f32_e32 v1, v1
	v_mul_lo_u32 v4, v4, v1
	v_mul_hi_u32 v4, v1, v4
	v_add_u32_e32 v1, v1, v4
	s_waitcnt vmcnt(0)
	v_mul_hi_u32 v1, v3, v1
	v_mul_lo_u32 v4, v1, v2
	v_sub_u32_e32 v4, v3, v4
	v_add_u32_e32 v5, 1, v1
	v_cmp_ge_u32_e32 vcc, v4, v2
	v_add_u32_e32 v3, 1, v3
	s_nop 0
	v_cndmask_b32_e32 v1, v1, v5, vcc
	v_sub_u32_e32 v5, v4, v2
	v_cndmask_b32_e32 v4, v4, v5, vcc
	v_add_u32_e32 v5, 1, v1
	v_cmp_ge_u32_e32 vcc, v4, v2
	s_nop 1
	v_cndmask_b32_e32 v1, v1, v5, vcc
	v_mul_lo_u32 v4, v2, v1
	v_add_u32_e32 v2, v4, v2
	v_cmp_ne_u32_e32 vcc, v3, v2
	s_and_saveexec_b64 s[6:7], vcc
	s_xor_b64 s[6:7], exec, s[6:7]
	s_cbranch_execz .LBB0_104
	s_waitcnt lgkmcnt(0)
	s_add_u32 s12, s28, 0x7500
	s_addc_u32 s13, s29, 0
	v_mov_b32_e32 v0, 0
	global_load_dword v0, v0, s[12:13] sc1
	s_waitcnt vmcnt(0)
	v_cmp_eq_u32_e32 vcc, v0, v1
	s_and_saveexec_b64 s[8:9], vcc
	s_cbranch_execz .LBB0_103
	s_add_u32 s10, s28, 0x4200
	s_addc_u32 s11, s29, 0
	s_mov_b32 s56, 1
	s_mov_b64 s[14:15], 0
	v_mov_b32_e32 v0, 0
	s_branch .LBB0_94

.LBB0_122:
	s_or_b64 exec, exec, s[2:3]
	s_waitcnt lgkmcnt(0)
	s_cmp_lg_u32 s33, 64
	s_cbranch_scc1 .Linvw1_skip0
	buffer_inv sc1
	s_waitcnt vmcnt(0)
.Linvw1_skip0:
	s_barrier
.LBB0_123:
	s_cmp_lt_i32 s30, 2
	s_cselect_b64 s[8:9], -1, 0
	s_add_u32 s2, s28, 0x4a0000
	s_addc_u32 s3, s29, 0
	v_writelane_b32 v254, s2, 14
	s_and_b64 s[0:1], s[8:9], s[0:1]
	s_andn2_b64 vcc, exec, s[0:1]
	v_writelane_b32 v254, s3, 15
	v_writelane_b32 v254, s97, 16
	s_cbranch_vccnz .LBB0_295
	v_mbcnt_lo_u32_b32 v232, -1, 0
	v_mbcnt_hi_u32_b32 v232, -1, v232
	s_lshr_b32 s98, s33, 6
	s_and_b32 s99, s16, 7
	s_lshl_b32 s99, s99, 3
	s_bfe_u32 s100, s16, 0x30003
	s_add_i32 s99, s99, s100
	s_lshl_b32 s99, s99, 8
	s_lshl_b32 s100, s98, 5
	s_add_i32 s99, s99, s100
	v_and_b32_e32 v233, 15, v232
	v_lshrrev_b32_e32 v234, 4, v232
	v_add_u32_e32 v235, s99, v233
	v_lshlrev_b32_e32 v236, 6, v235
	v_lshl_add_u32 v236, v234, 4, v236
	s_add_u32 s100, s28, 0x100000
	s_addc_u32 s101, s29, 0
	global_load_dwordx4 v[240:243], v236, s[100:101]
	global_load_dwordx4 v[244:247], v236, s[100:101] offset:1024
	v_lshlrev_b32_e32 v237, 2, v232
	global_load_dword v248, v237, s[62:63]
	global_load_dword v249, v237, s[64:65]
	v_xor_b32_e32 v238, 16, v232
	v_lshlrev_b32_e32 v238, 2, v238
	v_xor_b32_e32 v239, 32, v232
	v_lshlrev_b32_e32 v239, 2, v239
	v_mbcnt_lo_u32_b32 v26, -1, 0
	v_mbcnt_hi_u32_b32 v26, -1, v26
	s_cmpk_lt_i32 s16, 0x400
	v_add_u32_e32 v0, s33, v26
	s_cselect_b64 s[4:5], -1, 0
	s_cmpk_gt_i32 s16, 0x3ff
	v_readfirstlane_b32 s10, v0
	s_cbranch_scc1 .LBB0_127
	s_ashr_i32 s0, s16, 31
	s_lshr_b32 s0, s0, 29
	s_add_i32 s2, s16, s0
	s_and_b32 s0, s2, -8
	s_sub_i32 s3, s16, s0
	s_cmp_gt_i32 s3, -1
	s_cbranch_scc0 .LBB0_128
	s_lshl_b32 s6, s3, 7
	s_cbranch_execz .LBB0_129
	s_branch .LBB0_130

.LBB0_312:
	v_readlane_b32 s4, v254, 5
	s_lshl_b32 s4, s4, 8
	v_readlane_b32 s6, v254, 3
	v_readlane_b32 s7, v254, 4
	s_add_u32 s4, s6, s4
	s_addc_u32 s5, s7, 0
	v_mov_b32_e32 v1, 0x1000
	v_mov_b32_e32 v3, 1
	global_atomic_add v3, v1, v3, s[4:5] offset:1024 sc0
	v_cvt_f32_u32_e32 v1, v2
	v_sub_u32_e32 v4, 0, v2
	v_rcp_iflag_f32_e32 v1, v1
	s_nop 0
	v_mul_f32_e32 v1, 0x4f7ffffe, v1
	v_cvt_u32_f32_e32 v1, v1
	v_mul_lo_u32 v4, v4, v1
	v_mul_hi_u32 v4, v1, v4
	v_add_u32_e32 v1, v1, v4
	s_waitcnt vmcnt(0)
	v_mul_hi_u32 v1, v3, v1
	v_mul_lo_u32 v4, v1, v2
	v_sub_u32_e32 v4, v3, v4
	v_add_u32_e32 v5, 1, v1
	v_cmp_ge_u32_e32 vcc, v4, v2
	v_add_u32_e32 v3, 1, v3
	s_nop 0
	v_cndmask_b32_e32 v1, v1, v5, vcc
	v_sub_u32_e32 v5, v4, v2
	v_cndmask_b32_e32 v4, v4, v5, vcc
	v_add_u32_e32 v5, 1, v1
	v_cmp_ge_u32_e32 vcc, v4, v2
	s_nop 1
	v_cndmask_b32_e32 v1, v1, v5, vcc
	v_mul_lo_u32 v4, v2, v1
	v_add_u32_e32 v2, v4, v2
	v_cmp_ne_u32_e32 vcc, v3, v2
	s_and_saveexec_b64 s[6:7], vcc
	s_xor_b64 s[6:7], exec, s[6:7]
	s_cbranch_execz .LBB0_326
	s_waitcnt lgkmcnt(0)
	s_add_u32 s12, s28, 0x7500
	s_addc_u32 s13, s29, 0
	v_mov_b32_e32 v0, 0
	global_load_dword v0, v0, s[12:13] sc1
	s_waitcnt vmcnt(0)
	v_cmp_eq_u32_e32 vcc, v0, v1
	s_and_saveexec_b64 s[8:9], vcc
	s_cbranch_execz .LBB0_325
	s_add_u32 s10, s28, 0x4200
	s_addc_u32 s11, s29, 0
	s_mov_b32 s40, 1
	s_mov_b64 s[14:15], 0
	v_mov_b32_e32 v0, 0
	s_branch .LBB0_316

.Linvw1_skip1:
	s_barrier
.LBB0_345:
	s_cmp_lt_i32 s30, 3
	s_cselect_b64 s[6:7], -1, 0
	s_add_u32 s2, s28, 0x558000
	s_addc_u32 s3, s29, 0
	s_and_b64 s[0:1], s[6:7], s[0:1]
	v_writelane_b32 v254, s2, 17
	s_andn2_b64 vcc, exec, s[0:1]
	s_nop 0
	v_writelane_b32 v254, s3, 18
	s_cbranch_vccnz .LBB0_529
	s_add_u32 s12, s28, 0x200000
	s_addc_u32 s13, s29, 0
	s_cmp_gt_i32 s16, 31
	s_mov_b64 s[0:1], -1
	v_mbcnt_lo_u32_b32 v32, -1, 0
	v_mbcnt_hi_u32_b32 v32, -1, v32
	s_cbranch_scc0 .LBB0_365
	s_cmp_lt_u32 s16, 34
	s_cbranch_scc0 .LBB0_349
	s_waitcnt lgkmcnt(0)
	v_readlane_b32 s58, v254, 11
	v_mov_b32_e32 v21, 0
	v_readlane_b32 s59, v254, 12
	s_lshl_b32 s2, s70, 13
	s_mov_b32 s1, 0x8000
	s_mov_b32 s0, 0x358637bd
	s_add_i32 s54, s2, 0
	v_mov_b64_e32 v[4:5], s[0:1]
	global_load_dwordx4 v[0:3], v21, s[58:59]
	global_load_dwordx4 v[22:25], v21, s[58:59] offset:32
	global_load_dwordx4 v[26:29], v21, s[58:59] offset:16
	s_add_u32 s10, s28, 0x6300000
	v_readlane_b32 s0, v254, 8
	v_ashrrev_i32_e32 v33, 31, v32
	s_addc_u32 s11, s29, 0
	s_addk_i32 s0, 0xff00
	v_lshlrev_b32_e32 v17, 2, v32
	v_lshlrev_b64 v[6:7], 2, v[32:33]
	s_lshl_b32 s8, s0, 6
	v_and_b32_e32 v12, 0xffffff80, v17
	v_lshl_add_u64 v[8:9], s[62:63], 0, v[6:7]
	v_lshl_add_u64 v[6:7], s[64:65], 0, v[6:7]
	s_lshl_b32 s2, s70, 5
	s_and_b32 s55, s8, 0xffffff00
	v_and_b32_e32 v10, 31, v32
	global_load_dword v11, v[8:9], off
	s_nop 0
	global_load_dword v7, v[6:7], off
	s_and_b32 s2, s2, 0x60
	v_add_u32_e32 v6, s55, v12
	v_or3_b32 v8, v6, s2, v10
	v_readlane_b32 s60, v254, 14
	v_ashrrev_i32_e32 v9, 31, v8
	v_readlane_b32 s61, v254, 15
	s_movk_i32 s41, 0x2000
	s_movk_i32 s19, 0x4000
	v_lshl_add_u64 v[96:97], v[8:9], 2, s[60:61]
	v_add_co_u32_e32 v8, vcc, s41, v96
	s_movk_i32 s15, 0x6000
	s_nop 0
	v_addc_co_u32_e32 v9, vcc, 0, v97, vcc
	v_add_co_u32_e32 v12, vcc, s19, v96
	s_mov_b32 s3, 0xa000
	s_nop 0
	v_addc_co_u32_e32 v13, vcc, 0, v97, vcc
	v_add_co_u32_e32 v18, vcc, s15, v96
	s_mov_b32 s5, 0x3f000
	s_nop 0
	v_addc_co_u32_e32 v19, vcc, 0, v97, vcc
	v_add_co_u32_e32 v30, vcc, s1, v96
	s_mov_b32 s4, 0x3a800000
	s_nop 0
	v_addc_co_u32_e32 v31, vcc, 0, v97, vcc
	v_add_co_u32_e32 v34, vcc, s3, v96
	s_mul_hi_i32 s9, s0, 0x8040
	s_nop 0
	v_addc_co_u32_e32 v35, vcc, 0, v97, vcc
	s_mul_i32 s0, s0, 0x8040
	v_add_co_u32_e32 v14, vcc, s5, v96
	s_mov_b32 s53, 0x800000
	s_waitcnt vmcnt(5)
	v_and_b32_e32 v39, 15, v32
	s_add_u32 s56, s12, s0
	v_addc_co_u32_e32 v15, vcc, 0, v97, vcc
	v_lshlrev_b32_e32 v16, 2, v39
	s_addc_u32 s57, s13, s9
	global_load_dword v67, v[96:97], off
	s_nop 0
	global_load_dword v15, v[14:15], off
	s_nop 0
	global_load_dword v6, v16, s[56:57]
	global_load_dword v66, v[8:9], off offset:-4096
	global_load_dword v55, v[8:9], off
	global_load_dword v100, v[12:13], off offset:-4096
	global_load_dwordx4 v[92:95], v21, s[58:59] offset:48
	s_mov_b32 s2, 0x10000
	s_movk_i32 s52, 0x1000
	s_movk_i32 s40, 0x3000
	s_movk_i32 s18, 0x5000
	s_movk_i32 s14, 0x7000
	s_waitcnt vmcnt(11)
	v_pk_fma_f32 v[0:1], v[0:1], s[4:5], v[4:5] op_sel_hi:[1,0,0]
	s_nop 0
	v_mul_f32_e32 v14, 0x4b800000, v1
	v_cmp_gt_f32_e64 s[0:1], s53, v1
	v_mul_f32_e32 v10, 0x4b800000, v0
	v_cmp_gt_f32_e32 vcc, s53, v0
	v_cndmask_b32_e64 v1, v1, v14, s[0:1]
	v_rsq_f32_e32 v1, v1
	v_cndmask_b32_e32 v0, v0, v10, vcc
	v_rsq_f32_e32 v0, v0
	v_pk_fma_f32 v[2:3], v[2:3], s[4:5], v[4:5] op_sel_hi:[1,0,0]
	v_mul_f32_e32 v9, 0x45800000, v1
	v_cndmask_b32_e64 v62, v1, v9, s[0:1]
	v_mul_f32_e32 v8, 0x45800000, v0
	s_mov_b32 s0, 0xc000
	v_cndmask_b32_e32 v16, v0, v8, vcc
	v_add_co_u32_e32 v0, vcc, s0, v96
	s_mov_b32 s0, 0xe000
	s_nop 0
	v_addc_co_u32_e32 v1, vcc, 0, v97, vcc
	v_add_co_u32_e32 v8, vcc, s0, v96
	v_mul_f32_e32 v10, 0x4b800000, v2
	s_nop 0
	v_addc_co_u32_e32 v9, vcc, 0, v97, vcc
	v_cmp_gt_f32_e32 vcc, s53, v2
	v_cmp_gt_f32_e64 s[0:1], s53, v3
	global_load_dword v65, v[12:13], off
	global_load_dword v64, v[18:19], off offset:-4096
	global_load_dword v101, v[18:19], off
	global_load_dword v102, v[30:31], off offset:-4096
	global_load_dword v61, v[30:31], off
	global_load_dword v60, v[34:35], off offset:-4096
	s_nop 0
	global_load_dword v35, v[34:35], off
	s_nop 0
	global_load_dword v91, v[0:1], off offset:-4096
	v_cndmask_b32_e32 v2, v2, v10, vcc
	v_rsq_f32_e32 v10, v2
	v_mul_f32_e32 v2, 0x4b800000, v3
	v_cndmask_b32_e64 v2, v3, v2, s[0:1]
	v_rsq_f32_e32 v12, v2
	v_mul_f32_e32 v13, 0x45800000, v10
	v_cndmask_b32_e32 v58, v10, v13, vcc
	v_add_co_u32_e64 v2, s[2:3], s2, v96
	v_mul_f32_e32 v10, 0x45800000, v12
	v_cndmask_b32_e64 v54, v12, v10, s[0:1]
	s_mov_b32 s0, 0x12000
	v_add_co_u32_e32 v12, vcc, s0, v96
	s_mov_b32 s0, 0x14000
	s_nop 0
	v_addc_co_u32_e32 v13, vcc, 0, v97, vcc
	v_add_co_u32_e32 v18, vcc, s0, v96
	s_mov_b32 s0, 0x16000
	s_nop 0
	v_addc_co_u32_e32 v19, vcc, 0, v97, vcc
	v_addc_co_u32_e64 v3, s[2:3], 0, v97, s[2:3]
	global_load_dword v57, v[0:1], off
	global_load_dword v56, v[8:9], off offset:-4096
	global_load_dword v43, v[8:9], off
	global_load_dword v90, v[2:3], off offset:-4096
	global_load_dword v53, v[2:3], off
	global_load_dword v52, v[12:13], off offset:-4096
	global_load_dword v47, v[12:13], off
	global_load_dword v89, v[18:19], off offset:-4096
	v_add_co_u32_e32 v0, vcc, s0, v96
	s_waitcnt vmcnt(25)
	v_pk_fma_f32 v[2:3], v[26:27], s[4:5], v[4:5] op_sel_hi:[1,0,0]
	v_addc_co_u32_e32 v1, vcc, 0, v97, vcc
	v_mul_f32_e32 v8, 0x4b800000, v2
	v_cmp_gt_f32_e32 vcc, s53, v2
	v_cmp_gt_f32_e64 s[0:1], s53, v3
	s_mov_b32 s2, 0x18000
	v_cndmask_b32_e32 v2, v2, v8, vcc
	v_rsq_f32_e32 v8, v2
	v_mul_f32_e32 v2, 0x4b800000, v3
	v_cndmask_b32_e64 v2, v3, v2, s[0:1]
	v_rsq_f32_e32 v9, v2
	v_mul_f32_e32 v10, 0x45800000, v8
	v_cndmask_b32_e32 v50, v8, v10, vcc
	v_add_co_u32_e64 v2, s[2:3], s2, v96
	v_mul_f32_e32 v8, 0x45800000, v9
	v_cndmask_b32_e64 v46, v9, v8, s[0:1]
	s_mov_b32 s0, 0x1a000
	v_add_co_u32_e32 v8, vcc, s0, v96
	s_mov_b32 s0, 0x1c000
	s_nop 0
	v_addc_co_u32_e32 v9, vcc, 0, v97, vcc
	v_add_co_u32_e32 v12, vcc, s0, v96
	s_mov_b32 s0, 0x1e000
	s_nop 0
	v_addc_co_u32_e32 v13, vcc, 0, v97, vcc
	v_addc_co_u32_e64 v3, s[2:3], 0, v97, s[2:3]
	global_load_dword v49, v[18:19], off
	global_load_dword v48, v[0:1], off offset:-4096
	global_load_dword v87, v[0:1], off
	global_load_dword v88, v[2:3], off offset:-4096
	global_load_dword v45, v[2:3], off
	global_load_dword v44, v[8:9], off offset:-4096
	global_load_dword v85, v[8:9], off
	global_load_dword v86, v[12:13], off offset:-4096
	v_add_co_u32_e32 v0, vcc, s0, v96
	v_pk_fma_f32 v[2:3], v[28:29], s[4:5], v[4:5] op_sel_hi:[1,0,0]
	s_nop 0
	v_addc_co_u32_e32 v1, vcc, 0, v97, vcc
	v_mul_f32_e32 v8, 0x4b800000, v2
	v_cmp_gt_f32_e32 vcc, s53, v2
	v_cmp_gt_f32_e64 s[0:1], s53, v3
	s_mov_b32 s2, 0x20000
	v_cndmask_b32_e32 v2, v2, v8, vcc
	v_rsq_f32_e32 v8, v2
	v_mul_f32_e32 v2, 0x4b800000, v3
	v_cndmask_b32_e64 v2, v3, v2, s[0:1]
	v_rsq_f32_e32 v9, v2
	v_mul_f32_e32 v10, 0x45800000, v8
	v_cndmask_b32_e32 v42, v8, v10, vcc
	v_add_co_u32_e64 v2, s[2:3], s2, v96
	v_mul_f32_e32 v8, 0x45800000, v9
	v_cndmask_b32_e64 v38, v9, v8, s[0:1]
	s_mov_b32 s0, 0x22000
	v_add_co_u32_e32 v8, vcc, s0, v96
	s_mov_b32 s0, 0x24000
	s_nop 0
	v_addc_co_u32_e32 v9, vcc, 0, v97, vcc
	v_add_co_u32_e32 v18, vcc, s0, v96
	s_mov_b32 s0, 0x26000
	s_nop 0
	v_addc_co_u32_e32 v19, vcc, 0, v97, vcc
	v_addc_co_u32_e64 v3, s[2:3], 0, v97, s[2:3]
	global_load_dword v41, v[12:13], off
	global_load_dword v40, v[0:1], off offset:-4096
	global_load_dword v83, v[0:1], off
	global_load_dword v84, v[2:3], off offset:-4096
	global_load_dword v37, v[2:3], off
	global_load_dword v36, v[8:9], off offset:-4096
	global_load_dword v81, v[8:9], off
	global_load_dword v82, v[18:19], off offset:-4096
	v_add_co_u32_e32 v0, vcc, s0, v96
	v_pk_fma_f32 v[2:3], v[22:23], s[4:5], v[4:5] op_sel_hi:[1,0,0]
	s_nop 0
	v_addc_co_u32_e32 v1, vcc, 0, v97, vcc
	v_mul_f32_e32 v8, 0x4b800000, v2
	v_cmp_gt_f32_e32 vcc, s53, v2
	v_cmp_gt_f32_e64 s[0:1], s53, v3
	s_mov_b32 s2, 0x28000
	v_cndmask_b32_e32 v2, v2, v8, vcc
	v_rsq_f32_e32 v8, v2
	v_mul_f32_e32 v2, 0x4b800000, v3
	v_cndmask_b32_e64 v2, v3, v2, s[0:1]
	v_rsq_f32_e32 v9, v2
	v_mul_f32_e32 v10, 0x45800000, v8
	v_cndmask_b32_e32 v34, v8, v10, vcc
	v_add_co_u32_e64 v2, s[2:3], s2, v96
	v_mul_f32_e32 v8, 0x45800000, v9
	v_cndmask_b32_e64 v28, v9, v8, s[0:1]
	s_mov_b32 s0, 0x2a000
	v_add_co_u32_e32 v8, vcc, s0, v96
	s_mov_b32 s0, 0x2c000
	s_nop 0
	v_addc_co_u32_e32 v9, vcc, 0, v97, vcc
	v_add_co_u32_e32 v12, vcc, s0, v96
	s_mov_b32 s0, 0x2e000
	s_nop 0
	v_addc_co_u32_e32 v13, vcc, 0, v97, vcc
	v_addc_co_u32_e64 v3, s[2:3], 0, v97, s[2:3]
	global_load_dword v31, v[18:19], off
	global_load_dword v30, v[0:1], off offset:-4096
	global_load_dword v79, v[0:1], off
	global_load_dword v80, v[2:3], off offset:-4096
	global_load_dword v27, v[2:3], off
	global_load_dword v26, v[8:9], off offset:-4096
	global_load_dword v77, v[8:9], off
	global_load_dword v78, v[12:13], off offset:-4096
	v_add_co_u32_e32 v0, vcc, s0, v96
	v_pk_fma_f32 v[2:3], v[24:25], s[4:5], v[4:5] op_sel_hi:[1,0,0]
	s_nop 0
	v_addc_co_u32_e32 v1, vcc, 0, v97, vcc
	v_mul_f32_e32 v8, 0x4b800000, v2
	v_cmp_gt_f32_e32 vcc, s53, v2
	v_cmp_gt_f32_e64 s[0:1], s53, v3
	s_mov_b32 s2, 0x30000
	v_cndmask_b32_e32 v2, v2, v8, vcc
	v_rsq_f32_e32 v8, v2
	v_mul_f32_e32 v2, 0x4b800000, v3
	v_cndmask_b32_e64 v2, v3, v2, s[0:1]
	v_rsq_f32_e32 v9, v2
	v_mul_f32_e32 v10, 0x45800000, v8
	v_cndmask_b32_e32 v24, v8, v10, vcc
	v_add_co_u32_e64 v2, s[2:3], s2, v96
	v_mul_f32_e32 v8, 0x45800000, v9
	v_cndmask_b32_e64 v20, v9, v8, s[0:1]
	s_mov_b32 s0, 0x32000
	v_add_co_u32_e32 v8, vcc, s0, v96
	s_mov_b32 s0, 0x34000
	s_nop 0
	v_addc_co_u32_e32 v9, vcc, 0, v97, vcc
	v_add_co_u32_e32 v68, vcc, s0, v96
	s_mov_b32 s0, 0x36000
	s_nop 0
	v_addc_co_u32_e32 v69, vcc, 0, v97, vcc
	v_addc_co_u32_e64 v3, s[2:3], 0, v97, s[2:3]
	global_load_dword v23, v[12:13], off
	global_load_dword v22, v[0:1], off offset:-4096
	global_load_dword v75, v[0:1], off
	global_load_dword v76, v[2:3], off offset:-4096
	global_load_dword v19, v[2:3], off
	global_load_dword v18, v[8:9], off offset:-4096
	global_load_dword v73, v[8:9], off
	global_load_dword v74, v[68:69], off offset:-4096
	v_add_co_u32_e32 v0, vcc, s0, v96
	s_waitcnt vmcnt(48)
	v_pk_fma_f32 v[2:3], v[92:93], s[4:5], v[4:5] op_sel_hi:[1,0,0]
	v_addc_co_u32_e32 v1, vcc, 0, v97, vcc
	v_mul_f32_e32 v8, 0x4b800000, v2
	v_cmp_gt_f32_e32 vcc, s53, v2
	v_cmp_gt_f32_e64 s[0:1], s53, v3
	s_mov_b32 s2, 0x38000
	v_cndmask_b32_e32 v2, v2, v8, vcc
	v_rsq_f32_e32 v8, v2
	v_mul_f32_e32 v2, 0x4b800000, v3
	v_cndmask_b32_e64 v2, v3, v2, s[0:1]
	v_rsq_f32_e32 v9, v2
	v_mul_f32_e32 v10, 0x45800000, v8
	v_cndmask_b32_e32 v14, v8, v10, vcc
	v_add_co_u32_e64 v2, s[2:3], s2, v96
	v_mul_f32_e32 v8, 0x45800000, v9
	v_cndmask_b32_e64 v10, v9, v8, s[0:1]
	s_mov_b32 s0, 0x3a000
	v_add_co_u32_e32 v92, vcc, s0, v96
	s_mov_b32 s0, 0x3c000
	s_nop 0
	v_addc_co_u32_e32 v93, vcc, 0, v97, vcc
	v_add_co_u32_e32 v98, vcc, s0, v96
	s_mov_b32 s0, 0x3e000
	s_nop 0
	v_addc_co_u32_e32 v99, vcc, 0, v97, vcc
	v_mbcnt_lo_u32_b32 v25, -1, 0
	v_addc_co_u32_e64 v3, s[2:3], 0, v97, s[2:3]
	global_load_dword v13, v[68:69], off
	global_load_dword v12, v[0:1], off offset:-4096
	global_load_dword v71, v[0:1], off
	global_load_dword v72, v[2:3], off offset:-4096
	global_load_dword v9, v[2:3], off
	global_load_dword v8, v[92:93], off offset:-4096
	global_load_dword v69, v[92:93], off
	global_load_dword v70, v[98:99], off offset:-4096
	v_add_co_u32_e32 v0, vcc, s0, v96
	v_mbcnt_hi_u32_b32 v63, -1, v25
	s_nop 0
	v_addc_co_u32_e32 v1, vcc, 0, v97, vcc
	v_and_b32_e32 v25, 0x70, v63
	v_add_u32_e32 v29, -1, v63
	v_cmp_lt_i32_e32 vcc, v29, v25
	v_pk_fma_f32 v[2:3], v[94:95], s[4:5], v[4:5] op_sel_hi:[1,0,0]
	v_cmp_gt_u32_e64 s[4:5], 2, v39
	v_cndmask_b32_e32 v29, v29, v63, vcc
	v_lshlrev_b32_e32 v29, 2, v29
	ds_bpermute_b32 v29, v29, v6
	v_mul_f32_e32 v51, 0x4b800000, v2
	v_cmp_gt_f32_e64 s[0:1], s53, v2
	v_cmp_eq_u32_e32 vcc, 0, v39
	v_pk_mul_f32 v[92:93], v[66:67], v[16:17] op_sel_hi:[1,0]
	v_cndmask_b32_e64 v2, v2, v51, s[0:1]
	v_rsq_f32_e32 v51, v2
	s_waitcnt lgkmcnt(0)
	v_add_f32_e32 v2, v6, v29
	v_cndmask_b32_e32 v2, v2, v6, vcc
	v_add_u32_e32 v6, -2, v63
	v_cmp_lt_i32_e64 s[2:3], v6, v25
	v_mul_f32_e32 v29, 0x4b800000, v3
	v_pk_mul_f32 v[66:67], v[92:93], v[92:93]
	v_cndmask_b32_e64 v6, v6, v63, s[2:3]
	v_lshlrev_b32_e32 v6, 2, v6
	ds_bpermute_b32 v6, v6, v2
	v_cmp_gt_f32_e64 s[2:3], s53, v3
	v_mov_b32_e32 v95, 0
	v_mov_b32_e32 v94, 0
	v_cndmask_b32_e64 v3, v3, v29, s[2:3]
	v_rsq_f32_e32 v29, v3
	s_waitcnt lgkmcnt(0)
	v_add_f32_e32 v3, v2, v6
	v_cndmask_b32_e64 v59, v3, v2, s[4:5]
	v_add_u32_e32 v2, -4, v63
	v_cmp_lt_i32_e64 s[4:5], v2, v25
	v_mov_b32_dpp v95, v67 quad_perm:[1,0,3,2] row_mask:0xf bank_mask:0xf
	v_mov_b32_dpp v94, v66 quad_perm:[1,0,3,2] row_mask:0xf bank_mask:0xf
	v_cndmask_b32_e64 v2, v2, v63, s[4:5]
	v_lshlrev_b32_e32 v2, 2, v2
	ds_bpermute_b32 v68, v2, v59
	global_load_dword v3, v[98:99], off
	global_load_dword v2, v[0:1], off offset:-4096
	s_nop 0
	global_load_dword v1, v[0:1], off
	v_mul_f32_e32 v0, 0x45800000, v51
	v_cndmask_b32_e64 v6, v51, v0, s[0:1]
	v_cmp_gt_u32_e64 s[0:1], 4, v39
	s_waitcnt lgkmcnt(0)
	v_add_f32_e32 v51, v59, v68
	v_pk_fma_f32 v[66:67], v[92:93], v[92:93], v[94:95]
	v_mov_b32_e32 v95, 0
	v_mov_b32_e32 v94, 0
	v_cndmask_b32_e64 v68, v51, v59, s[0:1]
	v_add_u32_e32 v51, -8, v63
	v_mov_b32_dpp v95, v67 quad_perm:[2,3,0,1] row_mask:0xf bank_mask:0xf
	v_mov_b32_dpp v94, v66 quad_perm:[2,3,0,1] row_mask:0xf bank_mask:0xf
	v_cmp_lt_i32_e64 s[0:1], v51, v25
	v_and_b32_e32 v59, 64, v63
	v_pk_add_f32 v[66:67], v[66:67], v[94:95]
	v_mov_b32_e32 v95, 0
	v_mov_b32_e32 v94, 0
	v_cndmask_b32_e64 v25, v51, v63, s[0:1]
	v_xor_b32_e32 v51, 16, v63
	v_add_u32_e32 v59, 64, v59
	v_mov_b32_dpp v95, v67 row_half_mirror row_mask:0xf bank_mask:0xf
	v_mov_b32_dpp v94, v66 row_half_mirror row_mask:0xf bank_mask:0xf
	v_cmp_lt_i32_e64 s[0:1], v51, v59
	v_pk_add_f32 v[66:67], v[66:67], v[94:95]
	v_mov_b32_e32 v95, 0
	v_mov_b32_e32 v94, 0
	v_cndmask_b32_e64 v51, v63, v51, s[0:1]
	v_mov_b32_dpp v95, v67 row_mirror row_mask:0xf bank_mask:0xf
	v_mov_b32_dpp v94, v66 row_mirror row_mask:0xf bank_mask:0xf
	v_lshlrev_b32_e32 v51, 2, v51
	v_pk_add_f32 v[66:67], v[66:67], v[94:95]
	ds_bpermute_b32 v95, v51, v67
	ds_bpermute_b32 v94, v51, v66
	v_xor_b32_e32 v96, 32, v63
	v_cmp_lt_i32_e64 s[0:1], v96, v59
	v_lshlrev_b32_e32 v25, 2, v25
	ds_bpermute_b32 v25, v25, v68
	v_cndmask_b32_e64 v59, v63, v96, s[0:1]
	v_lshlrev_b32_e32 v59, 2, v59
	s_waitcnt lgkmcnt(1)
	v_pk_add_f32 v[94:95], v[66:67], v[94:95]
	ds_bpermute_b32 v97, v59, v95
	ds_bpermute_b32 v96, v59, v94
	s_mov_b32 s4, 0x3c800000
	s_waitcnt lgkmcnt(2)
	v_add_f32_e32 v66, v68, v25
	v_mul_f32_e32 v0, 0x45800000, v29
	v_cndmask_b32_e64 v0, v29, v0, s[2:3]
	s_waitcnt lgkmcnt(0)
	v_pk_add_f32 v[94:95], v[94:95], v[96:97]
	s_add_u32 s2, s28, 0x8400000
	v_pk_fma_f32 v[94:95], v[94:95], s[4:5], v[4:5] op_sel_hi:[1,0,0]
	s_movk_i32 s5, 0x7fff
	v_mul_f32_e32 v25, 0x4b800000, v95
	v_cmp_gt_f32_e64 s[0:1], s53, v95
	s_addc_u32 s3, s29, 0
	s_ashr_i32 s9, s8, 31
	v_cndmask_b32_e64 v25, v95, v25, s[0:1]
	v_rsq_f32_e32 v25, v25
	v_lshl_add_u64 v[96:97], v[32:33], 0, s[8:9]
	s_waitcnt vmcnt(57)
	v_pk_mul_f32 v[64:65], v[64:65], v[62:63] op_sel_hi:[1,0]
	v_add_u32_e32 v67, s54, v17
	v_mul_f32_e32 v29, 0x45800000, v25
	v_cndmask_b32_e64 v25, v25, v29, s[0:1]
	v_mul_f32_e32 v29, 0x4b800000, v94
	v_cmp_gt_f32_e64 s[0:1], s53, v94
	v_mul_f32_e32 v25, v93, v25
	v_mul_f32_e32 v25, v11, v25
	v_cndmask_b32_e64 v29, v94, v29, s[0:1]
	v_rsq_f32_e32 v29, v29
	v_mul_f32_e32 v103, 0x3e000000, v25
	v_pk_mul_f32 v[94:95], v[64:65], v[64:65]
	v_mul_f32_e32 v25, 0x45800000, v29
	v_cndmask_b32_e64 v25, v29, v25, s[0:1]
	v_mul_f32_e32 v29, v100, v16
	v_mul_f32_e32 v29, 0xbfb8aa3b, v29
	v_exp_f32_e32 v29, v29
	v_mul_f32_e32 v25, v92, v25
	v_mul_f32_e32 v100, v7, v25
	v_mul_f32_e32 v25, v55, v16
	v_add_f32_e32 v16, 1.0, v29
	v_rcp_f32_e32 v55, v16
	v_bfe_u32 v16, v100, 16, 1
	v_add3_u32 v16, v100, v16, s5
	v_lshrrev_b32_e32 v29, 16, v16
	v_bfe_u32 v16, v25, 16, 1
	v_add3_u32 v16, v25, v16, s5
	v_lshrrev_b32_e32 v104, 16, v16
	v_lshlrev_b64 v[16:17], 1, v[96:97]
	v_mov_b32_e32 v97, 0
	v_mov_b32_e32 v96, 0
	s_mov_b64 s[0:1], 0x38000
	v_mov_b32_dpp v97, v95 quad_perm:[1,0,3,2] row_mask:0xf bank_mask:0xf
	v_mov_b32_dpp v96, v94 quad_perm:[1,0,3,2] row_mask:0xf bank_mask:0xf
	v_pk_fma_f32 v[94:95], v[64:65], v[64:65], v[96:97]
	v_mov_b32_e32 v97, 0
	v_mov_b32_e32 v96, 0
	v_lshl_add_u64 v[92:93], v[16:17], 0, s[0:1]
	v_mov_b32_dpp v97, v95 quad_perm:[2,3,0,1] row_mask:0xf bank_mask:0xf
	v_mov_b32_dpp v96, v94 quad_perm:[2,3,0,1] row_mask:0xf bank_mask:0xf
	v_pk_add_f32 v[94:95], v[94:95], v[96:97]
	v_mov_b32_e32 v97, 0
	v_mov_b32_e32 v96, 0
	v_lshl_add_u64 v[98:99], s[10:11], 0, v[92:93]
	v_mov_b32_dpp v97, v95 row_half_mirror row_mask:0xf bank_mask:0xf
	v_mov_b32_dpp v96, v94 row_half_mirror row_mask:0xf bank_mask:0xf
	v_pk_add_f32 v[94:95], v[94:95], v[96:97]
	v_mov_b32_e32 v97, 0
	v_mov_b32_e32 v96, 0
	v_lshl_add_u64 v[92:93], s[2:3], 0, v[92:93]
	v_mov_b32_dpp v97, v95 row_mirror row_mask:0xf bank_mask:0xf
	v_mov_b32_dpp v96, v94 row_mirror row_mask:0xf bank_mask:0xf
	v_pk_add_f32 v[94:95], v[94:95], v[96:97]
	ds_bpermute_b32 v97, v51, v95
	ds_bpermute_b32 v96, v51, v94
	global_store_short v[92:93], v104, off
	s_mov_b64 s[0:1], 0x1078000
	global_store_short v[98:99], v29, off
	s_waitcnt vmcnt(55)
	v_pk_mul_f32 v[60:61], v[60:61], v[58:59] op_sel_hi:[1,0]
	s_waitcnt lgkmcnt(0)
	v_pk_add_f32 v[92:93], v[94:95], v[96:97]
	ds_bpermute_b32 v95, v59, v93
	ds_bpermute_b32 v94, v59, v92
	v_lshl_add_u64 v[96:97], v[16:17], 0, s[0:1]
	v_lshl_add_u64 v[98:99], s[10:11], 0, v[96:97]
	global_store_short v[98:99], v29, off
	s_waitcnt vmcnt(52)
	v_pk_mul_f32 v[56:57], v[56:57], v[54:55] op_sel_hi:[1,0]
	s_waitcnt lgkmcnt(0)
	v_pk_add_f32 v[92:93], v[92:93], v[94:95]
	v_mul_f32_e32 v35, v35, v58
	v_pk_fma_f32 v[92:93], v[92:93], s[4:5], v[4:5] op_sel_hi:[1,0,0]
	s_waitcnt vmcnt(48)
	v_pk_mul_f32 v[52:53], v[52:53], v[50:51] op_sel_hi:[1,0]
	v_mul_f32_e32 v94, 0x4b800000, v93
	v_cmp_gt_f32_e64 s[0:1], s53, v93
	v_mul_f32_e32 v43, v43, v54
	s_waitcnt vmcnt(47)
	v_mul_f32_e32 v47, v47, v50
	v_cndmask_b32_e64 v93, v93, v94, s[0:1]
	v_rsq_f32_e32 v93, v93
	v_lshl_add_u64 v[94:95], s[2:3], 0, v[96:97]
	global_store_short v[94:95], v104, off
	v_mov_b32_e32 v95, 0
	v_mul_f32_e32 v29, 0x45800000, v93
	v_cndmask_b32_e64 v29, v93, v29, s[0:1]
	v_mul_f32_e32 v93, 0x4b800000, v92
	v_cmp_gt_f32_e64 s[0:1], s53, v92
	v_mul_f32_e32 v29, v65, v29
	v_mov_b32_e32 v94, 0
	v_cndmask_b32_e64 v92, v92, v93, s[0:1]
	v_rsq_f32_e32 v92, v92
	v_mul_f32_e32 v29, v11, v29
	v_mul_f32_e32 v29, 0x3e000000, v29
	s_waitcnt vmcnt(45)
	v_pk_mul_f32 v[48:49], v[48:49], v[46:47] op_sel_hi:[1,0]
	v_mul_f32_e32 v65, 0x45800000, v92
	v_cndmask_b32_e64 v65, v92, v65, s[0:1]
	v_pk_mul_f32 v[92:93], v[60:61], v[60:61]
	v_mul_f32_e32 v64, v64, v65
	v_mul_f32_e32 v65, v102, v62
	v_mov_b32_dpp v95, v93 quad_perm:[1,0,3,2] row_mask:0xf bank_mask:0xf
	v_mov_b32_dpp v94, v92 quad_perm:[1,0,3,2] row_mask:0xf bank_mask:0xf
	v_pk_fma_f32 v[92:93], v[60:61], v[60:61], v[94:95]
	v_mov_b32_e32 v95, 0
	v_mov_b32_e32 v94, 0
	v_mul_f32_e32 v65, 0xbfb8aa3b, v65
	v_mov_b32_dpp v95, v93 quad_perm:[2,3,0,1] row_mask:0xf bank_mask:0xf
	v_mov_b32_dpp v94, v92 quad_perm:[2,3,0,1] row_mask:0xf bank_mask:0xf
	v_exp_f32_e32 v65, v65
	v_pk_add_f32 v[92:93], v[92:93], v[94:95]
	v_mov_b32_e32 v95, 0
	v_mov_b32_e32 v94, 0
	v_mul_f32_e32 v64, v7, v64
	v_mov_b32_dpp v95, v93 row_half_mirror row_mask:0xf bank_mask:0xf
	v_mov_b32_dpp v94, v92 row_half_mirror row_mask:0xf bank_mask:0xf
	v_pk_add_f32 v[92:93], v[92:93], v[94:95]
	v_mov_b32_e32 v95, 0
	v_mov_b32_e32 v94, 0
	ds_write2st64_b32 v67, v103, v29 offset1:1
	ds_write2st64_b32 v67, v100, v64 offset0:16 offset1:17
	v_mov_b32_dpp v95, v93 row_mirror row_mask:0xf bank_mask:0xf
	v_mov_b32_dpp v94, v92 row_mirror row_mask:0xf bank_mask:0xf
	v_mul_f32_e32 v29, v101, v62
	v_add_f32_e32 v62, 1.0, v65
	v_bfe_u32 v65, v64, 16, 1
	v_pk_add_f32 v[92:93], v[92:93], v[94:95]
	v_add3_u32 v64, v64, v65, s5
	ds_bpermute_b32 v95, v51, v93
	ds_bpermute_b32 v94, v51, v92
	v_lshrrev_b32_e32 v98, 16, v64
	v_bfe_u32 v64, v29, 16, 1
	v_add3_u32 v64, v29, v64, s5
	s_mov_b64 s[0:1], 0x38800
	v_lshrrev_b32_e32 v99, 16, v64
	v_lshl_add_u64 v[64:65], v[16:17], 0, s[0:1]
	v_lshl_add_u64 v[96:97], s[10:11], 0, v[64:65]
	v_lshl_add_u64 v[64:65], s[2:3], 0, v[64:65]
	global_store_short v[64:65], v99, off
	s_waitcnt lgkmcnt(0)
	v_pk_add_f32 v[64:65], v[92:93], v[94:95]
	ds_bpermute_b32 v93, v59, v65
	ds_bpermute_b32 v92, v59, v64
	s_mov_b64 s[0:1], 0x1078800
	v_lshl_add_u64 v[94:95], v[16:17], 0, s[0:1]
	global_store_short v[96:97], v98, off
	v_lshl_add_u64 v[96:97], s[10:11], 0, v[94:95]
	s_waitcnt lgkmcnt(0)
	v_pk_add_f32 v[64:65], v[64:65], v[92:93]
	global_store_short v[96:97], v98, off
	v_pk_fma_f32 v[64:65], v[64:65], s[4:5], v[4:5] op_sel_hi:[1,0,0]
	s_waitcnt vmcnt(44)
	v_pk_mul_f32 v[44:45], v[44:45], v[42:43] op_sel_hi:[1,0]
	v_mul_f32_e32 v92, 0x4b800000, v65
	v_cmp_gt_f32_e64 s[0:1], s53, v65
	s_waitcnt vmcnt(40)
	v_pk_mul_f32 v[40:41], v[40:41], v[38:39] op_sel_hi:[1,0]
	s_waitcnt vmcnt(36)
	v_pk_mul_f32 v[36:37], v[36:37], v[34:35] op_sel_hi:[1,0]
	v_cndmask_b32_e64 v65, v65, v92, s[0:1]
	v_rsq_f32_e32 v65, v65
	v_lshl_add_u64 v[92:93], s[2:3], 0, v[94:95]
	global_store_short v[92:93], v99, off
	v_mov_b32_e32 v93, 0
	v_mul_f32_e32 v92, 0x45800000, v65
	v_cndmask_b32_e64 v65, v65, v92, s[0:1]
	v_mul_f32_e32 v92, 0x4b800000, v64
	v_cmp_gt_f32_e64 s[0:1], s53, v64
	v_mul_f32_e32 v61, v61, v65
	v_mul_f32_e32 v61, v11, v61
	v_cndmask_b32_e64 v64, v64, v92, s[0:1]
	v_rsq_f32_e32 v64, v64
	v_mul_f32_e32 v96, 0x3e000000, v61
	v_mov_b32_e32 v92, 0
	s_waitcnt vmcnt(33)
	v_pk_mul_f32 v[30:31], v[30:31], v[28:29] op_sel_hi:[1,0]
	v_mul_f32_e32 v61, 0x45800000, v64
	v_cndmask_b32_e64 v61, v64, v61, s[0:1]
	v_mul_f32_e32 v64, v91, v58
	v_mul_f32_e32 v64, 0xbfb8aa3b, v64
	v_exp_f32_e32 v64, v64
	v_mul_f32_e32 v60, v60, v61
	v_mul_f32_e32 v91, v7, v60
	v_bfe_u32 v60, v91, 16, 1
	v_add_f32_e32 v58, 1.0, v64
	v_pk_mul_f32 v[64:65], v[56:57], v[56:57]
	v_add3_u32 v60, v91, v60, s5
	v_lshrrev_b32_e32 v97, 16, v60
	v_mov_b32_dpp v93, v65 quad_perm:[1,0,3,2] row_mask:0xf bank_mask:0xf
	v_mov_b32_dpp v92, v64 quad_perm:[1,0,3,2] row_mask:0xf bank_mask:0xf
	v_pk_fma_f32 v[64:65], v[56:57], v[56:57], v[92:93]
	v_mov_b32_e32 v93, 0
	v_mov_b32_e32 v92, 0
	v_bfe_u32 v60, v35, 16, 1
	v_mov_b32_dpp v93, v65 quad_perm:[2,3,0,1] row_mask:0xf bank_mask:0xf
	v_mov_b32_dpp v92, v64 quad_perm:[2,3,0,1] row_mask:0xf bank_mask:0xf
	v_pk_add_f32 v[64:65], v[64:65], v[92:93]
	v_mov_b32_e32 v93, 0
	v_mov_b32_e32 v92, 0
	v_add3_u32 v60, v35, v60, s5
	v_mov_b32_dpp v93, v65 row_half_mirror row_mask:0xf bank_mask:0xf
	v_mov_b32_dpp v92, v64 row_half_mirror row_mask:0xf bank_mask:0xf
	v_pk_add_f32 v[64:65], v[64:65], v[92:93]
	v_mov_b32_e32 v93, 0
	v_mov_b32_e32 v92, 0
	s_mov_b64 s[0:1], 0x39000
	v_mov_b32_dpp v93, v65 row_mirror row_mask:0xf bank_mask:0xf
	v_mov_b32_dpp v92, v64 row_mirror row_mask:0xf bank_mask:0xf
	v_pk_add_f32 v[64:65], v[64:65], v[92:93]
	ds_bpermute_b32 v93, v51, v65
	ds_bpermute_b32 v92, v51, v64
	v_lshrrev_b32_e32 v98, 16, v60
	v_lshl_add_u64 v[60:61], v[16:17], 0, s[0:1]
	v_lshl_add_u64 v[94:95], s[10:11], 0, v[60:61]
	v_lshl_add_u64 v[60:61], s[2:3], 0, v[60:61]
	global_store_short v[60:61], v98, off
	s_waitcnt lgkmcnt(0)
	v_pk_add_f32 v[60:61], v[64:65], v[92:93]
	ds_bpermute_b32 v65, v59, v61
	ds_bpermute_b32 v64, v59, v60
	s_mov_b64 s[0:1], 0x1079000
	v_lshl_add_u64 v[92:93], v[16:17], 0, s[0:1]
	global_store_short v[94:95], v97, off
	v_lshl_add_u64 v[94:95], s[10:11], 0, v[92:93]
	s_waitcnt lgkmcnt(0)
	v_pk_add_f32 v[60:61], v[60:61], v[64:65]
	global_store_short v[94:95], v97, off
	v_pk_fma_f32 v[60:61], v[60:61], s[4:5], v[4:5] op_sel_hi:[1,0,0]
	s_waitcnt vmcnt(32)
	v_pk_mul_f32 v[26:27], v[26:27], v[24:25] op_sel_hi:[1,0]
	v_mul_f32_e32 v64, 0x4b800000, v61
	v_cmp_gt_f32_e64 s[0:1], s53, v61
	s_waitcnt vmcnt(28)
	v_pk_mul_f32 v[22:23], v[22:23], v[20:21] op_sel_hi:[1,0]
	s_waitcnt vmcnt(24)
	v_pk_mul_f32 v[18:19], v[18:19], v[14:15] op_sel_hi:[1,0]
	v_cndmask_b32_e64 v61, v61, v64, s[0:1]
	v_rsq_f32_e32 v61, v61
	v_lshl_add_u64 v[64:65], s[2:3], 0, v[92:93]
	global_store_short v[64:65], v98, off
	v_mov_b32_e32 v65, 0
	v_mul_f32_e32 v64, 0x45800000, v61
	v_cndmask_b32_e64 v61, v61, v64, s[0:1]
	v_mul_f32_e32 v64, 0x4b800000, v60
	v_cmp_gt_f32_e64 s[0:1], s53, v60
	v_mul_f32_e32 v57, v57, v61
	v_mul_f32_e32 v57, v11, v57
	v_cndmask_b32_e64 v60, v60, v64, s[0:1]
	v_rsq_f32_e32 v60, v60
	v_mov_b32_e32 v64, 0
	v_mul_f32_e32 v57, 0x3e000000, v57
	s_waitcnt vmcnt(21)
	v_pk_mul_f32 v[12:13], v[12:13], v[10:11] op_sel_hi:[1,0]
	v_mul_f32_e32 v61, 0x45800000, v60
	v_cndmask_b32_e64 v60, v60, v61, s[0:1]
	v_mul_f32_e32 v56, v56, v60
	v_mul_f32_e32 v60, v90, v54
	v_mul_f32_e32 v60, 0xbfb8aa3b, v60
	v_exp_f32_e32 v60, v60
	v_mul_f32_e32 v56, v7, v56
	ds_write2st64_b32 v67, v96, v57 offset0:2 offset1:3
	ds_write2st64_b32 v67, v91, v56 offset0:18 offset1:19
	v_bfe_u32 v57, v56, 16, 1
	v_add_f32_e32 v54, 1.0, v60
	v_pk_mul_f32 v[60:61], v[52:53], v[52:53]
	v_add3_u32 v56, v56, v57, s5
	v_lshrrev_b32_e32 v92, 16, v56
	v_mov_b32_dpp v65, v61 quad_perm:[1,0,3,2] row_mask:0xf bank_mask:0xf
	v_mov_b32_dpp v64, v60 quad_perm:[1,0,3,2] row_mask:0xf bank_mask:0xf
	v_pk_fma_f32 v[60:61], v[52:53], v[52:53], v[64:65]
	v_mov_b32_e32 v65, 0
	v_mov_b32_e32 v64, 0
	v_bfe_u32 v56, v43, 16, 1
	v_mov_b32_dpp v65, v61 quad_perm:[2,3,0,1] row_mask:0xf bank_mask:0xf
	v_mov_b32_dpp v64, v60 quad_perm:[2,3,0,1] row_mask:0xf bank_mask:0xf
	v_pk_add_f32 v[60:61], v[60:61], v[64:65]
	v_mov_b32_e32 v65, 0
	v_mov_b32_e32 v64, 0
	v_add3_u32 v56, v43, v56, s5
	v_mov_b32_dpp v65, v61 row_half_mirror row_mask:0xf bank_mask:0xf
	v_mov_b32_dpp v64, v60 row_half_mirror row_mask:0xf bank_mask:0xf
	v_pk_add_f32 v[60:61], v[60:61], v[64:65]
	v_mov_b32_e32 v65, 0
	v_mov_b32_e32 v64, 0
	s_mov_b64 s[0:1], 0x39800
	v_mov_b32_dpp v65, v61 row_mirror row_mask:0xf bank_mask:0xf
	v_mov_b32_dpp v64, v60 row_mirror row_mask:0xf bank_mask:0xf
	v_pk_add_f32 v[60:61], v[60:61], v[64:65]
	ds_bpermute_b32 v65, v51, v61
	ds_bpermute_b32 v64, v51, v60
	v_lshrrev_b32_e32 v93, 16, v56
	v_lshl_add_u64 v[56:57], v[16:17], 0, s[0:1]
	v_lshl_add_u64 v[90:91], s[10:11], 0, v[56:57]
	v_lshl_add_u64 v[56:57], s[2:3], 0, v[56:57]
	global_store_short v[56:57], v93, off
	s_waitcnt lgkmcnt(0)
	v_pk_add_f32 v[56:57], v[60:61], v[64:65]
	ds_bpermute_b32 v61, v59, v57
	ds_bpermute_b32 v60, v59, v56
	s_mov_b64 s[0:1], 0x1079800
	v_lshl_add_u64 v[64:65], v[16:17], 0, s[0:1]
	global_store_short v[90:91], v92, off
	v_lshl_add_u64 v[90:91], s[10:11], 0, v[64:65]
	s_waitcnt lgkmcnt(0)
	v_pk_add_f32 v[56:57], v[56:57], v[60:61]
	global_store_short v[90:91], v92, off
	v_pk_fma_f32 v[56:57], v[56:57], s[4:5], v[4:5] op_sel_hi:[1,0,0]
	s_waitcnt vmcnt(20)
	v_pk_mul_f32 v[8:9], v[8:9], v[6:7] op_sel_hi:[1,0]
	v_mul_f32_e32 v60, 0x4b800000, v57
	v_cmp_gt_f32_e64 s[0:1], s53, v57
	s_waitcnt vmcnt(15)
	v_pk_mul_f32 v[2:3], v[2:3], v[0:1] op_sel_hi:[1,0]
	v_rcp_f32_e32 v62, v62
	v_cndmask_b32_e64 v57, v57, v60, s[0:1]
	v_rsq_f32_e32 v57, v57
	v_lshl_add_u64 v[60:61], s[2:3], 0, v[64:65]
	global_store_short v[60:61], v93, off
	v_mov_b32_e32 v61, 0
	v_mul_f32_e32 v60, 0x45800000, v57
	v_cndmask_b32_e64 v57, v57, v60, s[0:1]
	v_mul_f32_e32 v60, 0x4b800000, v56
	v_cmp_gt_f32_e64 s[0:1], s53, v56
	v_mul_f32_e32 v53, v53, v57
	v_mul_f32_e32 v53, v11, v53
	v_cndmask_b32_e64 v56, v56, v60, s[0:1]
	v_rsq_f32_e32 v56, v56
	v_mul_f32_e32 v90, 0x3e000000, v53
	v_mov_b32_e32 v60, 0
	v_rcp_f32_e32 v58, v58
	v_mul_f32_e32 v53, 0x45800000, v56
	v_cndmask_b32_e64 v53, v56, v53, s[0:1]
	v_mul_f32_e32 v56, v89, v50
	v_mul_f32_e32 v56, 0xbfb8aa3b, v56
	v_exp_f32_e32 v56, v56
	v_mul_f32_e32 v52, v52, v53
	v_mul_f32_e32 v89, v7, v52
	v_bfe_u32 v52, v89, 16, 1
	v_add_f32_e32 v50, 1.0, v56
	v_pk_mul_f32 v[56:57], v[48:49], v[48:49]
	v_add3_u32 v52, v89, v52, s5
	v_lshrrev_b32_e32 v91, 16, v52
	v_mov_b32_dpp v61, v57 quad_perm:[1,0,3,2] row_mask:0xf bank_mask:0xf
	v_mov_b32_dpp v60, v56 quad_perm:[1,0,3,2] row_mask:0xf bank_mask:0xf
	v_pk_fma_f32 v[56:57], v[48:49], v[48:49], v[60:61]
	v_mov_b32_e32 v61, 0
	v_mov_b32_e32 v60, 0
	v_bfe_u32 v52, v47, 16, 1
	v_mov_b32_dpp v61, v57 quad_perm:[2,3,0,1] row_mask:0xf bank_mask:0xf
	v_mov_b32_dpp v60, v56 quad_perm:[2,3,0,1] row_mask:0xf bank_mask:0xf
	v_pk_add_f32 v[56:57], v[56:57], v[60:61]
	v_mov_b32_e32 v61, 0
	v_mov_b32_e32 v60, 0
	v_add3_u32 v52, v47, v52, s5
	v_mov_b32_dpp v61, v57 row_half_mirror row_mask:0xf bank_mask:0xf
	v_mov_b32_dpp v60, v56 row_half_mirror row_mask:0xf bank_mask:0xf
	v_pk_add_f32 v[56:57], v[56:57], v[60:61]
	v_mov_b32_e32 v61, 0
	v_mov_b32_e32 v60, 0
	s_mov_b64 s[0:1], 0x3a000
	v_mov_b32_dpp v61, v57 row_mirror row_mask:0xf bank_mask:0xf
	v_mov_b32_dpp v60, v56 row_mirror row_mask:0xf bank_mask:0xf
	v_pk_add_f32 v[56:57], v[56:57], v[60:61]
	ds_bpermute_b32 v61, v51, v57
	ds_bpermute_b32 v60, v51, v56
	v_lshrrev_b32_e32 v92, 16, v52
	v_lshl_add_u64 v[52:53], v[16:17], 0, s[0:1]
	v_lshl_add_u64 v[64:65], s[10:11], 0, v[52:53]
	v_lshl_add_u64 v[52:53], s[2:3], 0, v[52:53]
	global_store_short v[52:53], v92, off
	s_waitcnt lgkmcnt(0)
	v_pk_add_f32 v[52:53], v[56:57], v[60:61]
	ds_bpermute_b32 v57, v59, v53
	ds_bpermute_b32 v56, v59, v52
	s_mov_b64 s[0:1], 0x107a000
	v_lshl_add_u64 v[60:61], v[16:17], 0, s[0:1]
	global_store_short v[64:65], v91, off
	v_lshl_add_u64 v[64:65], s[10:11], 0, v[60:61]
	s_waitcnt lgkmcnt(0)
	v_pk_add_f32 v[52:53], v[52:53], v[56:57]
	global_store_short v[64:65], v91, off
	v_pk_fma_f32 v[52:53], v[52:53], s[4:5], v[4:5] op_sel_hi:[1,0,0]
	v_rcp_f32_e32 v54, v54
	v_mul_f32_e32 v56, 0x4b800000, v53
	v_cmp_gt_f32_e64 s[0:1], s53, v53
	v_rcp_f32_e32 v50, v50
	s_nop 0
	v_cndmask_b32_e64 v53, v53, v56, s[0:1]
	v_rsq_f32_e32 v53, v53
	v_lshl_add_u64 v[56:57], s[2:3], 0, v[60:61]
	global_store_short v[56:57], v92, off
	v_mov_b32_e32 v61, 0
	v_mul_f32_e32 v56, 0x45800000, v53
	v_cndmask_b32_e64 v53, v53, v56, s[0:1]
	v_mul_f32_e32 v56, 0x4b800000, v52
	v_cmp_gt_f32_e64 s[0:1], s53, v52
	v_mov_b32_e32 v60, 0
	v_mul_f32_e32 v49, v49, v53
	v_cndmask_b32_e64 v52, v52, v56, s[0:1]
	v_pk_mul_f32 v[56:57], v[44:45], v[44:45]
	v_rsq_f32_e32 v52, v52
	v_mul_f32_e32 v49, v11, v49
	v_mov_b32_dpp v61, v57 quad_perm:[1,0,3,2] row_mask:0xf bank_mask:0xf
	v_mov_b32_dpp v60, v56 quad_perm:[1,0,3,2] row_mask:0xf bank_mask:0xf
	v_pk_fma_f32 v[56:57], v[44:45], v[44:45], v[60:61]
	v_mov_b32_e32 v61, 0
	v_mov_b32_e32 v60, 0
	v_mul_f32_e32 v53, 0x45800000, v52
	v_mov_b32_dpp v61, v57 quad_perm:[2,3,0,1] row_mask:0xf bank_mask:0xf
	v_mov_b32_dpp v60, v56 quad_perm:[2,3,0,1] row_mask:0xf bank_mask:0xf
	v_pk_add_f32 v[56:57], v[56:57], v[60:61]
	v_mov_b32_e32 v61, 0
	v_mov_b32_e32 v60, 0
	v_cndmask_b32_e64 v52, v52, v53, s[0:1]
	v_mov_b32_dpp v61, v57 row_half_mirror row_mask:0xf bank_mask:0xf
	v_mov_b32_dpp v60, v56 row_half_mirror row_mask:0xf bank_mask:0xf
	v_pk_add_f32 v[56:57], v[56:57], v[60:61]
	v_mov_b32_e32 v61, 0
	v_mov_b32_e32 v60, 0
	v_mul_f32_e32 v48, v48, v52
	v_mov_b32_dpp v61, v57 row_mirror row_mask:0xf bank_mask:0xf
	v_mov_b32_dpp v60, v56 row_mirror row_mask:0xf bank_mask:0xf
	v_mul_f32_e32 v49, 0x3e000000, v49
	v_mul_f32_e32 v52, v7, v48
	v_pk_add_f32 v[56:57], v[56:57], v[60:61]
	v_mul_f32_e32 v48, v88, v46
	ds_write2st64_b32 v67, v90, v49 offset0:4 offset1:5
	ds_write2st64_b32 v67, v89, v52 offset0:20 offset1:21
	v_mul_f32_e32 v46, v87, v46
	v_bfe_u32 v49, v52, 16, 1
	ds_bpermute_b32 v61, v51, v57
	ds_bpermute_b32 v60, v51, v56
	v_add3_u32 v49, v52, v49, s5
	v_bfe_u32 v52, v46, 16, 1
	v_add3_u32 v52, v46, v52, s5
	s_mov_b64 s[0:1], 0x3a800
	v_lshrrev_b32_e32 v87, 16, v52
	v_lshl_add_u64 v[52:53], v[16:17], 0, s[0:1]
	v_lshl_add_u64 v[64:65], s[10:11], 0, v[52:53]
	v_lshl_add_u64 v[52:53], s[2:3], 0, v[52:53]
	global_store_short v[52:53], v87, off
	s_waitcnt lgkmcnt(0)
	v_pk_add_f32 v[52:53], v[56:57], v[60:61]
	ds_bpermute_b32 v57, v59, v53
	ds_bpermute_b32 v56, v59, v52
	s_mov_b64 s[0:1], 0x107a800
	v_lshl_add_u64 v[60:61], v[16:17], 0, s[0:1]
	v_lshrrev_b32_e32 v49, 16, v49
	global_store_short v[64:65], v49, off
	s_waitcnt lgkmcnt(0)
	v_pk_add_f32 v[52:53], v[52:53], v[56:57]
	v_lshl_add_u64 v[64:65], s[10:11], 0, v[60:61]
	v_pk_fma_f32 v[52:53], v[52:53], s[4:5], v[4:5] op_sel_hi:[1,0,0]
	global_store_short v[64:65], v49, off
	v_mul_f32_e32 v56, 0x4b800000, v53
	v_cmp_gt_f32_e64 s[0:1], s53, v53
	v_mul_f32_e32 v48, 0xbfb8aa3b, v48
	v_exp_f32_e32 v48, v48
	v_cndmask_b32_e64 v53, v53, v56, s[0:1]
	v_rsq_f32_e32 v53, v53
	v_lshl_add_u64 v[56:57], s[2:3], 0, v[60:61]
	global_store_short v[56:57], v87, off
	v_pk_mul_f32 v[56:57], v[40:41], v[40:41]
	v_mul_f32_e32 v49, 0x45800000, v53
	v_cndmask_b32_e64 v49, v53, v49, s[0:1]
	v_mul_f32_e32 v53, 0x4b800000, v52
	v_cmp_gt_f32_e64 s[0:1], s53, v52
	v_mov_b32_e32 v61, 0
	v_mov_b32_e32 v60, 0
	v_cndmask_b32_e64 v52, v52, v53, s[0:1]
	v_rsq_f32_e32 v52, v52
	v_mul_f32_e32 v45, v45, v49
	v_mov_b32_dpp v61, v57 quad_perm:[1,0,3,2] row_mask:0xf bank_mask:0xf
	v_mov_b32_dpp v60, v56 quad_perm:[1,0,3,2] row_mask:0xf bank_mask:0xf
	v_mul_f32_e32 v49, 0x45800000, v52
	v_cndmask_b32_e64 v49, v52, v49, s[0:1]
	v_mul_f32_e32 v52, v86, v42
	v_pk_fma_f32 v[56:57], v[40:41], v[40:41], v[60:61]
	v_mov_b32_e32 v61, 0
	v_mov_b32_e32 v60, 0
	v_mul_f32_e32 v52, 0xbfb8aa3b, v52
	v_mov_b32_dpp v61, v57 quad_perm:[2,3,0,1] row_mask:0xf bank_mask:0xf
	v_mov_b32_dpp v60, v56 quad_perm:[2,3,0,1] row_mask:0xf bank_mask:0xf
	v_exp_f32_e32 v52, v52
	v_pk_add_f32 v[56:57], v[56:57], v[60:61]
	v_mov_b32_e32 v61, 0
	v_mov_b32_e32 v60, 0
	v_mul_f32_e32 v44, v44, v49
	v_mov_b32_dpp v61, v57 row_half_mirror row_mask:0xf bank_mask:0xf
	v_mov_b32_dpp v60, v56 row_half_mirror row_mask:0xf bank_mask:0xf
	v_pk_add_f32 v[56:57], v[56:57], v[60:61]
	v_mov_b32_e32 v61, 0
	v_mov_b32_e32 v60, 0
	v_mul_f32_e32 v49, v7, v44
	v_mov_b32_dpp v61, v57 row_mirror row_mask:0xf bank_mask:0xf
	v_mov_b32_dpp v60, v56 row_mirror row_mask:0xf bank_mask:0xf
	v_add_f32_e32 v44, 1.0, v52
	v_bfe_u32 v52, v49, 16, 1
	v_pk_add_f32 v[56:57], v[56:57], v[60:61]
	v_mul_f32_e32 v42, v85, v42
	v_add3_u32 v52, v49, v52, s5
	ds_bpermute_b32 v61, v51, v57
	ds_bpermute_b32 v60, v51, v56
	v_lshrrev_b32_e32 v85, 16, v52
	v_bfe_u32 v52, v42, 16, 1
	v_add3_u32 v52, v42, v52, s5
	s_mov_b64 s[0:1], 0x3b000
	v_lshrrev_b32_e32 v86, 16, v52
	v_lshl_add_u64 v[52:53], v[16:17], 0, s[0:1]
	v_lshl_add_u64 v[64:65], s[10:11], 0, v[52:53]
	v_lshl_add_u64 v[52:53], s[2:3], 0, v[52:53]
	global_store_short v[52:53], v86, off
	s_waitcnt lgkmcnt(0)
	v_pk_add_f32 v[52:53], v[56:57], v[60:61]
	ds_bpermute_b32 v57, v59, v53
	ds_bpermute_b32 v56, v59, v52
	s_mov_b64 s[0:1], 0x107b000
	v_lshl_add_u64 v[60:61], v[16:17], 0, s[0:1]
	global_store_short v[64:65], v85, off
	v_lshl_add_u64 v[64:65], s[10:11], 0, v[60:61]
	s_waitcnt lgkmcnt(0)
	v_pk_add_f32 v[52:53], v[52:53], v[56:57]
	v_mul_f32_e32 v45, v11, v45
	v_pk_fma_f32 v[52:53], v[52:53], s[4:5], v[4:5] op_sel_hi:[1,0,0]
	v_mul_f32_e32 v45, 0x3e000000, v45
	v_mul_f32_e32 v56, 0x4b800000, v53
	v_cmp_gt_f32_e64 s[0:1], s53, v53
	global_store_short v[64:65], v85, off
	v_add_f32_e32 v48, 1.0, v48
	v_cndmask_b32_e64 v53, v53, v56, s[0:1]
	v_rsq_f32_e32 v53, v53
	v_lshl_add_u64 v[56:57], s[2:3], 0, v[60:61]
	global_store_short v[56:57], v86, off
	v_mov_b32_e32 v61, 0
	v_mul_f32_e32 v56, 0x45800000, v53
	v_cndmask_b32_e64 v53, v53, v56, s[0:1]
	v_mul_f32_e32 v56, 0x4b800000, v52
	v_cmp_gt_f32_e64 s[0:1], s53, v52
	v_mov_b32_e32 v60, 0
	v_mul_f32_e32 v41, v41, v53
	v_cndmask_b32_e64 v52, v52, v56, s[0:1]
	v_pk_mul_f32 v[56:57], v[36:37], v[36:37]
	v_rsq_f32_e32 v52, v52
	v_mul_f32_e32 v41, v11, v41
	v_mov_b32_dpp v61, v57 quad_perm:[1,0,3,2] row_mask:0xf bank_mask:0xf
	v_mov_b32_dpp v60, v56 quad_perm:[1,0,3,2] row_mask:0xf bank_mask:0xf
	v_pk_fma_f32 v[56:57], v[36:37], v[36:37], v[60:61]
	v_mov_b32_e32 v61, 0
	v_mov_b32_e32 v60, 0
	v_mul_f32_e32 v53, 0x45800000, v52
	v_mov_b32_dpp v61, v57 quad_perm:[2,3,0,1] row_mask:0xf bank_mask:0xf
	v_mov_b32_dpp v60, v56 quad_perm:[2,3,0,1] row_mask:0xf bank_mask:0xf
	v_pk_add_f32 v[56:57], v[56:57], v[60:61]
	v_mov_b32_e32 v61, 0
	v_mov_b32_e32 v60, 0
	v_cndmask_b32_e64 v52, v52, v53, s[0:1]
	v_mov_b32_dpp v61, v57 row_half_mirror row_mask:0xf bank_mask:0xf
	v_mov_b32_dpp v60, v56 row_half_mirror row_mask:0xf bank_mask:0xf
	v_pk_add_f32 v[56:57], v[56:57], v[60:61]
	v_mov_b32_e32 v61, 0
	v_mov_b32_e32 v60, 0
	v_mul_f32_e32 v40, v40, v52
	v_mov_b32_dpp v61, v57 row_mirror row_mask:0xf bank_mask:0xf
	v_mov_b32_dpp v60, v56 row_mirror row_mask:0xf bank_mask:0xf
	v_pk_add_f32 v[56:57], v[56:57], v[60:61]
	ds_bpermute_b32 v61, v51, v57
	ds_bpermute_b32 v60, v51, v56
	v_mul_f32_e32 v41, 0x3e000000, v41
	v_mul_f32_e32 v52, v7, v40
	v_mul_f32_e32 v40, v84, v38
	v_mul_f32_e32 v38, v83, v38
	ds_write2st64_b32 v67, v45, v41 offset0:6 offset1:7
	ds_write2st64_b32 v67, v49, v52 offset0:22 offset1:23
	v_bfe_u32 v41, v52, 16, 1
	v_bfe_u32 v45, v38, 16, 1
	s_mov_b64 s[0:1], 0x3b800
	v_add3_u32 v41, v52, v41, s5
	v_add3_u32 v45, v38, v45, s5
	v_lshl_add_u64 v[52:53], v[16:17], 0, s[0:1]
	v_lshrrev_b32_e32 v45, 16, v45
	v_lshl_add_u64 v[64:65], s[10:11], 0, v[52:53]
	v_lshl_add_u64 v[52:53], s[2:3], 0, v[52:53]
	global_store_short v[52:53], v45, off
	s_waitcnt lgkmcnt(2)
	v_pk_add_f32 v[52:53], v[56:57], v[60:61]
	ds_bpermute_b32 v57, v59, v53
	ds_bpermute_b32 v56, v59, v52
	s_mov_b64 s[0:1], 0x107b800
	v_lshl_add_u64 v[60:61], v[16:17], 0, s[0:1]
	v_lshrrev_b32_e32 v41, 16, v41
	global_store_short v[64:65], v41, off
	s_waitcnt lgkmcnt(0)
	v_pk_add_f32 v[52:53], v[52:53], v[56:57]
	v_lshl_add_u64 v[56:57], s[2:3], 0, v[60:61]
	v_pk_fma_f32 v[52:53], v[52:53], s[4:5], v[4:5] op_sel_hi:[1,0,0]
	v_lshl_add_u64 v[64:65], s[10:11], 0, v[60:61]
	v_mul_f32_e32 v49, 0x4b800000, v53
	v_cmp_gt_f32_e64 s[0:1], s53, v53
	global_store_short v[56:57], v45, off
	v_pk_mul_f32 v[56:57], v[30:31], v[30:31]
	v_cndmask_b32_e64 v49, v53, v49, s[0:1]
	v_rsq_f32_e32 v49, v49
	v_mov_b32_e32 v61, 0
	v_mov_b32_e32 v60, 0
	global_store_short v[64:65], v41, off
	v_mov_b32_dpp v61, v57 quad_perm:[1,0,3,2] row_mask:0xf bank_mask:0xf
	v_mov_b32_dpp v60, v56 quad_perm:[1,0,3,2] row_mask:0xf bank_mask:0xf
	v_mul_f32_e32 v41, 0x45800000, v49
	v_pk_fma_f32 v[56:57], v[30:31], v[30:31], v[60:61]
	v_mov_b32_e32 v61, 0
	v_mov_b32_e32 v60, 0
	v_cndmask_b32_e64 v41, v49, v41, s[0:1]
	v_mul_f32_e32 v45, 0x4b800000, v52
	v_cmp_gt_f32_e64 s[0:1], s53, v52
	v_mov_b32_dpp v61, v57 quad_perm:[2,3,0,1] row_mask:0xf bank_mask:0xf
	v_mov_b32_dpp v60, v56 quad_perm:[2,3,0,1] row_mask:0xf bank_mask:0xf
	v_cndmask_b32_e64 v45, v52, v45, s[0:1]
	v_pk_add_f32 v[56:57], v[56:57], v[60:61]
	v_mov_b32_e32 v61, 0
	v_mov_b32_e32 v60, 0
	v_rsq_f32_e32 v45, v45
	v_mov_b32_dpp v61, v57 row_half_mirror row_mask:0xf bank_mask:0xf
	v_mov_b32_dpp v60, v56 row_half_mirror row_mask:0xf bank_mask:0xf
	v_pk_add_f32 v[56:57], v[56:57], v[60:61]
	v_mov_b32_e32 v61, 0
	v_mov_b32_e32 v60, 0
	v_mul_f32_e32 v37, v37, v41
	v_mov_b32_dpp v61, v57 row_mirror row_mask:0xf bank_mask:0xf
	v_mov_b32_dpp v60, v56 row_mirror row_mask:0xf bank_mask:0xf
	v_pk_add_f32 v[56:57], v[56:57], v[60:61]
	v_mul_f32_e32 v41, 0x45800000, v45
	ds_bpermute_b32 v61, v51, v57
	ds_bpermute_b32 v60, v51, v56
	v_cndmask_b32_e64 v41, v45, v41, s[0:1]
	v_mul_f32_e32 v45, v82, v34
	v_mul_f32_e32 v34, v81, v34
	v_bfe_u32 v49, v34, 16, 1
	s_mov_b64 s[0:1], 0x3c000
	v_add3_u32 v49, v34, v49, s5
	v_lshl_add_u64 v[52:53], v[16:17], 0, s[0:1]
	v_lshrrev_b32_e32 v49, 16, v49
	v_lshl_add_u64 v[64:65], s[10:11], 0, v[52:53]
	v_lshl_add_u64 v[52:53], s[2:3], 0, v[52:53]
	global_store_short v[52:53], v49, off
	s_waitcnt lgkmcnt(0)
	v_pk_add_f32 v[52:53], v[56:57], v[60:61]
	ds_bpermute_b32 v57, v59, v53
	ds_bpermute_b32 v56, v59, v52
	v_mul_f32_e32 v45, 0xbfb8aa3b, v45
	v_exp_f32_e32 v45, v45
	s_mov_b64 s[0:1], 0x107c000
	v_mul_f32_e32 v36, v36, v41
	s_waitcnt lgkmcnt(0)
	v_pk_add_f32 v[52:53], v[52:53], v[56:57]
	v_lshl_add_u64 v[60:61], v[16:17], 0, s[0:1]
	v_pk_fma_f32 v[52:53], v[52:53], s[4:5], v[4:5] op_sel_hi:[1,0,0]
	v_mul_f32_e32 v41, v7, v36
	v_mul_f32_e32 v56, 0x4b800000, v53
	v_cmp_gt_f32_e64 s[0:1], s53, v53
	v_add_f32_e32 v36, 1.0, v45
	v_bfe_u32 v45, v41, 16, 1
	v_cndmask_b32_e64 v53, v53, v56, s[0:1]
	v_rsq_f32_e32 v53, v53
	v_add3_u32 v45, v41, v45, s5
	v_lshrrev_b32_e32 v45, 16, v45
	global_store_short v[64:65], v45, off
	v_lshl_add_u64 v[64:65], s[10:11], 0, v[60:61]
	v_lshl_add_u64 v[56:57], s[2:3], 0, v[60:61]
	global_store_short v[64:65], v45, off
	global_store_short v[56:57], v49, off
	v_mul_f32_e32 v45, 0x45800000, v53
	v_pk_mul_f32 v[56:57], v[26:27], v[26:27]
	v_mov_b32_e32 v61, 0
	v_mov_b32_e32 v60, 0
	v_cndmask_b32_e64 v45, v53, v45, s[0:1]
	v_mul_f32_e32 v49, 0x4b800000, v52
	v_cmp_gt_f32_e64 s[0:1], s53, v52
	v_mov_b32_dpp v61, v57 quad_perm:[1,0,3,2] row_mask:0xf bank_mask:0xf
	v_mov_b32_dpp v60, v56 quad_perm:[1,0,3,2] row_mask:0xf bank_mask:0xf
	v_cndmask_b32_e64 v49, v52, v49, s[0:1]
	v_pk_fma_f32 v[56:57], v[26:27], v[26:27], v[60:61]
	v_mov_b32_e32 v61, 0
	v_mov_b32_e32 v60, 0
	v_rsq_f32_e32 v49, v49
	v_mov_b32_dpp v61, v57 quad_perm:[2,3,0,1] row_mask:0xf bank_mask:0xf
	v_mov_b32_dpp v60, v56 quad_perm:[2,3,0,1] row_mask:0xf bank_mask:0xf
	v_pk_add_f32 v[56:57], v[56:57], v[60:61]
	v_mov_b32_e32 v61, 0
	v_mov_b32_e32 v60, 0
	v_mul_f32_e32 v31, v31, v45
	v_mov_b32_dpp v61, v57 row_half_mirror row_mask:0xf bank_mask:0xf
	v_mov_b32_dpp v60, v56 row_half_mirror row_mask:0xf bank_mask:0xf
	v_pk_add_f32 v[56:57], v[56:57], v[60:61]
	v_mov_b32_e32 v61, 0
	v_mov_b32_e32 v60, 0
	v_mul_f32_e32 v45, 0x45800000, v49
	v_mov_b32_dpp v61, v57 row_mirror row_mask:0xf bank_mask:0xf
	v_mov_b32_dpp v60, v56 row_mirror row_mask:0xf bank_mask:0xf
	v_cndmask_b32_e64 v45, v49, v45, s[0:1]
	v_pk_add_f32 v[56:57], v[56:57], v[60:61]
	v_mul_f32_e32 v37, v11, v37
	v_mul_f32_e32 v31, v11, v31
	v_mul_f32_e32 v30, v30, v45
	ds_bpermute_b32 v61, v51, v57
	ds_bpermute_b32 v60, v51, v56
	v_mul_f32_e32 v37, 0x3e000000, v37
	v_mul_f32_e32 v31, 0x3e000000, v31
	v_mul_f32_e32 v45, v7, v30
	v_mul_f32_e32 v30, v80, v28
	v_mul_f32_e32 v28, v79, v28
	ds_write2st64_b32 v67, v37, v31 offset0:8 offset1:9
	ds_write2st64_b32 v67, v41, v45 offset0:24 offset1:25
	v_bfe_u32 v37, v28, 16, 1
	s_mov_b64 s[0:1], 0x3c800
	v_add3_u32 v37, v28, v37, s5
	v_lshl_add_u64 v[52:53], v[16:17], 0, s[0:1]
	v_lshrrev_b32_e32 v37, 16, v37
	v_lshl_add_u64 v[64:65], s[10:11], 0, v[52:53]
	v_lshl_add_u64 v[52:53], s[2:3], 0, v[52:53]
	global_store_short v[52:53], v37, off
	s_waitcnt lgkmcnt(2)
	v_pk_add_f32 v[52:53], v[56:57], v[60:61]
	ds_bpermute_b32 v57, v59, v53
	ds_bpermute_b32 v56, v59, v52
	s_mov_b64 s[0:1], 0x107c800
	v_lshl_add_u64 v[60:61], v[16:17], 0, s[0:1]
	v_bfe_u32 v31, v45, 16, 1
	v_add3_u32 v31, v45, v31, s5
	s_waitcnt lgkmcnt(0)
	v_pk_add_f32 v[52:53], v[52:53], v[56:57]
	v_lshrrev_b32_e32 v31, 16, v31
	v_pk_fma_f32 v[52:53], v[52:53], s[4:5], v[4:5] op_sel_hi:[1,0,0]
	v_lshl_add_u64 v[56:57], s[2:3], 0, v[60:61]
	v_mul_f32_e32 v41, 0x4b800000, v53
	v_cmp_gt_f32_e64 s[0:1], s53, v53
	global_store_short v[64:65], v31, off
	v_lshl_add_u64 v[64:65], s[10:11], 0, v[60:61]
	v_cndmask_b32_e64 v41, v53, v41, s[0:1]
	v_rsq_f32_e32 v41, v41
	global_store_short v[56:57], v37, off
	v_pk_mul_f32 v[56:57], v[22:23], v[22:23]
	v_mov_b32_e32 v61, 0
	v_mov_b32_e32 v60, 0
	global_store_short v[64:65], v31, off
	v_mov_b32_dpp v61, v57 quad_perm:[1,0,3,2] row_mask:0xf bank_mask:0xf
	v_mov_b32_dpp v60, v56 quad_perm:[1,0,3,2] row_mask:0xf bank_mask:0xf
	v_mul_f32_e32 v31, 0x45800000, v41
	v_pk_fma_f32 v[56:57], v[22:23], v[22:23], v[60:61]
	v_mov_b32_e32 v61, 0
	v_mov_b32_e32 v60, 0
	v_cndmask_b32_e64 v31, v41, v31, s[0:1]
	v_mul_f32_e32 v37, 0x4b800000, v52
	v_cmp_gt_f32_e64 s[0:1], s53, v52
	v_mov_b32_dpp v61, v57 quad_perm:[2,3,0,1] row_mask:0xf bank_mask:0xf
	v_mov_b32_dpp v60, v56 quad_perm:[2,3,0,1] row_mask:0xf bank_mask:0xf
	v_cndmask_b32_e64 v37, v52, v37, s[0:1]
	v_pk_add_f32 v[56:57], v[56:57], v[60:61]
	v_mov_b32_e32 v61, 0
	v_mov_b32_e32 v60, 0
	v_rsq_f32_e32 v37, v37
	v_mov_b32_dpp v61, v57 row_half_mirror row_mask:0xf bank_mask:0xf
	v_mov_b32_dpp v60, v56 row_half_mirror row_mask:0xf bank_mask:0xf
	v_pk_add_f32 v[56:57], v[56:57], v[60:61]
	v_mov_b32_e32 v61, 0
	v_mov_b32_e32 v60, 0
	v_mul_f32_e32 v27, v27, v31
	v_mov_b32_dpp v61, v57 row_mirror row_mask:0xf bank_mask:0xf
	v_mov_b32_dpp v60, v56 row_mirror row_mask:0xf bank_mask:0xf
	v_pk_add_f32 v[56:57], v[56:57], v[60:61]
	v_mul_f32_e32 v31, 0x45800000, v37
	ds_bpermute_b32 v61, v51, v57
	ds_bpermute_b32 v60, v51, v56
	v_cndmask_b32_e64 v31, v37, v31, s[0:1]
	v_mul_f32_e32 v37, v78, v24
	v_mul_f32_e32 v24, v77, v24
	v_bfe_u32 v41, v24, 16, 1
	s_mov_b64 s[0:1], 0x3d000
	v_add3_u32 v41, v24, v41, s5
	v_lshl_add_u64 v[52:53], v[16:17], 0, s[0:1]
	v_lshrrev_b32_e32 v41, 16, v41
	v_lshl_add_u64 v[64:65], s[10:11], 0, v[52:53]
	v_lshl_add_u64 v[52:53], s[2:3], 0, v[52:53]
	global_store_short v[52:53], v41, off
	s_waitcnt lgkmcnt(0)
	v_pk_add_f32 v[52:53], v[56:57], v[60:61]
	ds_bpermute_b32 v57, v59, v53
	ds_bpermute_b32 v56, v59, v52
	v_mul_f32_e32 v37, 0xbfb8aa3b, v37
	v_exp_f32_e32 v37, v37
	s_mov_b64 s[0:1], 0x107d000
	v_mul_f32_e32 v26, v26, v31
	s_waitcnt lgkmcnt(0)
	v_pk_add_f32 v[52:53], v[52:53], v[56:57]
	v_lshl_add_u64 v[60:61], v[16:17], 0, s[0:1]
	v_pk_fma_f32 v[52:53], v[52:53], s[4:5], v[4:5] op_sel_hi:[1,0,0]
	v_mul_f32_e32 v31, v7, v26
	v_mul_f32_e32 v45, 0x4b800000, v53
	v_cmp_gt_f32_e64 s[0:1], s53, v53
	v_add_f32_e32 v26, 1.0, v37
	v_bfe_u32 v37, v31, 16, 1
	v_cndmask_b32_e64 v45, v53, v45, s[0:1]
	v_rsq_f32_e32 v45, v45
	v_add3_u32 v37, v31, v37, s5
	v_lshrrev_b32_e32 v37, 16, v37
	global_store_short v[64:65], v37, off
	v_lshl_add_u64 v[64:65], s[10:11], 0, v[60:61]
	v_lshl_add_u64 v[56:57], s[2:3], 0, v[60:61]
	global_store_short v[64:65], v37, off
	global_store_short v[56:57], v41, off
	v_mul_f32_e32 v37, 0x45800000, v45
	v_pk_mul_f32 v[56:57], v[18:19], v[18:19]
	v_mov_b32_e32 v61, 0
	v_mov_b32_e32 v60, 0
	v_cndmask_b32_e64 v37, v45, v37, s[0:1]
	v_mul_f32_e32 v41, 0x4b800000, v52
	v_cmp_gt_f32_e64 s[0:1], s53, v52
	v_mov_b32_dpp v61, v57 quad_perm:[1,0,3,2] row_mask:0xf bank_mask:0xf
	v_mov_b32_dpp v60, v56 quad_perm:[1,0,3,2] row_mask:0xf bank_mask:0xf
	v_cndmask_b32_e64 v41, v52, v41, s[0:1]
	v_pk_fma_f32 v[56:57], v[18:19], v[18:19], v[60:61]
	v_mov_b32_e32 v61, 0
	v_mov_b32_e32 v60, 0
	v_rsq_f32_e32 v41, v41
	v_mov_b32_dpp v61, v57 quad_perm:[2,3,0,1] row_mask:0xf bank_mask:0xf
	v_mov_b32_dpp v60, v56 quad_perm:[2,3,0,1] row_mask:0xf bank_mask:0xf
	v_pk_add_f32 v[56:57], v[56:57], v[60:61]
	v_mov_b32_e32 v61, 0
	v_mov_b32_e32 v60, 0
	v_mul_f32_e32 v23, v23, v37
	v_mov_b32_dpp v61, v57 row_half_mirror row_mask:0xf bank_mask:0xf
	v_mov_b32_dpp v60, v56 row_half_mirror row_mask:0xf bank_mask:0xf
	v_pk_add_f32 v[56:57], v[56:57], v[60:61]
	v_mov_b32_e32 v61, 0
	v_mov_b32_e32 v60, 0
	v_mul_f32_e32 v37, 0x45800000, v41
	v_mov_b32_dpp v61, v57 row_mirror row_mask:0xf bank_mask:0xf
	v_mov_b32_dpp v60, v56 row_mirror row_mask:0xf bank_mask:0xf
	v_cndmask_b32_e64 v37, v41, v37, s[0:1]
	v_pk_add_f32 v[56:57], v[56:57], v[60:61]
	v_mul_f32_e32 v27, v11, v27
	v_mul_f32_e32 v23, v11, v23
	v_mul_f32_e32 v22, v22, v37
	ds_bpermute_b32 v61, v51, v57
	ds_bpermute_b32 v60, v51, v56
	v_mul_f32_e32 v27, 0x3e000000, v27
	v_mul_f32_e32 v23, 0x3e000000, v23
	v_mul_f32_e32 v37, v7, v22
	v_mul_f32_e32 v22, v76, v20
	v_mul_f32_e32 v20, v75, v20
	ds_write2st64_b32 v67, v27, v23 offset0:10 offset1:11
	ds_write2st64_b32 v67, v31, v37 offset0:26 offset1:27
	v_bfe_u32 v27, v20, 16, 1
	s_mov_b64 s[0:1], 0x3d800
	v_add3_u32 v27, v20, v27, s5
	v_lshl_add_u64 v[52:53], v[16:17], 0, s[0:1]
	v_lshrrev_b32_e32 v27, 16, v27
	v_lshl_add_u64 v[64:65], s[10:11], 0, v[52:53]
	v_lshl_add_u64 v[52:53], s[2:3], 0, v[52:53]
	global_store_short v[52:53], v27, off
	s_waitcnt lgkmcnt(2)
	v_pk_add_f32 v[52:53], v[56:57], v[60:61]
	ds_bpermute_b32 v57, v59, v53
	ds_bpermute_b32 v56, v59, v52
	s_mov_b64 s[0:1], 0x107d800
	v_lshl_add_u64 v[60:61], v[16:17], 0, s[0:1]
	v_bfe_u32 v23, v37, 16, 1
	v_add3_u32 v23, v37, v23, s5
	s_waitcnt lgkmcnt(0)
	v_pk_add_f32 v[52:53], v[52:53], v[56:57]
	v_lshrrev_b32_e32 v23, 16, v23
	v_pk_fma_f32 v[52:53], v[52:53], s[4:5], v[4:5] op_sel_hi:[1,0,0]
	global_store_short v[64:65], v23, off
	v_mul_f32_e32 v31, 0x4b800000, v53
	v_cmp_gt_f32_e64 s[0:1], s53, v53
	v_lshl_add_u64 v[64:65], s[10:11], 0, v[60:61]
	global_store_short v[64:65], v23, off
	v_cndmask_b32_e64 v31, v53, v31, s[0:1]
	v_rsq_f32_e32 v31, v31
	v_lshl_add_u64 v[56:57], s[2:3], 0, v[60:61]
	global_store_short v[56:57], v27, off
	v_mul_f32_e32 v27, 0x4b800000, v52
	v_mul_f32_e32 v23, 0x45800000, v31
	v_cndmask_b32_e64 v23, v31, v23, s[0:1]
	v_cmp_gt_f32_e64 s[0:1], s53, v52
	v_pk_mul_f32 v[56:57], v[12:13], v[12:13]
	v_mov_b32_e32 v61, 0
	v_cndmask_b32_e64 v27, v52, v27, s[0:1]
	v_rsq_f32_e32 v27, v27
	v_mov_b32_e32 v60, 0
	v_mov_b32_dpp v61, v57 quad_perm:[1,0,3,2] row_mask:0xf bank_mask:0xf
	v_mul_f32_e32 v19, v19, v23
	v_mov_b32_dpp v60, v56 quad_perm:[1,0,3,2] row_mask:0xf bank_mask:0xf
	v_pk_fma_f32 v[56:57], v[12:13], v[12:13], v[60:61]
	v_mov_b32_e32 v61, 0
	v_mov_b32_e32 v60, 0
	v_mul_f32_e32 v23, 0x45800000, v27
	v_mov_b32_dpp v61, v57 quad_perm:[2,3,0,1] row_mask:0xf bank_mask:0xf
	v_mov_b32_dpp v60, v56 quad_perm:[2,3,0,1] row_mask:0xf bank_mask:0xf
	v_pk_add_f32 v[56:57], v[56:57], v[60:61]
	v_mov_b32_e32 v61, 0
	v_mov_b32_e32 v60, 0
	v_cndmask_b32_e64 v23, v27, v23, s[0:1]
	v_mul_f32_e32 v27, v74, v14
	v_mov_b32_dpp v61, v57 row_half_mirror row_mask:0xf bank_mask:0xf
	v_mov_b32_dpp v60, v56 row_half_mirror row_mask:0xf bank_mask:0xf
	v_mul_f32_e32 v27, 0xbfb8aa3b, v27
	v_pk_add_f32 v[56:57], v[56:57], v[60:61]
	v_mov_b32_e32 v61, 0
	v_mov_b32_e32 v60, 0
	v_exp_f32_e32 v27, v27
	v_mov_b32_dpp v61, v57 row_mirror row_mask:0xf bank_mask:0xf
	v_mov_b32_dpp v60, v56 row_mirror row_mask:0xf bank_mask:0xf
	v_pk_add_f32 v[56:57], v[56:57], v[60:61]
	v_mul_f32_e32 v18, v18, v23
	ds_bpermute_b32 v61, v51, v57
	ds_bpermute_b32 v60, v51, v56
	v_mul_f32_e32 v31, v7, v18
	v_mul_f32_e32 v18, v73, v14
	v_add_f32_e32 v14, 1.0, v27
	v_bfe_u32 v27, v18, 16, 1
	s_mov_b64 s[0:1], 0x3e000
	v_add3_u32 v27, v18, v27, s5
	v_lshl_add_u64 v[52:53], v[16:17], 0, s[0:1]
	v_lshrrev_b32_e32 v27, 16, v27
	v_lshl_add_u64 v[64:65], s[10:11], 0, v[52:53]
	v_lshl_add_u64 v[52:53], s[2:3], 0, v[52:53]
	global_store_short v[52:53], v27, off
	s_waitcnt lgkmcnt(0)
	v_pk_add_f32 v[52:53], v[56:57], v[60:61]
	ds_bpermute_b32 v57, v59, v53
	ds_bpermute_b32 v56, v59, v52
	s_mov_b64 s[0:1], 0x107e000
	v_lshl_add_u64 v[60:61], v[16:17], 0, s[0:1]
	v_rcp_f32_e32 v23, v14
	v_bfe_u32 v14, v31, 16, 1
	s_waitcnt lgkmcnt(0)
	v_pk_add_f32 v[52:53], v[52:53], v[56:57]
	v_add3_u32 v14, v31, v14, s5
	v_pk_fma_f32 v[52:53], v[52:53], s[4:5], v[4:5] op_sel_hi:[1,0,0]
	v_lshrrev_b32_e32 v14, 16, v14
	v_mul_f32_e32 v37, 0x4b800000, v53
	v_cmp_gt_f32_e64 s[0:1], s53, v53
	global_store_short v[64:65], v14, off
	v_lshl_add_u64 v[64:65], s[10:11], 0, v[60:61]
	v_cndmask_b32_e64 v37, v53, v37, s[0:1]
	v_rsq_f32_e32 v37, v37
	global_store_short v[64:65], v14, off
	v_lshl_add_u64 v[56:57], s[2:3], 0, v[60:61]
	global_store_short v[56:57], v27, off
	v_mul_f32_e32 v14, 0x45800000, v37
	v_cndmask_b32_e64 v14, v37, v14, s[0:1]
	v_mul_f32_e32 v27, 0x4b800000, v52
	v_cmp_gt_f32_e64 s[0:1], s53, v52
	v_mul_f32_e32 v13, v13, v14
	v_mov_b32_e32 v57, 0
	v_cndmask_b32_e64 v27, v52, v27, s[0:1]
	v_rsq_f32_e32 v27, v27
	v_pk_mul_f32 v[52:53], v[8:9], v[8:9]
	v_mov_b32_e32 v56, 0
	v_mul_f32_e32 v19, v11, v19
	v_mul_f32_e32 v14, 0x45800000, v27
	v_cndmask_b32_e64 v14, v27, v14, s[0:1]
	v_mov_b32_dpp v57, v53 quad_perm:[1,0,3,2] row_mask:0xf bank_mask:0xf
	v_mov_b32_dpp v56, v52 quad_perm:[1,0,3,2] row_mask:0xf bank_mask:0xf
	v_mul_f32_e32 v12, v12, v14
	v_mul_f32_e32 v14, v72, v10
	v_pk_fma_f32 v[52:53], v[8:9], v[8:9], v[56:57]
	v_mov_b32_e32 v57, 0
	v_mov_b32_e32 v56, 0
	v_mul_f32_e32 v14, 0xbfb8aa3b, v14
	v_mov_b32_dpp v57, v53 quad_perm:[2,3,0,1] row_mask:0xf bank_mask:0xf
	v_mov_b32_dpp v56, v52 quad_perm:[2,3,0,1] row_mask:0xf bank_mask:0xf
	v_exp_f32_e32 v14, v14
	v_pk_add_f32 v[52:53], v[52:53], v[56:57]
	v_mov_b32_e32 v57, 0
	v_mov_b32_e32 v56, 0
	v_mul_f32_e32 v13, v11, v13
	v_mov_b32_dpp v57, v53 row_half_mirror row_mask:0xf bank_mask:0xf
	v_mov_b32_dpp v56, v52 row_half_mirror row_mask:0xf bank_mask:0xf
	v_pk_add_f32 v[52:53], v[52:53], v[56:57]
	v_mov_b32_e32 v57, 0
	v_mov_b32_e32 v56, 0
	v_mul_f32_e32 v19, 0x3e000000, v19
	v_mul_f32_e32 v13, 0x3e000000, v13
	v_mov_b32_dpp v57, v53 row_mirror row_mask:0xf bank_mask:0xf
	v_mov_b32_dpp v56, v52 row_mirror row_mask:0xf bank_mask:0xf
	v_mul_f32_e32 v12, v7, v12
	ds_write2st64_b32 v67, v19, v13 offset0:12 offset1:13
	ds_write2st64_b32 v67, v31, v12 offset0:28 offset1:29
	v_mul_f32_e32 v19, v71, v10
	v_add_f32_e32 v10, 1.0, v14
	v_pk_add_f32 v[52:53], v[52:53], v[56:57]
	v_rcp_f32_e32 v31, v10
	v_bfe_u32 v10, v12, 16, 1
	ds_bpermute_b32 v57, v51, v53
	ds_bpermute_b32 v56, v51, v52
	v_add3_u32 v10, v12, v10, s5
	v_bfe_u32 v12, v19, 16, 1
	v_add3_u32 v12, v19, v12, s5
	s_mov_b64 s[0:1], 0x3e800
	v_lshrrev_b32_e32 v14, 16, v12
	v_lshl_add_u64 v[12:13], v[16:17], 0, s[0:1]
	v_lshl_add_u64 v[60:61], s[10:11], 0, v[12:13]
	v_lshl_add_u64 v[12:13], s[2:3], 0, v[12:13]
	global_store_short v[12:13], v14, off
	s_waitcnt lgkmcnt(0)
	v_pk_add_f32 v[12:13], v[52:53], v[56:57]
	ds_bpermute_b32 v53, v59, v13
	ds_bpermute_b32 v52, v59, v12
	s_mov_b64 s[0:1], 0x107e800
	v_lshl_add_u64 v[56:57], v[16:17], 0, s[0:1]
	v_lshrrev_b32_e32 v10, 16, v10
	global_store_short v[60:61], v10, off
	s_waitcnt lgkmcnt(0)
	v_pk_add_f32 v[12:13], v[12:13], v[52:53]
	v_lshl_add_u64 v[60:61], s[10:11], 0, v[56:57]
	v_pk_fma_f32 v[12:13], v[12:13], s[4:5], v[4:5] op_sel_hi:[1,0,0]
	global_store_short v[60:61], v10, off
	v_mul_f32_e32 v27, 0x4b800000, v13
	v_cmp_gt_f32_e64 s[0:1], s53, v13
	v_lshl_add_u64 v[52:53], s[2:3], 0, v[56:57]
	global_store_short v[52:53], v14, off
	v_cndmask_b32_e64 v13, v13, v27, s[0:1]
	v_rsq_f32_e32 v13, v13
	v_mul_f32_e32 v27, v69, v6
	v_mov_b32_e32 v53, 0
	v_mov_b32_e32 v52, 0
	v_mul_f32_e32 v10, 0x45800000, v13
	v_cndmask_b32_e64 v10, v13, v10, s[0:1]
	v_mul_f32_e32 v13, 0x4b800000, v12
	v_cmp_gt_f32_e64 s[0:1], s53, v12
	v_mul_f32_e32 v9, v9, v10
	v_mul_f32_e32 v9, v11, v9
	v_cndmask_b32_e64 v12, v12, v13, s[0:1]
	v_rsq_f32_e32 v12, v12
	v_mul_f32_e32 v10, 0x3e000000, v9
	v_rcp_f32_e32 v48, v48
	v_rcp_f32_e32 v44, v44
	v_mul_f32_e32 v9, 0x45800000, v12
	v_cndmask_b32_e64 v9, v12, v9, s[0:1]
	v_mul_f32_e32 v12, v70, v6
	v_mul_f32_e32 v12, 0xbfb8aa3b, v12
	v_exp_f32_e32 v12, v12
	v_mul_f32_e32 v8, v8, v9
	v_mul_f32_e32 v14, v7, v8
	v_bfe_u32 v8, v27, 16, 1
	v_add_f32_e32 v6, 1.0, v12
	v_pk_mul_f32 v[12:13], v[2:3], v[2:3]
	v_add3_u32 v8, v27, v8, s5
	s_mov_b64 s[0:1], 0x3f000
	v_mov_b32_dpp v53, v13 quad_perm:[1,0,3,2] row_mask:0xf bank_mask:0xf
	v_mov_b32_dpp v52, v12 quad_perm:[1,0,3,2] row_mask:0xf bank_mask:0xf
	v_pk_fma_f32 v[12:13], v[2:3], v[2:3], v[52:53]
	v_mov_b32_e32 v53, 0
	v_mov_b32_e32 v52, 0
	v_lshrrev_b32_e32 v41, 16, v8
	v_mov_b32_dpp v53, v13 quad_perm:[2,3,0,1] row_mask:0xf bank_mask:0xf
	v_mov_b32_dpp v52, v12 quad_perm:[2,3,0,1] row_mask:0xf bank_mask:0xf
	v_pk_add_f32 v[12:13], v[12:13], v[52:53]
	v_mov_b32_e32 v53, 0
	v_mov_b32_e32 v52, 0
	v_lshl_add_u64 v[8:9], v[16:17], 0, s[0:1]
	v_mov_b32_dpp v53, v13 row_half_mirror row_mask:0xf bank_mask:0xf
	v_mov_b32_dpp v52, v12 row_half_mirror row_mask:0xf bank_mask:0xf
	v_pk_add_f32 v[12:13], v[12:13], v[52:53]
	v_mov_b32_e32 v53, 0
	v_mov_b32_e32 v52, 0
	v_lshl_add_u64 v[56:57], s[10:11], 0, v[8:9]
	v_mov_b32_dpp v53, v13 row_mirror row_mask:0xf bank_mask:0xf
	v_mov_b32_dpp v52, v12 row_mirror row_mask:0xf bank_mask:0xf
	v_pk_add_f32 v[12:13], v[12:13], v[52:53]
	ds_bpermute_b32 v53, v51, v13
	ds_bpermute_b32 v52, v51, v12
	v_lshl_add_u64 v[8:9], s[2:3], 0, v[8:9]
	global_store_short v[8:9], v41, off
	s_mov_b64 s[0:1], 0x107f000
	v_rcp_f32_e32 v37, v6
	s_waitcnt lgkmcnt(0)
	v_pk_add_f32 v[8:9], v[12:13], v[52:53]
	ds_bpermute_b32 v13, v59, v9
	ds_bpermute_b32 v12, v59, v8
	v_lshl_add_u64 v[52:53], v[16:17], 0, s[0:1]
	v_bfe_u32 v6, v14, 16, 1
	v_add3_u32 v6, v14, v6, s5
	v_lshrrev_b32_e32 v6, 16, v6
	s_waitcnt lgkmcnt(0)
	v_pk_add_f32 v[8:9], v[8:9], v[12:13]
	global_store_short v[56:57], v6, off
	v_pk_fma_f32 v[4:5], v[8:9], s[4:5], v[4:5] op_sel_hi:[1,0,0]
	v_lshl_add_u64 v[56:57], s[10:11], 0, v[52:53]
	v_mul_f32_e32 v8, 0x4b800000, v5
	v_cmp_gt_f32_e64 s[0:1], s53, v5
	global_store_short v[56:57], v6, off
	v_mul_f32_e32 v40, 0xbfb8aa3b, v40
	v_cndmask_b32_e64 v5, v5, v8, s[0:1]
	v_rsq_f32_e32 v5, v5
	v_lshl_add_u64 v[8:9], s[2:3], 0, v[52:53]
	global_store_short v[8:9], v41, off
	v_mul_f32_e32 v41, v1, v0
	v_mul_f32_e32 v6, 0x45800000, v5
	v_cndmask_b32_e64 v5, v5, v6, s[0:1]
	v_mul_f32_e32 v6, 0x4b800000, v4
	v_cmp_gt_f32_e64 s[0:1], s53, v4
	v_mul_f32_e32 v3, v3, v5
	v_mul_f32_e32 v3, v11, v3
	v_cndmask_b32_e64 v4, v4, v6, s[0:1]
	v_rsq_f32_e32 v4, v4
	v_mul_f32_e32 v3, 0x3e000000, v3
	v_exp_f32_e32 v40, v40
	v_rcp_f32_e32 v36, v36
	v_mul_f32_e32 v5, 0x45800000, v4
	v_cndmask_b32_e64 v4, v4, v5, s[0:1]
	v_mul_f32_e32 v2, v2, v4
	v_mul_f32_e32 v4, v15, v0
	v_mul_f32_e32 v4, 0xbfb8aa3b, v4
	v_exp_f32_e32 v4, v4
	v_mul_f32_e32 v2, v7, v2
	s_mov_b64 s[0:1], 0x3f800
	ds_write2st64_b32 v67, v10, v3 offset0:14 offset1:15
	ds_write2st64_b32 v67, v14, v2 offset0:30 offset1:31
	v_add_f32_e32 v0, 1.0, v4
	v_rcp_f32_e32 v45, v0
	v_bfe_u32 v0, v2, 16, 1
	v_add3_u32 v0, v2, v0, s5
	v_lshrrev_b32_e32 v60, 16, v0
	v_bfe_u32 v0, v41, 16, 1
	v_add3_u32 v0, v41, v0, s5
	v_lshrrev_b32_e32 v61, 16, v0
	v_lshl_add_u64 v[0:1], v[16:17], 0, s[0:1]
	v_lshl_add_u64 v[2:3], s[10:11], 0, v[0:1]
	v_lshl_add_u64 v[0:1], s[2:3], 0, v[0:1]
	global_store_short v[0:1], v61, off
	v_and_b32_e32 v0, 0x3ffffff0, v32
	v_lshl_add_u32 v52, v0, 2, s54
	global_store_short v[2:3], v60, off
	v_lshl_add_u32 v0, v39, 8, v52
	ds_read_b128 v[70:73], v52
	ds_read_b128 v[74:77], v52 offset:16
	ds_read_b128 v[12:15], v0 offset:4096
	ds_read_b128 v[78:81], v52 offset:32
	ds_read_b128 v[82:85], v52 offset:48
	ds_read_b128 v[8:11], v0 offset:4112
	ds_read_b128 v[4:7], v0 offset:4128
	ds_read_b128 v[0:3], v0 offset:4144
	s_waitcnt lgkmcnt(5)
	v_mul_f32_e32 v49, v71, v13
	v_mul_f32_e32 v53, v73, v15
	v_fmac_f32_e32 v49, v70, v12
	v_fmac_f32_e32 v53, v72, v14
	v_add_f32_e32 v49, v49, v53
	s_waitcnt lgkmcnt(2)
	v_mul_f32_e32 v53, v75, v9
	v_mul_f32_e32 v56, v77, v11
	v_fmac_f32_e32 v53, v74, v8
	v_fmac_f32_e32 v56, v76, v10
	v_add_f32_e32 v49, 0, v49
	v_add_f32_e32 v53, v53, v56
	v_add_f32_e32 v49, v49, v53
	s_waitcnt lgkmcnt(1)
	v_mul_f32_e32 v53, v79, v5
	v_mul_f32_e32 v56, v81, v7
	v_fmac_f32_e32 v53, v78, v4
	v_fmac_f32_e32 v56, v80, v6
	v_add_f32_e32 v53, v53, v56
	v_add_f32_e32 v49, v49, v53
	s_waitcnt lgkmcnt(0)
	v_mul_f32_e32 v53, v83, v1
	v_mul_f32_e32 v56, v85, v3
	v_fmac_f32_e32 v53, v82, v0
	v_fmac_f32_e32 v56, v84, v2
	v_add_f32_e32 v53, v53, v56
	v_add_f32_e32 v49, v49, v53
	ds_bpermute_b32 v56, v51, v49
	v_cmp_gt_u32_e64 s[0:1], 8, v39
	s_mov_b64 s[54:55], 0x107f800
	v_lshl_add_u64 v[16:17], v[16:17], 0, s[54:55]
	v_cndmask_b32_e64 v53, v66, v68, s[0:1]
	s_waitcnt lgkmcnt(0)
	v_add_f32_e32 v64, v49, v56
	v_lshlrev_b32_e32 v49, 2, v63
	ds_bpermute_b32 v65, v59, v64
	v_and_b32_e32 v49, 0x100, v49
	ds_bpermute_b32 v63, v49, v53
	v_lshl_add_u64 v[56:57], s[10:11], 0, v[16:17]
	global_store_short v[56:57], v60, off
	s_waitcnt lgkmcnt(1)
	v_add_f32_e32 v56, v64, v65
	v_mov_b32_e32 v57, 0xff800000
	s_waitcnt lgkmcnt(0)
	v_add_f32_e32 v56, v56, v63
	v_sub_f32_e32 v56, v56, v53
	v_cndmask_b32_e32 v56, v57, v56, vcc
	v_mov_b32_e32 v60, 0
	v_mov_b32_e32 v63, 0
	ds_read_b128 v[64:67], v52 offset:256
	ds_read_b128 v[68:71], v52 offset:272
	v_mov_b32_dpp v60, v56 quad_perm:[1,0,3,2] row_mask:0xf bank_mask:0xf
	v_max_f32_e32 v60, v60, v60
	v_max_f32_e32 v60, v56, v60
	v_lshl_add_u64 v[16:17], s[2:3], 0, v[16:17]
	global_store_short v[16:17], v61, off
	v_mov_b32_dpp v63, v60 quad_perm:[2,3,0,1] row_mask:0xf bank_mask:0xf
	v_max_f32_e32 v63, v63, v63
	v_max_f32_e32 v60, v60, v63
	v_mov_b32_e32 v63, 0
	s_lshl_b64 s[0:1], s[8:9], 1
	v_readlane_b32 s2, v254, 17
	v_mov_b32_dpp v63, v60 row_half_mirror row_mask:0xf bank_mask:0xf
	v_max_f32_e32 v63, v63, v63
	v_max_f32_e32 v60, v60, v63
	v_mov_b32_e32 v63, 0
	v_readlane_b32 s3, v254, 18
	s_add_u32 s0, s2, s0
	v_mov_b32_dpp v63, v60 row_mirror row_mask:0xf bank_mask:0xf
	v_max_f32_e32 v63, v63, v63
	v_max_f32_e32 v60, v60, v63
	v_sub_f32_e32 v56, v56, v60
	s_waitcnt lgkmcnt(1)
	v_mul_f32_e32 v60, v13, v65
	v_mul_f32_e32 v63, v15, v67
	v_fmac_f32_e32 v60, v12, v64
	v_fmac_f32_e32 v63, v14, v66
	ds_read_b128 v[64:67], v52 offset:288
	v_add_f32_e32 v60, v60, v63
	s_waitcnt lgkmcnt(1)
	v_mul_f32_e32 v63, v9, v69
	v_fmac_f32_e32 v63, v8, v68
	v_mul_f32_e32 v68, v11, v71
	v_fmac_f32_e32 v68, v10, v70
	v_add_f32_e32 v60, 0, v60
	v_add_f32_e32 v63, v63, v68
	ds_read_b128 v[68:71], v52 offset:304
	v_add_f32_e32 v60, v60, v63
	s_waitcnt lgkmcnt(1)
	v_mul_f32_e32 v63, v5, v65
	v_fmac_f32_e32 v63, v4, v64
	v_mul_f32_e32 v64, v7, v67
	v_fmac_f32_e32 v64, v6, v66
	v_add_f32_e32 v63, v63, v64
	v_add_f32_e32 v60, v60, v63
	s_waitcnt lgkmcnt(0)
	v_mul_f32_e32 v63, v1, v69
	v_mul_f32_e32 v64, v3, v71
	v_fmac_f32_e32 v63, v0, v68
	v_fmac_f32_e32 v64, v2, v70
	v_add_f32_e32 v63, v63, v64
	v_add_f32_e32 v60, v60, v63
	ds_bpermute_b32 v63, v51, v60
	v_mul_f32_e32 v56, 0x3fb8aa3b, v56
	v_exp_f32_e32 v56, v56
	ds_read_b128 v[64:67], v52 offset:512
	ds_read_b128 v[68:71], v52 offset:528
	s_waitcnt lgkmcnt(2)
	v_add_f32_e32 v60, v60, v63
	ds_bpermute_b32 v61, v59, v60
	ds_bpermute_b32 v63, v49, v53 offset:4
	v_cndmask_b32_e32 v16, 0, v56, vcc
	v_cmp_lt_u32_e32 vcc, 1, v39
	v_mov_b32_e32 v56, 0
	s_waitcnt lgkmcnt(1)
	v_add_f32_e32 v60, v60, v61
	s_waitcnt lgkmcnt(0)
	v_add_f32_e32 v60, v60, v63
	v_sub_f32_e32 v60, v60, v53
	v_cndmask_b32_e32 v60, v60, v57, vcc
	v_mov_b32_e32 v61, 0
	v_mov_b32_e32 v63, 0
	v_add_f32_dpp v17, v16, v16 quad_perm:[1,0,3,2] row_mask:0xf bank_mask:0xf bound_ctrl:1
	v_mov_b32_dpp v61, v60 quad_perm:[1,0,3,2] row_mask:0xf bank_mask:0xf
	v_max_f32_e32 v61, v61, v61
	v_max_f32_e32 v61, v60, v61
	v_add_f32_dpp v17, v17, v17 quad_perm:[2,3,0,1] row_mask:0xf bank_mask:0xf bound_ctrl:1
	s_addc_u32 s1, s3, s1
	v_mov_b32_dpp v63, v61 quad_perm:[2,3,0,1] row_mask:0xf bank_mask:0xf
	v_max_f32_e32 v63, v63, v63
	v_max_f32_e32 v61, v61, v63
	v_mov_b32_e32 v63, 0
	v_add_f32_dpp v17, v17, v17 row_half_mirror row_mask:0xf bank_mask:0xf bound_ctrl:1
	v_add_f32_e32 v40, 1.0, v40
	v_mov_b32_dpp v63, v61 row_half_mirror row_mask:0xf bank_mask:0xf
	v_max_f32_e32 v63, v63, v63
	v_max_f32_e32 v61, v61, v63
	v_mov_b32_e32 v63, 0
	v_mov_b32_dpp v56, v17 row_mirror row_mask:0xf bank_mask:0xf
	v_rcp_f32_e32 v40, v40
	v_mov_b32_dpp v63, v61 row_mirror row_mask:0xf bank_mask:0xf
	v_max_f32_e32 v63, v63, v63
	v_max_f32_e32 v61, v61, v63
	v_sub_f32_e32 v60, v60, v61
	v_mul_f32_e32 v61, v13, v65
	v_mul_f32_e32 v63, v15, v67
	v_fmac_f32_e32 v61, v12, v64
	v_fmac_f32_e32 v63, v14, v66
	ds_read_b128 v[64:67], v52 offset:544
	v_add_f32_e32 v61, v61, v63
	v_mul_f32_e32 v63, v9, v69
	v_fmac_f32_e32 v63, v8, v68
	v_mul_f32_e32 v68, v11, v71
	v_fmac_f32_e32 v68, v10, v70
	v_add_f32_e32 v61, 0, v61
	v_add_f32_e32 v63, v63, v68
	ds_read_b128 v[68:71], v52 offset:560
	v_add_f32_e32 v61, v61, v63
	s_waitcnt lgkmcnt(1)
	v_mul_f32_e32 v63, v5, v65
	v_fmac_f32_e32 v63, v4, v64
	v_mul_f32_e32 v64, v7, v67
	v_fmac_f32_e32 v64, v6, v66
	v_add_f32_e32 v63, v63, v64
	v_add_f32_e32 v61, v61, v63
	s_waitcnt lgkmcnt(0)
	v_mul_f32_e32 v63, v1, v69
	v_mul_f32_e32 v64, v3, v71
	v_fmac_f32_e32 v63, v0, v68
	v_fmac_f32_e32 v64, v2, v70
	v_add_f32_e32 v63, v63, v64
	v_add_f32_e32 v61, v61, v63
	ds_bpermute_b32 v63, v51, v61
	v_mul_f32_e32 v60, 0x3fb8aa3b, v60
	ds_bpermute_b32 v65, v49, v53 offset:8
	v_exp_f32_e32 v60, v60
	ds_read_b128 v[68:71], v52 offset:784
	s_waitcnt lgkmcnt(2)
	v_add_f32_e32 v61, v61, v63
	ds_bpermute_b32 v63, v59, v61
	v_cndmask_b32_e64 v60, v60, 0, vcc
	v_cmp_lt_u32_e32 vcc, 2, v39
	s_waitcnt lgkmcnt(1)
	v_mul_f32_e32 v69, v9, v69
	v_add_f32_dpp v64, v60, v60 quad_perm:[1,0,3,2] row_mask:0xf bank_mask:0xf bound_ctrl:1
	s_waitcnt lgkmcnt(0)
	v_add_f32_e32 v61, v61, v63
	v_add_f32_e32 v61, v61, v65
	v_sub_f32_e32 v61, v61, v53
	v_add_f32_dpp v64, v64, v64 quad_perm:[2,3,0,1] row_mask:0xf bank_mask:0xf bound_ctrl:1
	v_cndmask_b32_e32 v61, v61, v57, vcc
	v_mov_b32_e32 v63, 0
	v_add_f32_dpp v64, v64, v64 row_half_mirror row_mask:0xf bank_mask:0xf bound_ctrl:1
	v_fmac_f32_e32 v69, v8, v68
	v_mov_b32_dpp v63, v61 quad_perm:[1,0,3,2] row_mask:0xf bank_mask:0xf
	v_add_f32_dpp v64, v64, v64 row_mirror row_mask:0xf bank_mask:0xf bound_ctrl:1
	v_max_f32_e32 v63, v63, v63
	v_rcp_f32_e32 v72, v64
	v_max_f32_e32 v63, v61, v63
	v_mov_b32_e32 v64, 0
	v_mul_f32_e32 v68, v11, v71
	v_fmac_f32_e32 v68, v10, v70
	v_mov_b32_dpp v64, v63 quad_perm:[2,3,0,1] row_mask:0xf bank_mask:0xf
	v_max_f32_e32 v64, v64, v64
	v_max_f32_e32 v63, v63, v64
	v_mov_b32_e32 v64, 0
	v_add_f32_e32 v68, v69, v68
	v_mul_f32_e32 v60, v60, v72
	v_mov_b32_dpp v64, v63 row_half_mirror row_mask:0xf bank_mask:0xf
	v_max_f32_e32 v64, v64, v64
	v_max_f32_e32 v63, v63, v64
	v_mov_b32_e32 v64, 0
	v_mul_f32_e32 v30, 0xbfb8aa3b, v30
	v_exp_f32_e32 v30, v30
	v_mov_b32_dpp v64, v63 row_mirror row_mask:0xf bank_mask:0xf
	v_max_f32_e32 v64, v64, v64
	v_max_f32_e32 v63, v63, v64
	ds_read_b128 v[64:67], v52 offset:768
	v_sub_f32_e32 v61, v61, v63
	v_mul_f32_e32 v61, 0x3fb8aa3b, v61
	v_exp_f32_e32 v61, v61
	v_add_f32_e32 v30, 1.0, v30
	s_waitcnt lgkmcnt(0)
	v_mul_f32_e32 v63, v13, v65
	v_fmac_f32_e32 v63, v12, v64
	v_mul_f32_e32 v64, v15, v67
	v_fmac_f32_e32 v64, v14, v66
	v_add_f32_e32 v63, v63, v64
	ds_read_b128 v[64:67], v52 offset:800
	v_add_f32_e32 v63, 0, v63
	v_add_f32_e32 v63, v63, v68
	ds_read_b128 v[68:71], v52 offset:816
	v_cndmask_b32_e64 v61, v61, 0, vcc
	s_waitcnt lgkmcnt(1)
	v_mul_f32_e32 v65, v5, v65
	v_fmac_f32_e32 v65, v4, v64
	v_mul_f32_e32 v64, v7, v67
	v_fmac_f32_e32 v64, v6, v66
	v_add_f32_e32 v64, v65, v64
	v_add_f32_e32 v63, v63, v64
	s_waitcnt lgkmcnt(0)
	v_mul_f32_e32 v64, v1, v69
	v_mul_f32_e32 v65, v3, v71
	v_fmac_f32_e32 v64, v0, v68
	v_fmac_f32_e32 v65, v2, v70
	v_add_f32_e32 v64, v64, v65
	v_add_f32_e32 v63, v63, v64
	ds_bpermute_b32 v64, v51, v63
	ds_bpermute_b32 v66, v49, v53 offset:12
	v_add_f32_dpp v65, v61, v61 quad_perm:[1,0,3,2] row_mask:0xf bank_mask:0xf bound_ctrl:1
	v_cmp_lt_u32_e32 vcc, 3, v39
	v_rcp_f32_e32 v30, v30
	s_waitcnt lgkmcnt(1)
	v_add_f32_e32 v63, v63, v64
	ds_bpermute_b32 v64, v59, v63
	v_add_f32_dpp v65, v65, v65 quad_perm:[2,3,0,1] row_mask:0xf bank_mask:0xf bound_ctrl:1
	v_rcp_f32_e32 v26, v26
	v_mul_f32_e32 v22, 0xbfb8aa3b, v22
	v_add_f32_dpp v65, v65, v65 row_half_mirror row_mask:0xf bank_mask:0xf bound_ctrl:1
	s_waitcnt lgkmcnt(0)
	v_add_f32_e32 v63, v63, v64
	v_add_f32_e32 v63, v63, v66
	v_sub_f32_e32 v63, v63, v53
	v_cndmask_b32_e32 v63, v63, v57, vcc
	v_mov_b32_e32 v64, 0
	v_add_f32_dpp v65, v65, v65 row_mirror row_mask:0xf bank_mask:0xf bound_ctrl:1
	v_rcp_f32_e32 v72, v65
	v_mov_b32_dpp v64, v63 quad_perm:[1,0,3,2] row_mask:0xf bank_mask:0xf
	v_max_f32_e32 v64, v64, v64
	v_max_f32_e32 v64, v63, v64
	v_mov_b32_e32 v65, 0
	v_mul_f32_e32 v61, v61, v72
	v_exp_f32_e32 v22, v22
	v_mov_b32_dpp v65, v64 quad_perm:[2,3,0,1] row_mask:0xf bank_mask:0xf
	v_max_f32_e32 v65, v65, v65
	v_max_f32_e32 v64, v64, v65
	v_mov_b32_e32 v65, 0
	v_add_f32_e32 v22, 1.0, v22
	v_rcp_f32_e32 v22, v22
	v_mov_b32_dpp v65, v64 row_half_mirror row_mask:0xf bank_mask:0xf
	v_max_f32_e32 v65, v65, v65
	v_max_f32_e32 v64, v64, v65
	v_mov_b32_e32 v65, 0
	s_nop 1
	v_mov_b32_dpp v65, v64 row_mirror row_mask:0xf bank_mask:0xf
	v_max_f32_e32 v65, v65, v65
	v_max_f32_e32 v68, v64, v65
	ds_read_b128 v[64:67], v52 offset:1024
	v_sub_f32_e32 v63, v63, v68
	ds_read_b128 v[68:71], v52 offset:1040
	v_mul_f32_e32 v63, 0x3fb8aa3b, v63
	v_exp_f32_e32 v63, v63
	s_waitcnt lgkmcnt(1)
	v_mul_f32_e32 v65, v13, v65
	v_fmac_f32_e32 v65, v12, v64
	v_mul_f32_e32 v64, v15, v67
	v_fmac_f32_e32 v64, v14, v66
	v_add_f32_e32 v64, v65, v64
	s_waitcnt lgkmcnt(0)
	v_mul_f32_e32 v69, v9, v69
	v_add_f32_e32 v73, 0, v64
	v_fmac_f32_e32 v69, v8, v68
	v_mul_f32_e32 v68, v11, v71
	ds_read_b128 v[64:67], v52 offset:1056
	v_fmac_f32_e32 v68, v10, v70
	v_add_f32_e32 v68, v69, v68
	v_add_f32_e32 v73, v73, v68
	ds_read_b128 v[68:71], v52 offset:1072
	s_waitcnt lgkmcnt(1)
	v_mul_f32_e32 v65, v5, v65
	v_fmac_f32_e32 v65, v4, v64
	v_mul_f32_e32 v64, v7, v67
	v_fmac_f32_e32 v64, v6, v66
	v_add_f32_e32 v64, v65, v64
	s_waitcnt lgkmcnt(0)
	v_mul_f32_e32 v65, v1, v69
	v_mul_f32_e32 v66, v3, v71
	v_fmac_f32_e32 v65, v0, v68
	v_fmac_f32_e32 v66, v2, v70
	v_add_f32_e32 v64, v73, v64
	v_add_f32_e32 v65, v65, v66
	v_add_f32_e32 v64, v64, v65
	ds_bpermute_b32 v65, v51, v64
	ds_bpermute_b32 v67, v49, v53 offset:16
	v_cndmask_b32_e64 v63, v63, 0, vcc
	v_cmp_lt_u32_e32 vcc, 4, v39
	s_waitcnt lgkmcnt(1)
	v_add_f32_e32 v64, v64, v65
	ds_bpermute_b32 v65, v59, v64
	v_add_f32_dpp v66, v63, v63 quad_perm:[1,0,3,2] row_mask:0xf bank_mask:0xf bound_ctrl:1
	s_waitcnt lgkmcnt(0)
	v_add_f32_e32 v64, v64, v65
	v_add_f32_e32 v64, v64, v67
	v_sub_f32_e32 v64, v64, v53
	v_cndmask_b32_e32 v68, v64, v57, vcc
	v_mov_b32_e32 v64, 0
	v_mov_b32_e32 v65, 0
	v_add_f32_dpp v66, v66, v66 quad_perm:[2,3,0,1] row_mask:0xf bank_mask:0xf bound_ctrl:1
	v_mov_b32_dpp v64, v68 quad_perm:[1,0,3,2] row_mask:0xf bank_mask:0xf
	v_max_f32_e32 v64, v64, v64
	v_max_f32_e32 v64, v68, v64
	v_add_f32_dpp v66, v66, v66 row_half_mirror row_mask:0xf bank_mask:0xf bound_ctrl:1
	s_nop 0
	v_mov_b32_dpp v65, v64 quad_perm:[2,3,0,1] row_mask:0xf bank_mask:0xf
	v_max_f32_e32 v65, v65, v65
	v_max_f32_e32 v64, v64, v65
	v_mov_b32_e32 v65, 0
	v_add_f32_dpp v66, v66, v66 row_mirror row_mask:0xf bank_mask:0xf bound_ctrl:1
	v_rcp_f32_e32 v72, v66
	v_mov_b32_dpp v65, v64 row_half_mirror row_mask:0xf bank_mask:0xf
	v_max_f32_e32 v65, v65, v65
	v_max_f32_e32 v64, v64, v65
	v_mov_b32_e32 v65, 0
	v_mul_f32_e32 v63, v63, v72
	s_nop 0
	v_mov_b32_dpp v65, v64 row_mirror row_mask:0xf bank_mask:0xf
	v_max_f32_e32 v65, v65, v65
	v_max_f32_e32 v69, v64, v65
	ds_read_b128 v[64:67], v52 offset:1280
	v_sub_f32_e32 v68, v68, v69
	v_mul_f32_e32 v68, 0x3fb8aa3b, v68
	v_exp_f32_e32 v73, v68
	ds_read_b128 v[68:71], v52 offset:1296
	s_waitcnt lgkmcnt(1)
	v_mul_f32_e32 v65, v13, v65
	v_fmac_f32_e32 v65, v12, v64
	v_mul_f32_e32 v64, v15, v67
	v_fmac_f32_e32 v64, v14, v66
	v_add_f32_e32 v64, v65, v64
	s_waitcnt lgkmcnt(0)
	v_mul_f32_e32 v69, v9, v69
	v_add_f32_e32 v74, 0, v64
	v_fmac_f32_e32 v69, v8, v68
	v_mul_f32_e32 v68, v11, v71
	ds_read_b128 v[64:67], v52 offset:1312
	v_fmac_f32_e32 v68, v10, v70
	v_add_f32_e32 v68, v69, v68
	v_add_f32_e32 v74, v74, v68
	ds_read_b128 v[68:71], v52 offset:1328
	s_waitcnt lgkmcnt(1)
	v_mul_f32_e32 v65, v5, v65
	v_fmac_f32_e32 v65, v4, v64
	v_mul_f32_e32 v64, v7, v67
	v_fmac_f32_e32 v64, v6, v66
	v_add_f32_e32 v64, v65, v64
	s_waitcnt lgkmcnt(0)
	v_mul_f32_e32 v65, v1, v69
	v_mul_f32_e32 v66, v3, v71
	v_fmac_f32_e32 v65, v0, v68
	v_fmac_f32_e32 v66, v2, v70
	v_add_f32_e32 v64, v74, v64
	v_add_f32_e32 v65, v65, v66
	v_add_f32_e32 v64, v64, v65
	ds_bpermute_b32 v65, v51, v64
	ds_bpermute_b32 v67, v49, v53 offset:20
	v_cndmask_b32_e64 v72, v73, 0, vcc
	v_cmp_lt_u32_e32 vcc, 5, v39
	s_waitcnt lgkmcnt(1)
	v_add_f32_e32 v64, v64, v65
	ds_bpermute_b32 v65, v59, v64
	v_add_f32_dpp v66, v72, v72 quad_perm:[1,0,3,2] row_mask:0xf bank_mask:0xf bound_ctrl:1
	s_waitcnt lgkmcnt(0)
	v_add_f32_e32 v64, v64, v65
	v_add_f32_e32 v64, v64, v67
	v_sub_f32_e32 v64, v64, v53
	v_cndmask_b32_e32 v68, v64, v57, vcc
	v_mov_b32_e32 v64, 0
	v_mov_b32_e32 v65, 0
	v_add_f32_dpp v66, v66, v66 quad_perm:[2,3,0,1] row_mask:0xf bank_mask:0xf bound_ctrl:1
	v_mov_b32_dpp v64, v68 quad_perm:[1,0,3,2] row_mask:0xf bank_mask:0xf
	v_max_f32_e32 v64, v64, v64
	v_max_f32_e32 v64, v68, v64
	v_add_f32_dpp v66, v66, v66 row_half_mirror row_mask:0xf bank_mask:0xf bound_ctrl:1
	s_nop 0
	v_mov_b32_dpp v65, v64 quad_perm:[2,3,0,1] row_mask:0xf bank_mask:0xf
	v_max_f32_e32 v65, v65, v65
	v_max_f32_e32 v64, v64, v65
	v_mov_b32_e32 v65, 0
	v_add_f32_dpp v66, v66, v66 row_mirror row_mask:0xf bank_mask:0xf bound_ctrl:1
	v_rcp_f32_e32 v73, v66
	v_mov_b32_dpp v65, v64 row_half_mirror row_mask:0xf bank_mask:0xf
	v_max_f32_e32 v65, v65, v65
	v_max_f32_e32 v64, v64, v65
	v_mov_b32_e32 v65, 0
	s_nop 1
	v_mov_b32_dpp v65, v64 row_mirror row_mask:0xf bank_mask:0xf
	v_max_f32_e32 v65, v65, v65
	v_max_f32_e32 v69, v64, v65
	ds_read_b128 v[64:67], v52 offset:1536
	v_sub_f32_e32 v68, v68, v69
	v_mul_f32_e32 v68, 0x3fb8aa3b, v68
	v_exp_f32_e32 v74, v68
	ds_read_b128 v[68:71], v52 offset:1552
	s_waitcnt lgkmcnt(1)
	v_mul_f32_e32 v65, v13, v65
	v_fmac_f32_e32 v65, v12, v64
	v_mul_f32_e32 v64, v15, v67
	v_fmac_f32_e32 v64, v14, v66
	v_add_f32_e32 v64, v65, v64
	s_waitcnt lgkmcnt(0)
	v_mul_f32_e32 v69, v9, v69
	v_add_f32_e32 v75, 0, v64
	v_fmac_f32_e32 v69, v8, v68
	v_mul_f32_e32 v68, v11, v71
	ds_read_b128 v[64:67], v52 offset:1568
	v_fmac_f32_e32 v68, v10, v70
	v_add_f32_e32 v68, v69, v68
	v_add_f32_e32 v75, v75, v68
	ds_read_b128 v[68:71], v52 offset:1584
	s_waitcnt lgkmcnt(1)
	v_mul_f32_e32 v65, v5, v65
	v_fmac_f32_e32 v65, v4, v64
	v_mul_f32_e32 v64, v7, v67
	v_fmac_f32_e32 v64, v6, v66
	v_add_f32_e32 v64, v65, v64
	s_waitcnt lgkmcnt(0)
	v_mul_f32_e32 v65, v1, v69
	v_mul_f32_e32 v66, v3, v71
	v_fmac_f32_e32 v65, v0, v68
	v_fmac_f32_e32 v66, v2, v70
	v_add_f32_e32 v64, v75, v64
	v_add_f32_e32 v65, v65, v66
	v_add_f32_e32 v65, v64, v65
	ds_bpermute_b32 v66, v51, v65
	ds_bpermute_b32 v68, v49, v53 offset:24
	v_cndmask_b32_e64 v74, v74, 0, vcc
	v_cmp_lt_u32_e32 vcc, 6, v39
	v_mul_f32_e32 v64, v72, v73
	s_waitcnt lgkmcnt(1)
	v_add_f32_e32 v65, v65, v66
	ds_bpermute_b32 v66, v59, v65
	v_add_f32_dpp v67, v74, v74 quad_perm:[1,0,3,2] row_mask:0xf bank_mask:0xf bound_ctrl:1
	s_waitcnt lgkmcnt(0)
	v_add_f32_e32 v65, v65, v66
	v_add_f32_e32 v65, v65, v68
	v_sub_f32_e32 v65, v65, v53
	v_add_f32_dpp v67, v67, v67 quad_perm:[2,3,0,1] row_mask:0xf bank_mask:0xf bound_ctrl:1
	v_cndmask_b32_e32 v65, v65, v57, vcc
	v_mov_b32_e32 v66, 0
	v_add_f32_dpp v67, v67, v67 row_half_mirror row_mask:0xf bank_mask:0xf bound_ctrl:1
	s_nop 0
	v_mov_b32_dpp v66, v65 quad_perm:[1,0,3,2] row_mask:0xf bank_mask:0xf
	v_add_f32_dpp v67, v67, v67 row_mirror row_mask:0xf bank_mask:0xf bound_ctrl:1
	v_max_f32_e32 v66, v66, v66
	v_rcp_f32_e32 v75, v67
	v_max_f32_e32 v66, v65, v66
	v_mov_b32_e32 v67, 0
	s_nop 1
	v_mov_b32_dpp v67, v66 quad_perm:[2,3,0,1] row_mask:0xf bank_mask:0xf
	v_max_f32_e32 v67, v67, v67
	v_max_f32_e32 v66, v66, v67
	v_mov_b32_e32 v67, 0
	s_nop 1
	v_mov_b32_dpp v67, v66 row_half_mirror row_mask:0xf bank_mask:0xf
	v_max_f32_e32 v67, v67, v67
	v_max_f32_e32 v66, v66, v67
	v_mov_b32_e32 v67, 0
	s_nop 1
	v_mov_b32_dpp v67, v66 row_mirror row_mask:0xf bank_mask:0xf
	v_max_f32_e32 v67, v67, v67
	v_max_f32_e32 v70, v66, v67
	ds_read_b128 v[66:69], v52 offset:1792
	v_sub_f32_e32 v65, v65, v70
	ds_read_b128 v[70:73], v52 offset:1808
	v_mul_f32_e32 v65, 0x3fb8aa3b, v65
	v_exp_f32_e32 v76, v65
	s_waitcnt lgkmcnt(1)
	v_mul_f32_e32 v65, v13, v67
	v_fmac_f32_e32 v65, v12, v66
	v_mul_f32_e32 v66, v15, v69
	v_fmac_f32_e32 v66, v14, v68
	v_add_f32_e32 v65, v65, v66
	s_waitcnt lgkmcnt(0)
	v_mul_f32_e32 v71, v9, v71
	ds_read_b128 v[66:69], v52 offset:1824
	v_fmac_f32_e32 v71, v8, v70
	v_mul_f32_e32 v70, v11, v73
	v_fmac_f32_e32 v70, v10, v72
	v_add_f32_e32 v65, 0, v65
	v_add_f32_e32 v70, v71, v70
	v_add_f32_e32 v65, v65, v70
	ds_read_b128 v[70:73], v52 offset:1840
	s_waitcnt lgkmcnt(1)
	v_mul_f32_e32 v67, v5, v67
	v_fmac_f32_e32 v67, v4, v66
	v_mul_f32_e32 v66, v7, v69
	v_fmac_f32_e32 v66, v6, v68
	v_add_f32_e32 v66, v67, v66
	v_add_f32_e32 v65, v65, v66
	s_waitcnt lgkmcnt(0)
	v_mul_f32_e32 v66, v1, v71
	v_mul_f32_e32 v67, v3, v73
	v_fmac_f32_e32 v66, v0, v70
	v_fmac_f32_e32 v67, v2, v72
	v_add_f32_e32 v66, v66, v67
	v_add_f32_e32 v66, v65, v66
	ds_bpermute_b32 v67, v51, v66
	ds_bpermute_b32 v69, v49, v53 offset:28
	v_mul_f32_e32 v65, v74, v75
	v_cndmask_b32_e64 v74, v76, 0, vcc
	v_cmp_lt_u32_e32 vcc, 7, v39
	s_waitcnt lgkmcnt(1)
	v_add_f32_e32 v66, v66, v67
	ds_bpermute_b32 v67, v59, v66
	v_add_f32_dpp v68, v74, v74 quad_perm:[1,0,3,2] row_mask:0xf bank_mask:0xf bound_ctrl:1
	s_waitcnt lgkmcnt(0)
	v_add_f32_e32 v66, v66, v67
	v_add_f32_e32 v66, v66, v69
	v_sub_f32_e32 v66, v66, v53
	v_cndmask_b32_e32 v70, v66, v57, vcc
	v_mov_b32_e32 v66, 0
	v_mov_b32_e32 v67, 0
	v_add_f32_dpp v68, v68, v68 quad_perm:[2,3,0,1] row_mask:0xf bank_mask:0xf bound_ctrl:1
	v_mov_b32_dpp v66, v70 quad_perm:[1,0,3,2] row_mask:0xf bank_mask:0xf
	v_max_f32_e32 v66, v66, v66
	v_max_f32_e32 v66, v70, v66
	v_add_f32_dpp v68, v68, v68 row_half_mirror row_mask:0xf bank_mask:0xf bound_ctrl:1
	s_nop 0
	v_mov_b32_dpp v67, v66 quad_perm:[2,3,0,1] row_mask:0xf bank_mask:0xf
	v_max_f32_e32 v67, v67, v67
	v_max_f32_e32 v66, v66, v67
	v_mov_b32_e32 v67, 0
	v_add_f32_dpp v68, v68, v68 row_mirror row_mask:0xf bank_mask:0xf bound_ctrl:1
	v_rcp_f32_e32 v75, v68
	v_mov_b32_dpp v67, v66 row_half_mirror row_mask:0xf bank_mask:0xf
	v_max_f32_e32 v67, v67, v67
	v_max_f32_e32 v66, v66, v67
	v_mov_b32_e32 v67, 0
	s_nop 1
	v_mov_b32_dpp v67, v66 row_mirror row_mask:0xf bank_mask:0xf
	v_max_f32_e32 v67, v67, v67
	v_max_f32_e32 v71, v66, v67
	ds_read_b128 v[66:69], v52 offset:2048
	v_sub_f32_e32 v70, v70, v71
	v_mul_f32_e32 v70, 0x3fb8aa3b, v70
	v_exp_f32_e32 v76, v70
	ds_read_b128 v[70:73], v52 offset:2064
	s_waitcnt lgkmcnt(1)
	v_mul_f32_e32 v67, v13, v67
	v_fmac_f32_e32 v67, v12, v66
	v_mul_f32_e32 v66, v15, v69
	v_fmac_f32_e32 v66, v14, v68
	v_add_f32_e32 v66, v67, v66
	s_waitcnt lgkmcnt(0)
	v_mul_f32_e32 v71, v9, v71
	v_add_f32_e32 v77, 0, v66
	v_fmac_f32_e32 v71, v8, v70
	v_mul_f32_e32 v70, v11, v73
	ds_read_b128 v[66:69], v52 offset:2080
	v_fmac_f32_e32 v70, v10, v72
	v_add_f32_e32 v70, v71, v70
	v_add_f32_e32 v77, v77, v70
	ds_read_b128 v[70:73], v52 offset:2096
	s_waitcnt lgkmcnt(1)
	v_mul_f32_e32 v67, v5, v67
	v_fmac_f32_e32 v67, v4, v66
	v_mul_f32_e32 v66, v7, v69
	v_fmac_f32_e32 v66, v6, v68
	v_add_f32_e32 v66, v67, v66
	s_waitcnt lgkmcnt(0)
	v_mul_f32_e32 v67, v1, v71
	v_mul_f32_e32 v68, v3, v73
	v_fmac_f32_e32 v67, v0, v70
	v_fmac_f32_e32 v68, v2, v72
	v_add_f32_e32 v66, v77, v66
	v_add_f32_e32 v67, v67, v68
	v_add_f32_e32 v67, v66, v67
	ds_bpermute_b32 v68, v51, v67
	ds_bpermute_b32 v70, v49, v53 offset:32
	v_cndmask_b32_e64 v76, v76, 0, vcc
	v_cmp_lt_u32_e32 vcc, 8, v39
	v_mul_f32_e32 v66, v74, v75
	s_waitcnt lgkmcnt(1)
	v_add_f32_e32 v67, v67, v68
	ds_bpermute_b32 v68, v59, v67
	v_add_f32_dpp v69, v76, v76 quad_perm:[1,0,3,2] row_mask:0xf bank_mask:0xf bound_ctrl:1
	s_waitcnt lgkmcnt(0)
	v_add_f32_e32 v67, v67, v68
	v_add_f32_e32 v67, v67, v70
	v_sub_f32_e32 v67, v67, v53
	v_add_f32_dpp v69, v69, v69 quad_perm:[2,3,0,1] row_mask:0xf bank_mask:0xf bound_ctrl:1
	v_cndmask_b32_e32 v67, v67, v57, vcc
	v_mov_b32_e32 v68, 0
	v_add_f32_dpp v69, v69, v69 row_half_mirror row_mask:0xf bank_mask:0xf bound_ctrl:1
	s_nop 0
	v_mov_b32_dpp v68, v67 quad_perm:[1,0,3,2] row_mask:0xf bank_mask:0xf
	v_add_f32_dpp v69, v69, v69 row_mirror row_mask:0xf bank_mask:0xf bound_ctrl:1
	v_max_f32_e32 v68, v68, v68
	v_rcp_f32_e32 v77, v69
	v_max_f32_e32 v68, v67, v68
	v_mov_b32_e32 v69, 0
	s_nop 1
	v_mov_b32_dpp v69, v68 quad_perm:[2,3,0,1] row_mask:0xf bank_mask:0xf
	v_max_f32_e32 v69, v69, v69
	v_max_f32_e32 v68, v68, v69
	v_mov_b32_e32 v69, 0
	s_nop 1
	v_mov_b32_dpp v69, v68 row_half_mirror row_mask:0xf bank_mask:0xf
	v_max_f32_e32 v69, v69, v69
	v_max_f32_e32 v68, v68, v69
	v_mov_b32_e32 v69, 0
	s_nop 1
	v_mov_b32_dpp v69, v68 row_mirror row_mask:0xf bank_mask:0xf
	v_max_f32_e32 v69, v69, v69
	v_max_f32_e32 v72, v68, v69
	ds_read_b128 v[68:71], v52 offset:2304
	v_sub_f32_e32 v67, v67, v72
	ds_read_b128 v[72:75], v52 offset:2320
	v_mul_f32_e32 v67, 0x3fb8aa3b, v67
	v_exp_f32_e32 v78, v67
	s_waitcnt lgkmcnt(1)
	v_mul_f32_e32 v67, v13, v69
	v_fmac_f32_e32 v67, v12, v68
	v_mul_f32_e32 v68, v15, v71
	v_fmac_f32_e32 v68, v14, v70
	v_add_f32_e32 v67, v67, v68
	s_waitcnt lgkmcnt(0)
	v_mul_f32_e32 v73, v9, v73
	ds_read_b128 v[68:71], v52 offset:2336
	v_fmac_f32_e32 v73, v8, v72
	v_mul_f32_e32 v72, v11, v75
	v_fmac_f32_e32 v72, v10, v74
	v_add_f32_e32 v67, 0, v67
	v_add_f32_e32 v72, v73, v72
	v_add_f32_e32 v67, v67, v72
	ds_read_b128 v[72:75], v52 offset:2352
	s_waitcnt lgkmcnt(1)
	v_mul_f32_e32 v69, v5, v69
	v_fmac_f32_e32 v69, v4, v68
	v_mul_f32_e32 v68, v7, v71
	v_fmac_f32_e32 v68, v6, v70
	v_add_f32_e32 v68, v69, v68
	v_add_f32_e32 v67, v67, v68
	s_waitcnt lgkmcnt(0)
	v_mul_f32_e32 v68, v1, v73
	v_mul_f32_e32 v69, v3, v75
	v_fmac_f32_e32 v68, v0, v72
	v_fmac_f32_e32 v69, v2, v74
	v_add_f32_e32 v68, v68, v69
	v_add_f32_e32 v68, v67, v68
	ds_bpermute_b32 v69, v51, v68
	ds_bpermute_b32 v71, v49, v53 offset:36
	v_mul_f32_e32 v67, v76, v77
	v_cndmask_b32_e64 v76, v78, 0, vcc
	v_cmp_lt_u32_e32 vcc, 9, v39
	s_waitcnt lgkmcnt(1)
	v_add_f32_e32 v68, v68, v69
	ds_bpermute_b32 v69, v59, v68
	v_add_f32_dpp v70, v76, v76 quad_perm:[1,0,3,2] row_mask:0xf bank_mask:0xf bound_ctrl:1
	s_waitcnt lgkmcnt(0)
	v_add_f32_e32 v68, v68, v69
	v_add_f32_e32 v68, v68, v71
	v_sub_f32_e32 v68, v68, v53
	v_cndmask_b32_e32 v72, v68, v57, vcc
	v_mov_b32_e32 v68, 0
	v_mov_b32_e32 v69, 0
	v_add_f32_dpp v70, v70, v70 quad_perm:[2,3,0,1] row_mask:0xf bank_mask:0xf bound_ctrl:1
	v_mov_b32_dpp v68, v72 quad_perm:[1,0,3,2] row_mask:0xf bank_mask:0xf
	v_max_f32_e32 v68, v68, v68
	v_max_f32_e32 v68, v72, v68
	v_add_f32_dpp v70, v70, v70 row_half_mirror row_mask:0xf bank_mask:0xf bound_ctrl:1
	s_nop 0
	v_mov_b32_dpp v69, v68 quad_perm:[2,3,0,1] row_mask:0xf bank_mask:0xf
	v_max_f32_e32 v69, v69, v69
	v_max_f32_e32 v68, v68, v69
	v_mov_b32_e32 v69, 0
	v_add_f32_dpp v70, v70, v70 row_mirror row_mask:0xf bank_mask:0xf bound_ctrl:1
	v_rcp_f32_e32 v77, v70
	v_mov_b32_dpp v69, v68 row_half_mirror row_mask:0xf bank_mask:0xf
	v_max_f32_e32 v69, v69, v69
	v_max_f32_e32 v68, v68, v69
	v_mov_b32_e32 v69, 0
	s_nop 1
	v_mov_b32_dpp v69, v68 row_mirror row_mask:0xf bank_mask:0xf
	v_max_f32_e32 v69, v69, v69
	v_max_f32_e32 v73, v68, v69
	ds_read_b128 v[68:71], v52 offset:2560
	v_sub_f32_e32 v72, v72, v73
	v_mul_f32_e32 v72, 0x3fb8aa3b, v72
	v_exp_f32_e32 v78, v72
	ds_read_b128 v[72:75], v52 offset:2576
	s_waitcnt lgkmcnt(1)
	v_mul_f32_e32 v69, v13, v69
	v_fmac_f32_e32 v69, v12, v68
	v_mul_f32_e32 v68, v15, v71
	v_fmac_f32_e32 v68, v14, v70
	v_add_f32_e32 v68, v69, v68
	s_waitcnt lgkmcnt(0)
	v_mul_f32_e32 v73, v9, v73
	v_add_f32_e32 v79, 0, v68
	v_fmac_f32_e32 v73, v8, v72
	v_mul_f32_e32 v72, v11, v75
	ds_read_b128 v[68:71], v52 offset:2592
	v_fmac_f32_e32 v72, v10, v74
	v_add_f32_e32 v72, v73, v72
	v_add_f32_e32 v79, v79, v72
	ds_read_b128 v[72:75], v52 offset:2608
	s_waitcnt lgkmcnt(1)
	v_mul_f32_e32 v69, v5, v69
	v_fmac_f32_e32 v69, v4, v68
	v_mul_f32_e32 v68, v7, v71
	v_fmac_f32_e32 v68, v6, v70
	v_add_f32_e32 v68, v69, v68
	s_waitcnt lgkmcnt(0)
	v_mul_f32_e32 v69, v1, v73
	v_mul_f32_e32 v70, v3, v75
	v_fmac_f32_e32 v69, v0, v72
	v_fmac_f32_e32 v70, v2, v74
	v_add_f32_e32 v68, v79, v68
	v_add_f32_e32 v69, v69, v70
	v_add_f32_e32 v69, v68, v69
	ds_bpermute_b32 v70, v51, v69
	ds_bpermute_b32 v72, v49, v53 offset:40
	v_cndmask_b32_e64 v78, v78, 0, vcc
	v_cmp_lt_u32_e32 vcc, 10, v39
	v_mul_f32_e32 v68, v76, v77
	s_waitcnt lgkmcnt(1)
	v_add_f32_e32 v69, v69, v70
	ds_bpermute_b32 v70, v59, v69
	v_add_f32_dpp v71, v78, v78 quad_perm:[1,0,3,2] row_mask:0xf bank_mask:0xf bound_ctrl:1
	s_waitcnt lgkmcnt(0)
	v_add_f32_e32 v69, v69, v70
	v_add_f32_e32 v69, v69, v72
	v_sub_f32_e32 v69, v69, v53
	v_add_f32_dpp v71, v71, v71 quad_perm:[2,3,0,1] row_mask:0xf bank_mask:0xf bound_ctrl:1
	v_cndmask_b32_e32 v69, v69, v57, vcc
	v_mov_b32_e32 v70, 0
	v_add_f32_dpp v71, v71, v71 row_half_mirror row_mask:0xf bank_mask:0xf bound_ctrl:1
	s_nop 0
	v_mov_b32_dpp v70, v69 quad_perm:[1,0,3,2] row_mask:0xf bank_mask:0xf
	v_add_f32_dpp v71, v71, v71 row_mirror row_mask:0xf bank_mask:0xf bound_ctrl:1
	v_max_f32_e32 v70, v70, v70
	v_rcp_f32_e32 v79, v71
	v_max_f32_e32 v70, v69, v70
	v_mov_b32_e32 v71, 0
	s_nop 1
	v_mov_b32_dpp v71, v70 quad_perm:[2,3,0,1] row_mask:0xf bank_mask:0xf
	v_max_f32_e32 v71, v71, v71
	v_max_f32_e32 v70, v70, v71
	v_mov_b32_e32 v71, 0
	s_nop 1
	v_mov_b32_dpp v71, v70 row_half_mirror row_mask:0xf bank_mask:0xf
	v_max_f32_e32 v71, v71, v71
	v_max_f32_e32 v70, v70, v71
	v_mov_b32_e32 v71, 0
	s_nop 1
	v_mov_b32_dpp v71, v70 row_mirror row_mask:0xf bank_mask:0xf
	v_max_f32_e32 v71, v71, v71
	v_max_f32_e32 v74, v70, v71
	ds_read_b128 v[70:73], v52 offset:2816
	v_sub_f32_e32 v69, v69, v74
	ds_read_b128 v[74:77], v52 offset:2832
	v_mul_f32_e32 v69, 0x3fb8aa3b, v69
	v_exp_f32_e32 v80, v69
	s_waitcnt lgkmcnt(1)
	v_mul_f32_e32 v69, v13, v71
	v_fmac_f32_e32 v69, v12, v70
	v_mul_f32_e32 v70, v15, v73
	v_fmac_f32_e32 v70, v14, v72
	v_add_f32_e32 v69, v69, v70
	s_waitcnt lgkmcnt(0)
	v_mul_f32_e32 v75, v9, v75
	ds_read_b128 v[70:73], v52 offset:2848
	v_fmac_f32_e32 v75, v8, v74
	v_mul_f32_e32 v74, v11, v77
	v_fmac_f32_e32 v74, v10, v76
	v_add_f32_e32 v69, 0, v69
	v_add_f32_e32 v74, v75, v74
	v_add_f32_e32 v69, v69, v74
	ds_read_b128 v[74:77], v52 offset:2864
	s_waitcnt lgkmcnt(1)
	v_mul_f32_e32 v71, v5, v71
	v_fmac_f32_e32 v71, v4, v70
	v_mul_f32_e32 v70, v7, v73
	v_fmac_f32_e32 v70, v6, v72
	v_add_f32_e32 v70, v71, v70
	v_add_f32_e32 v69, v69, v70
	s_waitcnt lgkmcnt(0)
	v_mul_f32_e32 v70, v1, v75
	v_mul_f32_e32 v71, v3, v77
	v_fmac_f32_e32 v70, v0, v74
	v_fmac_f32_e32 v71, v2, v76
	v_add_f32_e32 v70, v70, v71
	v_add_f32_e32 v70, v69, v70
	ds_bpermute_b32 v71, v51, v70
	ds_bpermute_b32 v73, v49, v53 offset:44
	v_mul_f32_e32 v69, v78, v79
	v_cndmask_b32_e64 v78, v80, 0, vcc
	v_cmp_lt_u32_e32 vcc, 11, v39
	s_waitcnt lgkmcnt(1)
	v_add_f32_e32 v70, v70, v71
	ds_bpermute_b32 v71, v59, v70
	v_add_f32_dpp v72, v78, v78 quad_perm:[1,0,3,2] row_mask:0xf bank_mask:0xf bound_ctrl:1
	s_waitcnt lgkmcnt(0)
	v_add_f32_e32 v70, v70, v71
	v_add_f32_e32 v70, v70, v73
	v_sub_f32_e32 v70, v70, v53
	v_cndmask_b32_e32 v74, v70, v57, vcc
	v_mov_b32_e32 v70, 0
	v_mov_b32_e32 v71, 0
	v_add_f32_dpp v72, v72, v72 quad_perm:[2,3,0,1] row_mask:0xf bank_mask:0xf bound_ctrl:1
	v_mov_b32_dpp v70, v74 quad_perm:[1,0,3,2] row_mask:0xf bank_mask:0xf
	v_max_f32_e32 v70, v70, v70
	v_max_f32_e32 v70, v74, v70
	v_add_f32_dpp v72, v72, v72 row_half_mirror row_mask:0xf bank_mask:0xf bound_ctrl:1
	s_nop 0
	v_mov_b32_dpp v71, v70 quad_perm:[2,3,0,1] row_mask:0xf bank_mask:0xf
	v_max_f32_e32 v71, v71, v71
	v_max_f32_e32 v70, v70, v71
	v_mov_b32_e32 v71, 0
	v_add_f32_dpp v72, v72, v72 row_mirror row_mask:0xf bank_mask:0xf bound_ctrl:1
	v_rcp_f32_e32 v79, v72
	v_mov_b32_dpp v71, v70 row_half_mirror row_mask:0xf bank_mask:0xf
	v_max_f32_e32 v71, v71, v71
	v_max_f32_e32 v70, v70, v71
	v_mov_b32_e32 v71, 0
	s_nop 1
	v_mov_b32_dpp v71, v70 row_mirror row_mask:0xf bank_mask:0xf
	v_max_f32_e32 v71, v71, v71
	v_max_f32_e32 v75, v70, v71
	ds_read_b128 v[70:73], v52 offset:3072
	v_sub_f32_e32 v74, v74, v75
	v_mul_f32_e32 v74, 0x3fb8aa3b, v74
	v_exp_f32_e32 v80, v74
	ds_read_b128 v[74:77], v52 offset:3088
	s_waitcnt lgkmcnt(1)
	v_mul_f32_e32 v71, v13, v71
	v_fmac_f32_e32 v71, v12, v70
	v_mul_f32_e32 v70, v15, v73
	v_fmac_f32_e32 v70, v14, v72
	v_add_f32_e32 v70, v71, v70
	s_waitcnt lgkmcnt(0)
	v_mul_f32_e32 v75, v9, v75
	v_add_f32_e32 v81, 0, v70
	v_fmac_f32_e32 v75, v8, v74
	v_mul_f32_e32 v74, v11, v77
	ds_read_b128 v[70:73], v52 offset:3104
	v_fmac_f32_e32 v74, v10, v76
	v_add_f32_e32 v74, v75, v74
	v_add_f32_e32 v81, v81, v74
	ds_read_b128 v[74:77], v52 offset:3120
	s_waitcnt lgkmcnt(1)
	v_mul_f32_e32 v71, v5, v71
	v_fmac_f32_e32 v71, v4, v70
	v_mul_f32_e32 v70, v7, v73
	v_fmac_f32_e32 v70, v6, v72
	v_add_f32_e32 v70, v71, v70
	s_waitcnt lgkmcnt(0)
	v_mul_f32_e32 v71, v1, v75
	v_mul_f32_e32 v72, v3, v77
	v_fmac_f32_e32 v71, v0, v74
	v_fmac_f32_e32 v72, v2, v76
	v_add_f32_e32 v70, v81, v70
	v_add_f32_e32 v71, v71, v72
	v_add_f32_e32 v71, v70, v71
	ds_bpermute_b32 v72, v51, v71
	ds_bpermute_b32 v74, v49, v53 offset:48
	v_cndmask_b32_e64 v80, v80, 0, vcc
	v_cmp_lt_u32_e32 vcc, 12, v39
	v_mul_f32_e32 v70, v78, v79
	s_waitcnt lgkmcnt(1)
	v_add_f32_e32 v71, v71, v72
	ds_bpermute_b32 v72, v59, v71
	v_add_f32_dpp v73, v80, v80 quad_perm:[1,0,3,2] row_mask:0xf bank_mask:0xf bound_ctrl:1
	s_waitcnt lgkmcnt(0)
	v_add_f32_e32 v71, v71, v72
	v_add_f32_e32 v71, v71, v74
	v_sub_f32_e32 v71, v71, v53
	v_add_f32_dpp v73, v73, v73 quad_perm:[2,3,0,1] row_mask:0xf bank_mask:0xf bound_ctrl:1
	v_cndmask_b32_e32 v71, v71, v57, vcc
	v_mov_b32_e32 v72, 0
	v_add_f32_dpp v73, v73, v73 row_half_mirror row_mask:0xf bank_mask:0xf bound_ctrl:1
	s_nop 0
	v_mov_b32_dpp v72, v71 quad_perm:[1,0,3,2] row_mask:0xf bank_mask:0xf
	v_add_f32_dpp v73, v73, v73 row_mirror row_mask:0xf bank_mask:0xf bound_ctrl:1
	v_max_f32_e32 v72, v72, v72
	v_rcp_f32_e32 v81, v73
	v_max_f32_e32 v72, v71, v72
	v_mov_b32_e32 v73, 0
	s_nop 1
	v_mov_b32_dpp v73, v72 quad_perm:[2,3,0,1] row_mask:0xf bank_mask:0xf
	v_max_f32_e32 v73, v73, v73
	v_max_f32_e32 v72, v72, v73
	v_mov_b32_e32 v73, 0
	s_nop 1
	v_mov_b32_dpp v73, v72 row_half_mirror row_mask:0xf bank_mask:0xf
	v_max_f32_e32 v73, v73, v73
	v_max_f32_e32 v72, v72, v73
	v_mov_b32_e32 v73, 0
	s_nop 1
	v_mov_b32_dpp v73, v72 row_mirror row_mask:0xf bank_mask:0xf
	v_max_f32_e32 v73, v73, v73
	v_max_f32_e32 v76, v72, v73
	ds_read_b128 v[72:75], v52 offset:3328
	v_sub_f32_e32 v71, v71, v76
	ds_read_b128 v[76:79], v52 offset:3344
	v_mul_f32_e32 v71, 0x3fb8aa3b, v71
	v_exp_f32_e32 v82, v71
	s_waitcnt lgkmcnt(1)
	v_mul_f32_e32 v71, v13, v73
	v_fmac_f32_e32 v71, v12, v72
	v_mul_f32_e32 v72, v15, v75
	v_fmac_f32_e32 v72, v14, v74
	v_add_f32_e32 v71, v71, v72
	s_waitcnt lgkmcnt(0)
	v_mul_f32_e32 v77, v9, v77
	ds_read_b128 v[72:75], v52 offset:3360
	v_fmac_f32_e32 v77, v8, v76
	v_mul_f32_e32 v76, v11, v79
	v_fmac_f32_e32 v76, v10, v78
	v_add_f32_e32 v71, 0, v71
	v_add_f32_e32 v76, v77, v76
	v_add_f32_e32 v71, v71, v76
	ds_read_b128 v[76:79], v52 offset:3376
	s_waitcnt lgkmcnt(1)
	v_mul_f32_e32 v73, v5, v73
	v_fmac_f32_e32 v73, v4, v72
	v_mul_f32_e32 v72, v7, v75
	v_fmac_f32_e32 v72, v6, v74
	v_add_f32_e32 v72, v73, v72
	v_add_f32_e32 v71, v71, v72
	s_waitcnt lgkmcnt(0)
	v_mul_f32_e32 v72, v1, v77
	v_mul_f32_e32 v73, v3, v79
	v_fmac_f32_e32 v72, v0, v76
	v_fmac_f32_e32 v73, v2, v78
	v_add_f32_e32 v72, v72, v73
	v_add_f32_e32 v72, v71, v72
	ds_bpermute_b32 v73, v51, v72
	ds_bpermute_b32 v75, v49, v53 offset:52
	v_mul_f32_e32 v71, v80, v81
	v_cndmask_b32_e64 v80, v82, 0, vcc
	v_cmp_lt_u32_e32 vcc, 13, v39
	s_waitcnt lgkmcnt(1)
	v_add_f32_e32 v72, v72, v73
	ds_bpermute_b32 v73, v59, v72
	v_add_f32_dpp v74, v80, v80 quad_perm:[1,0,3,2] row_mask:0xf bank_mask:0xf bound_ctrl:1
	s_waitcnt lgkmcnt(0)
	v_add_f32_e32 v72, v72, v73
	v_add_f32_e32 v72, v72, v75
	v_sub_f32_e32 v72, v72, v53
	v_cndmask_b32_e32 v76, v72, v57, vcc
	v_mov_b32_e32 v72, 0
	v_mov_b32_e32 v73, 0
	v_add_f32_dpp v74, v74, v74 quad_perm:[2,3,0,1] row_mask:0xf bank_mask:0xf bound_ctrl:1
	v_mov_b32_dpp v72, v76 quad_perm:[1,0,3,2] row_mask:0xf bank_mask:0xf
	v_max_f32_e32 v72, v72, v72
	v_max_f32_e32 v72, v76, v72
	v_add_f32_dpp v74, v74, v74 row_half_mirror row_mask:0xf bank_mask:0xf bound_ctrl:1
	s_nop 0
	v_mov_b32_dpp v73, v72 quad_perm:[2,3,0,1] row_mask:0xf bank_mask:0xf
	v_max_f32_e32 v73, v73, v73
	v_max_f32_e32 v72, v72, v73
	v_mov_b32_e32 v73, 0
	v_add_f32_dpp v74, v74, v74 row_mirror row_mask:0xf bank_mask:0xf bound_ctrl:1
	v_rcp_f32_e32 v81, v74
	v_mov_b32_dpp v73, v72 row_half_mirror row_mask:0xf bank_mask:0xf
	v_max_f32_e32 v73, v73, v73
	v_max_f32_e32 v72, v72, v73
	v_mov_b32_e32 v73, 0
	s_nop 1
	v_mov_b32_dpp v73, v72 row_mirror row_mask:0xf bank_mask:0xf
	v_max_f32_e32 v73, v73, v73
	v_max_f32_e32 v77, v72, v73
	ds_read_b128 v[72:75], v52 offset:3584
	v_sub_f32_e32 v76, v76, v77
	v_mul_f32_e32 v76, 0x3fb8aa3b, v76
	v_exp_f32_e32 v82, v76
	ds_read_b128 v[76:79], v52 offset:3600
	s_waitcnt lgkmcnt(1)
	v_mul_f32_e32 v73, v13, v73
	v_fmac_f32_e32 v73, v12, v72
	v_mul_f32_e32 v72, v15, v75
	v_fmac_f32_e32 v72, v14, v74
	v_add_f32_e32 v72, v73, v72
	s_waitcnt lgkmcnt(0)
	v_mul_f32_e32 v77, v9, v77
	v_add_f32_e32 v83, 0, v72
	v_fmac_f32_e32 v77, v8, v76
	v_mul_f32_e32 v76, v11, v79
	ds_read_b128 v[72:75], v52 offset:3616
	v_fmac_f32_e32 v76, v10, v78
	v_add_f32_e32 v76, v77, v76
	v_add_f32_e32 v83, v83, v76
	ds_read_b128 v[76:79], v52 offset:3632
	s_waitcnt lgkmcnt(1)
	v_mul_f32_e32 v73, v5, v73
	v_fmac_f32_e32 v73, v4, v72
	v_mul_f32_e32 v72, v7, v75
	v_fmac_f32_e32 v72, v6, v74
	v_add_f32_e32 v72, v73, v72
	s_waitcnt lgkmcnt(0)
	v_mul_f32_e32 v73, v1, v77
	v_mul_f32_e32 v74, v3, v79
	v_fmac_f32_e32 v73, v0, v76
	v_fmac_f32_e32 v74, v2, v78
	v_add_f32_e32 v72, v83, v72
	v_add_f32_e32 v73, v73, v74
	v_add_f32_e32 v73, v72, v73
	ds_bpermute_b32 v74, v51, v73
	v_cndmask_b32_e64 v82, v82, 0, vcc
	ds_bpermute_b32 v76, v49, v53 offset:56
	v_mul_f32_e32 v72, v80, v81
	v_add_f32_dpp v75, v82, v82 quad_perm:[1,0,3,2] row_mask:0xf bank_mask:0xf bound_ctrl:1
	s_waitcnt lgkmcnt(1)
	v_add_f32_e32 v73, v73, v74
	ds_bpermute_b32 v74, v59, v73
	v_add_f32_dpp v75, v75, v75 quad_perm:[2,3,0,1] row_mask:0xf bank_mask:0xf bound_ctrl:1
	ds_read_b128 v[78:81], v52 offset:3856
	v_cmp_eq_u32_e32 vcc, 15, v39
	v_add_f32_dpp v75, v75, v75 row_half_mirror row_mask:0xf bank_mask:0xf bound_ctrl:1
	s_waitcnt lgkmcnt(1)
	v_add_f32_e32 v73, v73, v74
	v_add_f32_e32 v73, v73, v76
	v_add_f32_dpp v75, v75, v75 row_mirror row_mask:0xf bank_mask:0xf bound_ctrl:1
	v_rcp_f32_e32 v83, v75
	ds_read_b128 v[74:77], v52 offset:3840
	s_waitcnt lgkmcnt(1)
	v_mul_f32_e32 v9, v9, v79
	v_fmac_f32_e32 v9, v8, v78
	v_mul_f32_e32 v8, v11, v81
	v_fmac_f32_e32 v8, v10, v80
	s_waitcnt lgkmcnt(0)
	v_mul_f32_e32 v13, v13, v75
	v_fmac_f32_e32 v13, v12, v74
	v_mul_f32_e32 v12, v15, v77
	v_fmac_f32_e32 v12, v14, v76
	v_add_f32_e32 v12, v13, v12
	v_add_f32_e32 v74, 0, v12
	ds_read_b128 v[12:15], v52 offset:3872
	v_add_f32_e32 v8, v9, v8
	v_add_f32_e32 v74, v74, v8
	ds_read_b128 v[8:11], v52 offset:3888
	v_sub_f32_e32 v73, v73, v53
	s_waitcnt lgkmcnt(1)
	v_mul_f32_e32 v5, v5, v13
	v_fmac_f32_e32 v5, v4, v12
	v_mul_f32_e32 v4, v7, v15
	s_waitcnt lgkmcnt(0)
	v_mul_f32_e32 v1, v1, v9
	v_fmac_f32_e32 v4, v6, v14
	v_fmac_f32_e32 v1, v0, v8
	v_mul_f32_e32 v0, v3, v11
	v_add_f32_e32 v4, v5, v4
	v_fmac_f32_e32 v0, v2, v10
	v_add_f32_e32 v4, v74, v4
	v_add_f32_e32 v0, v1, v0
	v_add_f32_e32 v0, v4, v0
	ds_bpermute_b32 v1, v51, v0
	ds_bpermute_b32 v3, v49, v53 offset:60
	v_cndmask_b32_e32 v39, v73, v57, vcc
	v_mov_b32_e32 v57, 0
	v_mov_b32_e32 v73, 0
	s_waitcnt lgkmcnt(1)
	v_add_f32_e32 v0, v0, v1
	ds_bpermute_b32 v1, v59, v0
	v_mov_b32_dpp v57, v39 quad_perm:[1,0,3,2] row_mask:0xf bank_mask:0xf
	v_max_f32_e32 v57, v57, v57
	v_max_f32_e32 v57, v39, v57
	ds_bpermute_b32 v6, v49, v60 offset:4
	s_waitcnt lgkmcnt(1)
	v_add_f32_e32 v0, v0, v1
	v_add_f32_e32 v0, v0, v3
	v_sub_f32_e32 v0, v0, v53
	v_mov_b32_e32 v1, 0
	v_mov_b32_e32 v3, 0
	v_mov_b32_dpp v73, v57 quad_perm:[2,3,0,1] row_mask:0xf bank_mask:0xf
	v_mov_b32_dpp v1, v0 quad_perm:[1,0,3,2] row_mask:0xf bank_mask:0xf
	v_max_f32_e32 v1, v1, v1
	v_max_f32_e32 v1, v0, v1
	v_max_f32_e32 v73, v73, v73
	v_max_f32_e32 v57, v57, v73
	v_mov_b32_dpp v3, v1 quad_perm:[2,3,0,1] row_mask:0xf bank_mask:0xf
	v_max_f32_e32 v3, v3, v3
	v_mov_b32_e32 v73, 0
	v_max_f32_e32 v1, v1, v3
	v_mov_b32_e32 v3, 0
	v_mov_b32_dpp v73, v57 row_half_mirror row_mask:0xf bank_mask:0xf
	v_max_f32_e32 v73, v73, v73
	v_mov_b32_dpp v3, v1 row_half_mirror row_mask:0xf bank_mask:0xf
	v_max_f32_e32 v3, v3, v3
	v_max_f32_e32 v57, v57, v73
	v_mov_b32_e32 v73, 0
	v_max_f32_e32 v1, v1, v3
	ds_bpermute_b32 v9, v49, v61 offset:8
	v_mov_b32_dpp v73, v57 row_mirror row_mask:0xf bank_mask:0xf
	v_mov_b32_dpp v21, v1 row_mirror row_mask:0xf bank_mask:0xf
	v_max_f32_e32 v73, v73, v73
	v_max_f32_e32 v3, v21, v21
	v_max_f32_e32 v2, v57, v73
	v_max_f32_e32 v1, v1, v3
	v_sub_f32_e32 v2, v39, v2
	v_sub_f32_e32 v0, v0, v1
	v_mul_f32_e32 v2, 0x3fb8aa3b, v2
	v_mul_f32_e32 v0, 0x3fb8aa3b, v0
	v_exp_f32_e32 v2, v2
	v_exp_f32_e32 v0, v0
	ds_bpermute_b32 v10, v49, v63
	ds_bpermute_b32 v11, v49, v63 offset:4
	v_cndmask_b32_e64 v2, v2, 0, vcc
	v_add_f32_dpp v3, v0, v0 quad_perm:[1,0,3,2] row_mask:0xf bank_mask:0xf bound_ctrl:1
	ds_bpermute_b32 v12, v49, v63 offset:8
	v_add_f32_dpp v4, v2, v2 quad_perm:[1,0,3,2] row_mask:0xf bank_mask:0xf bound_ctrl:1
	v_add_f32_dpp v3, v3, v3 quad_perm:[2,3,0,1] row_mask:0xf bank_mask:0xf bound_ctrl:1
	ds_bpermute_b32 v13, v49, v63 offset:12
	v_add_f32_dpp v4, v4, v4 quad_perm:[2,3,0,1] row_mask:0xf bank_mask:0xf bound_ctrl:1
	v_add_f32_dpp v3, v3, v3 row_half_mirror row_mask:0xf bank_mask:0xf bound_ctrl:1
	ds_bpermute_b32 v14, v49, v67 offset:28
	v_add_f32_dpp v1, v4, v4 row_half_mirror row_mask:0xf bank_mask:0xf bound_ctrl:1
	v_add_f32_dpp v3, v3, v3 row_mirror row_mask:0xf bank_mask:0xf bound_ctrl:1
	v_rcp_f32_e32 v4, v3
	v_add_f32_dpp v1, v1, v1 row_mirror row_mask:0xf bank_mask:0xf bound_ctrl:1
	v_add_f32_e32 v3, v17, v56
	v_rcp_f32_e32 v1, v1
	v_rcp_f32_e32 v5, v3
	v_mul_f32_e32 v8, v82, v83
	v_mul_f32_e32 v3, v2, v1
	v_mul_f32_e32 v2, v0, v4
	v_mul_f32_e32 v0, v16, v5
	ds_bpermute_b32 v4, v49, v0
	ds_bpermute_b32 v5, v49, v60
	v_lshl_add_u64 v[0:1], v[32:33], 1, s[0:1]
	s_mov_b64 s[0:1], 0
	s_waitcnt lgkmcnt(1)
	v_fma_f32 v4, v25, v4, 0
	v_mul_f32_e32 v4, v55, v4
	v_bfe_u32 v7, v4, 16, 1
	v_add3_u32 v4, v4, v7, s5
	global_store_short_d16_hi v[0:1], v4, off
	s_waitcnt lgkmcnt(0)
	v_fma_f32 v4, v25, v5, 0
	v_fmac_f32_e32 v4, v29, v6
	ds_bpermute_b32 v6, v49, v61
	ds_bpermute_b32 v7, v49, v61 offset:4
	v_mul_f32_e32 v4, v62, v4
	v_bfe_u32 v5, v4, 16, 1
	v_add3_u32 v4, v4, v5, s5
	global_store_short_d16_hi v[0:1], v4, off offset:2048
	s_waitcnt lgkmcnt(1)
	v_fma_f32 v4, v25, v6, 0
	s_waitcnt lgkmcnt(0)
	v_fmac_f32_e32 v4, v29, v7
	v_fmac_f32_e32 v4, v35, v9
	v_mul_f32_e32 v4, v58, v4
	v_bfe_u32 v5, v4, 16, 1
	v_add3_u32 v9, v4, v5, s5
	v_add_co_u32_e32 v4, vcc, s52, v0
	s_nop 1
	v_addc_co_u32_e32 v5, vcc, 0, v1, vcc
	v_add_co_u32_e32 v6, vcc, s41, v0
	s_nop 1
	v_addc_co_u32_e32 v7, vcc, 0, v1, vcc
	global_store_short_d16_hi v[6:7], v9, off offset:-4096
	v_fma_f32 v9, v25, v10, 0
	v_fmac_f32_e32 v9, v29, v11
	v_fmac_f32_e32 v9, v35, v12
	v_fmac_f32_e32 v9, v43, v13
	v_mul_f32_e32 v9, v54, v9
	v_bfe_u32 v10, v9, 16, 1
	v_add3_u32 v9, v9, v10, s5
	global_store_short_d16_hi v[4:5], v9, off offset:2048
	ds_bpermute_b32 v4, v49, v64
	ds_bpermute_b32 v5, v49, v64 offset:4
	ds_bpermute_b32 v9, v49, v64 offset:8
	ds_bpermute_b32 v10, v49, v64 offset:12
	ds_bpermute_b32 v11, v49, v64 offset:16
	s_waitcnt lgkmcnt(4)
	v_fma_f32 v4, v25, v4, 0
	s_waitcnt lgkmcnt(3)
	v_fmac_f32_e32 v4, v29, v5
	s_waitcnt lgkmcnt(2)
	v_fmac_f32_e32 v4, v35, v9
	s_waitcnt lgkmcnt(1)
	v_fmac_f32_e32 v4, v43, v10
	ds_bpermute_b32 v5, v49, v65
	s_waitcnt lgkmcnt(1)
	v_fmac_f32_e32 v4, v47, v11
	v_mul_f32_e32 v4, v50, v4
	v_bfe_u32 v9, v4, 16, 1
	v_add3_u32 v4, v4, v9, s5
	global_store_short_d16_hi v[6:7], v4, off
	s_waitcnt lgkmcnt(0)
	v_fma_f32 v4, v25, v5, 0
	ds_bpermute_b32 v5, v49, v65 offset:4
	ds_bpermute_b32 v9, v49, v65 offset:8
	ds_bpermute_b32 v10, v49, v65 offset:12
	ds_bpermute_b32 v11, v49, v65 offset:16
	ds_bpermute_b32 v12, v49, v65 offset:20
	s_waitcnt lgkmcnt(4)
	v_fmac_f32_e32 v4, v29, v5
	s_waitcnt lgkmcnt(3)
	v_fmac_f32_e32 v4, v35, v9
	s_waitcnt lgkmcnt(2)
	v_fmac_f32_e32 v4, v43, v10
	s_waitcnt lgkmcnt(1)
	v_fmac_f32_e32 v4, v47, v11
	ds_bpermute_b32 v5, v49, v66
	s_waitcnt lgkmcnt(1)
	v_fmac_f32_e32 v4, v46, v12
	v_mul_f32_e32 v4, v48, v4
	ds_bpermute_b32 v9, v49, v66 offset:4
	v_bfe_u32 v10, v4, 16, 1
	v_add3_u32 v4, v4, v10, s5
	global_store_short_d16_hi v[6:7], v4, off offset:2048
	s_waitcnt lgkmcnt(1)
	v_fma_f32 v4, v25, v5, 0
	ds_bpermute_b32 v5, v49, v66 offset:8
	ds_bpermute_b32 v6, v49, v66 offset:12
	ds_bpermute_b32 v7, v49, v66 offset:16
	s_waitcnt lgkmcnt(3)
	v_fmac_f32_e32 v4, v29, v9
	ds_bpermute_b32 v9, v49, v66 offset:20
	ds_bpermute_b32 v10, v49, v66 offset:24
	s_waitcnt lgkmcnt(4)
	v_fmac_f32_e32 v4, v35, v5
	s_waitcnt lgkmcnt(3)
	v_fmac_f32_e32 v4, v43, v6
	s_waitcnt lgkmcnt(2)
	v_fmac_f32_e32 v4, v47, v7
	s_waitcnt lgkmcnt(1)
	v_fmac_f32_e32 v4, v46, v9
	s_waitcnt lgkmcnt(0)
	v_fmac_f32_e32 v4, v42, v10
	v_mul_f32_e32 v4, v44, v4
	v_bfe_u32 v5, v4, 16, 1
	ds_bpermute_b32 v10, v49, v67
	v_add3_u32 v9, v4, v5, s5
	v_add_co_u32_e32 v4, vcc, s40, v0
	ds_bpermute_b32 v11, v49, v67 offset:4
	s_nop 0
	v_addc_co_u32_e32 v5, vcc, 0, v1, vcc
	ds_bpermute_b32 v12, v49, v67 offset:8
	v_add_co_u32_e32 v6, vcc, s19, v0
	ds_bpermute_b32 v13, v49, v67 offset:24
	s_nop 0
	v_addc_co_u32_e32 v7, vcc, 0, v1, vcc
	global_store_short_d16_hi v[6:7], v9, off offset:-4096
	s_waitcnt lgkmcnt(3)
	v_fma_f32 v9, v25, v10, 0
	ds_bpermute_b32 v10, v49, v67 offset:12
	s_waitcnt lgkmcnt(3)
	v_fmac_f32_e32 v9, v29, v11
	ds_bpermute_b32 v11, v49, v67 offset:16
	s_waitcnt lgkmcnt(3)
	v_fmac_f32_e32 v9, v35, v12
	ds_bpermute_b32 v12, v49, v67 offset:20
	s_waitcnt lgkmcnt(2)
	v_fmac_f32_e32 v9, v43, v10
	s_waitcnt lgkmcnt(1)
	v_fmac_f32_e32 v9, v47, v11
	ds_bpermute_b32 v11, v49, v68 offset:4
	s_waitcnt lgkmcnt(1)
	v_fmac_f32_e32 v9, v46, v12
	v_fmac_f32_e32 v9, v42, v13
	v_fmac_f32_e32 v9, v38, v14
	v_mul_f32_e32 v9, v40, v9
	v_bfe_u32 v10, v9, 16, 1
	v_add3_u32 v9, v9, v10, s5
	ds_bpermute_b32 v10, v49, v68
	ds_bpermute_b32 v12, v49, v68 offset:8
	ds_bpermute_b32 v13, v49, v68 offset:12
	global_store_short_d16_hi v[4:5], v9, off offset:2048
	ds_bpermute_b32 v5, v49, v68 offset:16
	s_waitcnt lgkmcnt(3)
	v_fma_f32 v4, v25, v10, 0
	ds_bpermute_b32 v9, v49, v68 offset:20
	v_fmac_f32_e32 v4, v29, v11
	ds_bpermute_b32 v10, v49, v68 offset:24
	s_waitcnt lgkmcnt(4)
	v_fmac_f32_e32 v4, v35, v12
	ds_bpermute_b32 v11, v49, v68 offset:28
	s_waitcnt lgkmcnt(4)
	v_fmac_f32_e32 v4, v43, v13
	ds_bpermute_b32 v12, v49, v68 offset:32
	s_waitcnt lgkmcnt(4)
	v_fmac_f32_e32 v4, v47, v5
	s_waitcnt lgkmcnt(3)
	v_fmac_f32_e32 v4, v46, v9
	s_waitcnt lgkmcnt(2)
	v_fmac_f32_e32 v4, v42, v10
	s_waitcnt lgkmcnt(1)
	v_fmac_f32_e32 v4, v38, v11
	s_waitcnt lgkmcnt(0)
	v_fmac_f32_e32 v4, v34, v12
	v_mul_f32_e32 v4, v36, v4
	v_bfe_u32 v5, v4, 16, 1
	v_add3_u32 v4, v4, v5, s5
	global_store_short_d16_hi v[6:7], v4, off
	ds_bpermute_b32 v4, v49, v69
	ds_bpermute_b32 v5, v49, v69 offset:4
	ds_bpermute_b32 v9, v49, v69 offset:8
	ds_bpermute_b32 v10, v49, v69 offset:12
	ds_bpermute_b32 v11, v49, v69 offset:16
	s_waitcnt lgkmcnt(4)
	v_fma_f32 v4, v25, v4, 0
	s_waitcnt lgkmcnt(3)
	v_fmac_f32_e32 v4, v29, v5
	ds_bpermute_b32 v5, v49, v69 offset:20
	s_waitcnt lgkmcnt(3)
	v_fmac_f32_e32 v4, v35, v9
	ds_bpermute_b32 v9, v49, v69 offset:24
	s_waitcnt lgkmcnt(3)
	v_fmac_f32_e32 v4, v43, v10
	ds_bpermute_b32 v10, v49, v69 offset:28
	s_waitcnt lgkmcnt(3)
	v_fmac_f32_e32 v4, v47, v11
	ds_bpermute_b32 v11, v49, v69 offset:32
	ds_bpermute_b32 v12, v49, v69 offset:36
	s_waitcnt lgkmcnt(4)
	v_fmac_f32_e32 v4, v46, v5
	s_waitcnt lgkmcnt(3)
	v_fmac_f32_e32 v4, v42, v9
	s_waitcnt lgkmcnt(2)
	v_fmac_f32_e32 v4, v38, v10
	s_waitcnt lgkmcnt(1)
	v_fmac_f32_e32 v4, v34, v11
	ds_bpermute_b32 v5, v49, v70
	s_waitcnt lgkmcnt(1)
	v_fmac_f32_e32 v4, v28, v12
	v_mul_f32_e32 v4, v30, v4
	v_bfe_u32 v9, v4, 16, 1
	v_add3_u32 v4, v4, v9, s5
	global_store_short_d16_hi v[6:7], v4, off offset:2048
	s_waitcnt lgkmcnt(0)
	v_fma_f32 v4, v25, v5, 0
	ds_bpermute_b32 v5, v49, v70 offset:4
	ds_bpermute_b32 v6, v49, v70 offset:8
	ds_bpermute_b32 v7, v49, v70 offset:12
	ds_bpermute_b32 v9, v49, v70 offset:16
	ds_bpermute_b32 v10, v49, v70 offset:20
	s_waitcnt lgkmcnt(4)
	v_fmac_f32_e32 v4, v29, v5
	ds_bpermute_b32 v5, v49, v70 offset:24
	s_waitcnt lgkmcnt(4)
	v_fmac_f32_e32 v4, v35, v6
	ds_bpermute_b32 v6, v49, v70 offset:28
	s_waitcnt lgkmcnt(4)
	v_fmac_f32_e32 v4, v43, v7
	ds_bpermute_b32 v7, v49, v70 offset:32
	s_waitcnt lgkmcnt(4)
	v_fmac_f32_e32 v4, v47, v9
	ds_bpermute_b32 v9, v49, v70 offset:36
	s_waitcnt lgkmcnt(4)
	v_fmac_f32_e32 v4, v46, v10
	ds_bpermute_b32 v10, v49, v70 offset:40
	s_waitcnt lgkmcnt(4)
	v_fmac_f32_e32 v4, v42, v5
	s_waitcnt lgkmcnt(3)
	v_fmac_f32_e32 v4, v38, v6
	s_waitcnt lgkmcnt(2)
	v_fmac_f32_e32 v4, v34, v7
	s_waitcnt lgkmcnt(1)
	v_fmac_f32_e32 v4, v28, v9
	s_waitcnt lgkmcnt(0)
	v_fmac_f32_e32 v4, v24, v10
	v_mul_f32_e32 v4, v26, v4
	v_bfe_u32 v5, v4, 16, 1
	ds_bpermute_b32 v10, v49, v71
	v_add3_u32 v9, v4, v5, s5
	v_add_co_u32_e32 v4, vcc, s18, v0
	ds_bpermute_b32 v11, v49, v71 offset:4
	s_nop 0
	v_addc_co_u32_e32 v5, vcc, 0, v1, vcc
	v_add_co_u32_e32 v6, vcc, s15, v0
	ds_bpermute_b32 v12, v49, v71 offset:16
	s_nop 0
	v_addc_co_u32_e32 v7, vcc, 0, v1, vcc
	global_store_short_d16_hi v[6:7], v9, off offset:-4096
	s_waitcnt lgkmcnt(2)
	v_fma_f32 v9, v25, v10, 0
	ds_bpermute_b32 v10, v49, v71 offset:8
	s_waitcnt lgkmcnt(2)
	v_fmac_f32_e32 v9, v29, v11
	ds_bpermute_b32 v11, v49, v71 offset:12
	ds_bpermute_b32 v13, v49, v71 offset:20
	ds_bpermute_b32 v14, v49, v71 offset:24
	s_waitcnt lgkmcnt(3)
	v_fmac_f32_e32 v9, v35, v10
	ds_bpermute_b32 v10, v49, v71 offset:28
	s_waitcnt lgkmcnt(3)
	v_fmac_f32_e32 v9, v43, v11
	ds_bpermute_b32 v11, v49, v71 offset:32
	v_fmac_f32_e32 v9, v47, v12
	ds_bpermute_b32 v12, v49, v71 offset:36
	s_waitcnt lgkmcnt(4)
	v_fmac_f32_e32 v9, v46, v13
	ds_bpermute_b32 v13, v49, v71 offset:40
	s_waitcnt lgkmcnt(4)
	v_fmac_f32_e32 v9, v42, v14
	ds_bpermute_b32 v14, v49, v71 offset:44
	s_waitcnt lgkmcnt(4)
	v_fmac_f32_e32 v9, v38, v10
	s_waitcnt lgkmcnt(3)
	v_fmac_f32_e32 v9, v34, v11
	s_waitcnt lgkmcnt(2)
	v_fmac_f32_e32 v9, v28, v12
	s_waitcnt lgkmcnt(1)
	v_fmac_f32_e32 v9, v24, v13
	s_waitcnt lgkmcnt(0)
	v_fmac_f32_e32 v9, v20, v14
	v_mul_f32_e32 v9, v22, v9
	ds_bpermute_b32 v11, v49, v72
	v_bfe_u32 v10, v9, 16, 1
	ds_bpermute_b32 v12, v49, v72 offset:4
	ds_bpermute_b32 v13, v49, v72 offset:8
	v_add3_u32 v9, v9, v10, s5
	global_store_short_d16_hi v[4:5], v9, off offset:2048
	ds_bpermute_b32 v5, v49, v72 offset:12
	ds_bpermute_b32 v9, v49, v72 offset:16
	s_waitcnt lgkmcnt(4)
	v_fma_f32 v4, v25, v11, 0
	ds_bpermute_b32 v10, v49, v72 offset:20
	s_waitcnt lgkmcnt(4)
	v_fmac_f32_e32 v4, v29, v12
	ds_bpermute_b32 v11, v49, v72 offset:24
	s_waitcnt lgkmcnt(4)
	v_fmac_f32_e32 v4, v35, v13
	ds_bpermute_b32 v12, v49, v72 offset:28
	s_waitcnt lgkmcnt(4)
	v_fmac_f32_e32 v4, v43, v5
	ds_bpermute_b32 v5, v49, v72 offset:32
	s_waitcnt lgkmcnt(4)
	v_fmac_f32_e32 v4, v47, v9
	ds_bpermute_b32 v9, v49, v72 offset:36
	s_waitcnt lgkmcnt(4)
	v_fmac_f32_e32 v4, v46, v10
	ds_bpermute_b32 v10, v49, v72 offset:40
	s_waitcnt lgkmcnt(4)
	v_fmac_f32_e32 v4, v42, v11
	ds_bpermute_b32 v11, v49, v72 offset:44
	s_waitcnt lgkmcnt(4)
	v_fmac_f32_e32 v4, v38, v12
	ds_bpermute_b32 v12, v49, v72 offset:48
	s_waitcnt lgkmcnt(4)
	v_fmac_f32_e32 v4, v34, v5
	s_waitcnt lgkmcnt(3)
	v_fmac_f32_e32 v4, v28, v9
	s_waitcnt lgkmcnt(2)
	v_fmac_f32_e32 v4, v24, v10
	s_waitcnt lgkmcnt(1)
	v_fmac_f32_e32 v4, v20, v11
	s_waitcnt lgkmcnt(0)
	v_fmac_f32_e32 v4, v18, v12
	v_mul_f32_e32 v4, v23, v4
	v_bfe_u32 v5, v4, 16, 1
	v_add3_u32 v4, v4, v5, s5
	ds_bpermute_b32 v5, v49, v8
	ds_bpermute_b32 v9, v49, v8 offset:4
	ds_bpermute_b32 v10, v49, v8 offset:8
	ds_bpermute_b32 v11, v49, v8 offset:12
	global_store_short_d16_hi v[6:7], v4, off
	s_waitcnt lgkmcnt(3)
	v_fma_f32 v4, v25, v5, 0
	ds_bpermute_b32 v5, v49, v8 offset:16
	s_waitcnt lgkmcnt(3)
	v_fmac_f32_e32 v4, v29, v9
	ds_bpermute_b32 v9, v49, v8 offset:20
	s_waitcnt lgkmcnt(3)
	v_fmac_f32_e32 v4, v35, v10
	ds_bpermute_b32 v10, v49, v8 offset:24
	s_waitcnt lgkmcnt(3)
	v_fmac_f32_e32 v4, v43, v11
	ds_bpermute_b32 v11, v49, v8 offset:28
	ds_bpermute_b32 v12, v49, v8 offset:32
	s_waitcnt lgkmcnt(4)
	v_fmac_f32_e32 v4, v47, v5
	ds_bpermute_b32 v5, v49, v8 offset:36
	s_waitcnt lgkmcnt(4)
	v_fmac_f32_e32 v4, v46, v9
	ds_bpermute_b32 v9, v49, v8 offset:40
	s_waitcnt lgkmcnt(4)
	v_fmac_f32_e32 v4, v42, v10
	ds_bpermute_b32 v10, v49, v8 offset:44
	s_waitcnt lgkmcnt(4)
	v_fmac_f32_e32 v4, v38, v11
	ds_bpermute_b32 v11, v49, v8 offset:48
	s_waitcnt lgkmcnt(4)
	v_fmac_f32_e32 v4, v34, v12
	ds_bpermute_b32 v8, v49, v8 offset:52
	s_waitcnt lgkmcnt(4)
	v_fmac_f32_e32 v4, v28, v5
	s_waitcnt lgkmcnt(3)
	v_fmac_f32_e32 v4, v24, v9
	s_waitcnt lgkmcnt(2)
	v_fmac_f32_e32 v4, v20, v10
	s_waitcnt lgkmcnt(1)
	v_fmac_f32_e32 v4, v18, v11
	s_waitcnt lgkmcnt(0)
	v_fmac_f32_e32 v4, v19, v8
	v_mul_f32_e32 v4, v31, v4
	v_bfe_u32 v5, v4, 16, 1
	v_add3_u32 v4, v4, v5, s5
	global_store_short_d16_hi v[6:7], v4, off offset:2048
	ds_bpermute_b32 v4, v49, v3
	ds_bpermute_b32 v5, v49, v3 offset:4
	ds_bpermute_b32 v6, v49, v3 offset:8
	ds_bpermute_b32 v7, v49, v3 offset:12
	ds_bpermute_b32 v8, v49, v3 offset:16
	s_waitcnt lgkmcnt(4)
	v_fma_f32 v4, v25, v4, 0
	s_waitcnt lgkmcnt(3)
	v_fmac_f32_e32 v4, v29, v5
	ds_bpermute_b32 v5, v49, v3 offset:20
	s_waitcnt lgkmcnt(3)
	v_fmac_f32_e32 v4, v35, v6
	ds_bpermute_b32 v6, v49, v3 offset:24
	s_waitcnt lgkmcnt(3)
	v_fmac_f32_e32 v4, v43, v7
	ds_bpermute_b32 v7, v49, v3 offset:28
	s_waitcnt lgkmcnt(3)
	v_fmac_f32_e32 v4, v47, v8
	ds_bpermute_b32 v8, v49, v3 offset:32
	ds_bpermute_b32 v9, v49, v3 offset:36
	s_waitcnt lgkmcnt(4)
	v_fmac_f32_e32 v4, v46, v5
	ds_bpermute_b32 v5, v49, v3 offset:40
	s_waitcnt lgkmcnt(4)
	v_fmac_f32_e32 v4, v42, v6
	ds_bpermute_b32 v6, v49, v3 offset:44
	s_waitcnt lgkmcnt(4)
	v_fmac_f32_e32 v4, v38, v7
	ds_bpermute_b32 v7, v49, v3 offset:48
	s_waitcnt lgkmcnt(4)
	v_fmac_f32_e32 v4, v34, v8
	ds_bpermute_b32 v8, v49, v3 offset:52
	s_waitcnt lgkmcnt(4)
	v_fmac_f32_e32 v4, v28, v9
	ds_bpermute_b32 v3, v49, v3 offset:56
	s_waitcnt lgkmcnt(4)
	v_fmac_f32_e32 v4, v24, v5
	s_waitcnt lgkmcnt(3)
	v_fmac_f32_e32 v4, v20, v6
	s_waitcnt lgkmcnt(2)
	v_fmac_f32_e32 v4, v18, v7
	s_waitcnt lgkmcnt(1)
	v_fmac_f32_e32 v4, v19, v8
	s_waitcnt lgkmcnt(0)
	v_fmac_f32_e32 v4, v27, v3
	v_mul_f32_e32 v3, v37, v4
	v_bfe_u32 v4, v3, 16, 1
	v_add3_u32 v3, v3, v4, s5
	ds_bpermute_b32 v4, v49, v2
	v_add_co_u32_e32 v0, vcc, s14, v0
	ds_bpermute_b32 v5, v49, v2 offset:8
	s_nop 0
	v_addc_co_u32_e32 v1, vcc, 0, v1, vcc
	global_store_short_d16_hi v[0:1], v3, off
	s_waitcnt lgkmcnt(1)
	v_fma_f32 v3, v25, v4, 0
	ds_bpermute_b32 v4, v49, v2 offset:4
	ds_bpermute_b32 v6, v49, v2 offset:12
	ds_bpermute_b32 v7, v49, v2 offset:16
	ds_bpermute_b32 v8, v49, v2 offset:20
	s_waitcnt lgkmcnt(3)
	v_fmac_f32_e32 v3, v29, v4
	ds_bpermute_b32 v4, v49, v2 offset:24
	v_fmac_f32_e32 v3, v35, v5
	ds_bpermute_b32 v5, v49, v2 offset:28
	s_waitcnt lgkmcnt(4)
	v_fmac_f32_e32 v3, v43, v6
	ds_bpermute_b32 v6, v49, v2 offset:32
	s_waitcnt lgkmcnt(4)
	v_fmac_f32_e32 v3, v47, v7
	ds_bpermute_b32 v7, v49, v2 offset:36
	s_waitcnt lgkmcnt(4)
	v_fmac_f32_e32 v3, v46, v8
	ds_bpermute_b32 v8, v49, v2 offset:40
	s_waitcnt lgkmcnt(4)
	v_fmac_f32_e32 v3, v42, v4
	ds_bpermute_b32 v4, v49, v2 offset:44
	s_waitcnt lgkmcnt(4)
	v_fmac_f32_e32 v3, v38, v5
	ds_bpermute_b32 v5, v49, v2 offset:48
	s_waitcnt lgkmcnt(4)
	v_fmac_f32_e32 v3, v34, v6
	ds_bpermute_b32 v6, v49, v2 offset:52
	s_waitcnt lgkmcnt(4)
	v_fmac_f32_e32 v3, v28, v7
	ds_bpermute_b32 v7, v49, v2 offset:56
	s_waitcnt lgkmcnt(4)
	v_fmac_f32_e32 v3, v24, v8
	ds_bpermute_b32 v2, v49, v2 offset:60
	s_waitcnt lgkmcnt(4)
	v_fmac_f32_e32 v3, v20, v4
	s_waitcnt lgkmcnt(3)
	v_fmac_f32_e32 v3, v18, v5
	s_waitcnt lgkmcnt(2)
	v_fmac_f32_e32 v3, v19, v6
	s_waitcnt lgkmcnt(1)
	v_fmac_f32_e32 v3, v27, v7
	s_waitcnt lgkmcnt(0)
	v_fmac_f32_e32 v3, v41, v2
	v_mul_f32_e32 v2, v45, v3
	v_bfe_u32 v3, v2, 16, 1
	v_add3_u32 v2, v2, v3, s5
	global_store_short_d16_hi v[0:1], v2, off offset:2048

.Linvw1_skip2:
	s_barrier
.LBB0_579:
	s_cmp_lt_i32 s30, 4
	s_cselect_b64 s[4:5], -1, 0
	s_add_u32 s2, s28, 0x4e0000
	s_addc_u32 s3, s29, 0
	s_and_b64 s[0:1], s[4:5], s[0:1]
	v_writelane_b32 v254, s2, 21
	s_andn2_b64 vcc, exec, s[0:1]
	s_nop 0
	v_writelane_b32 v254, s3, 22
	s_cbranch_vccnz .LBB0_672
	v_mbcnt_lo_u32_b32 v24, -1, 0
	v_mbcnt_hi_u32_b32 v24, -1, v24
	s_cmp_gt_i32 s16, 63
	v_add_u32_e32 v183, s33, v24
	s_cbranch_scc1 .LBB0_587
	v_ashrrev_i32_e32 v2, 4, v24
	v_lshlrev_b32_e32 v0, 3, v2
	s_add_i32 s0, 0, 0x20540
	v_lshlrev_b32_e32 v2, 2, v2
	v_and_b32_e32 v20, 15, v24
	v_lshl_add_u32 v25, v24, 4, s0
	v_readlane_b32 s0, v254, 21
	s_waitcnt lgkmcnt(0)
	v_ashrrev_i32_e32 v3, 31, v2
	s_lshl_b32 s2, s70, 7
	v_lshlrev_b32_e32 v4, 2, v20
	v_mov_b32_e32 v5, 0
	v_readlane_b32 s1, v254, 22
	v_lshlrev_b64 v[8:9], 12, v[2:3]
	v_or_b32_e32 v10, 1, v2
	v_or_b32_e32 v12, 2, v2
	v_or_b32_e32 v2, 3, v2
	s_ashr_i32 s3, s2, 31
	v_ashrrev_i32_e32 v1, 31, v0
	v_lshl_add_u64 v[6:7], s[0:1], 0, v[4:5]
	v_ashrrev_i32_e32 v3, 31, v2
	s_lshl_b32 s6, s70, 10
	v_lshlrev_b32_e32 v4, 11, v20
	s_lshl_b64 s[2:3], s[2:3], 1
	v_lshlrev_b64 v[14:15], 12, v[2:3]
	v_lshl_add_u64 v[2:3], v[4:5], 0, s[2:3]
	v_lshlrev_b64 v[0:1], 1, v[0:1]
	s_add_u32 s2, s28, s2
	v_ashrrev_i32_e32 v11, 31, v10
	v_ashrrev_i32_e32 v13, 31, v12
	v_lshl_add_u64 v[2:3], v[2:3], 0, v[0:1]
	s_addc_u32 s3, s29, s3
	v_lshlrev_b64 v[10:11], 12, v[10:11]
	v_lshlrev_b64 v[12:13], 12, v[12:13]
	v_cmp_gt_i32_e64 s[0:1], 64, v183
	v_lshl_add_u64 v[16:17], s[28:29], 0, v[2:3]
	v_lshl_add_u64 v[18:19], s[2:3], 0, v[0:1]
	v_lshl_or_b32 v20, s16, 4, v20
	v_add_u32_e32 v4, s6, v25
	s_mov_b32 s8, s16
	s_branch .LBB0_583

.Linvw1_skip3:
	s_barrier
.LBB0_722:
	s_cmp_lt_i32 s30, 5
	s_cselect_b64 s[4:5], -1, 0
	s_and_b64 s[0:1], s[4:5], s[0:1]
	s_andn2_b64 vcc, exec, s[0:1]
	s_cbranch_vccnz .LBB0_761
	v_mbcnt_lo_u32_b32 v8, -1, 0
	v_mbcnt_hi_u32_b32 v8, -1, v8
	s_cmpk_lt_i32 s16, 0x100
	v_add_u32_e32 v0, s33, v8
	s_cselect_b64 s[6:7], -1, 0
	s_cmpk_gt_i32 s16, 0xff
	s_waitcnt lgkmcnt(0)
	v_readfirstlane_b32 s40, v0
	s_cbranch_scc1 .LBB0_726
	s_ashr_i32 s0, s16, 31
	s_lshr_b32 s0, s0, 29
	s_add_i32 s2, s16, s0
	s_and_b32 s0, s2, -8
	s_sub_i32 s3, s16, s0
	s_cmp_gt_i32 s3, -1
	s_cbranch_scc0 .LBB0_727
	s_lshl_b32 s8, s3, 5
	s_cbranch_execz .LBB0_728
	s_branch .LBB0_729

.Linvw1_skip5:
	s_barrier
.LBB0_942:
	s_cmp_lt_i32 s30, 7
	s_cselect_b64 s[8:9], -1, 0
	s_and_b64 s[0:1], s[8:9], s[0:1]
	s_andn2_b64 vcc, exec, s[0:1]
	v_readlane_b32 s69, v254, 13
	s_cbranch_vccnz .LBB0_1002
	s_mul_i32 s0, s17, 3
	s_ashr_i32 s1, s0, 31
	s_lshr_b32 s1, s1, 30
	s_add_i32 s0, s0, s1
	s_ashr_i32 s0, s0, 2
	s_waitcnt vmcnt(0)
	v_mbcnt_lo_u32_b32 v38, -1, 0
	v_mbcnt_hi_u32_b32 v38, -1, v38
	s_cmp_lt_i32 s16, s0
	v_add_u32_e32 v39, s33, v38
	s_cbranch_scc1 .LBB0_960
	s_sub_i32 s5, s16, s0
	s_lshl_b32 s1, s5, 3
	s_sub_i32 s4, s17, s0
	s_lshl_b32 s0, s69, 14
	s_add_i32 s6, s1, s69
	s_lshl_b32 s7, s4, 3
	s_add_i32 s10, s0, 0
	v_readlane_b32 s40, v254, 24
	s_cmpk_gt_u32 s6, 0x7ff
	v_ashrrev_i32_e32 v40, 3, v38
	v_lshlrev_b32_e32 v42, 4, v38
	v_lshlrev_b32_e32 v41, 3, v38
	v_readlane_b32 s41, v254, 25
	s_cbranch_scc1 .LBB0_949
	v_and_b32_e32 v0, 0x70, v42
	v_mov_b32_e32 v1, 0
	v_lshl_add_u64 v[32:33], s[38:39], 0, v[0:1]
	v_add_u32_e32 v2, s10, v0
	v_and_b32_e32 v0, 56, v41
	s_movk_i32 s2, 0x84
	v_mul_u32_u24_e32 v4, 0x84, v0
	v_lshlrev_b32_e32 v0, 1, v0
	s_cmp_lg_u64 s[36:37], 0
	v_mul_lo_u32 v3, v40, s2
	v_lshl_add_u64 v[0:1], s[28:29], 0, v[0:1]
	s_mov_b64 s[2:3], 0x3900000
	s_cselect_b64 s[0:1], -1, 0
	v_lshl_add_u64 v[34:35], v[0:1], 0, s[2:3]
	v_lshlrev_b32_e32 v0, 2, v40
	v_add3_u32 v43, s10, v4, v0
	v_cndmask_b32_e64 v0, 0, 1, s[0:1]
	s_lshl_b32 s11, s6, 5
	s_lshl_b32 s12, s7, 5
	s_mov_b32 s13, 0x20000
	s_mov_b32 s14, 0x40000
	s_mov_b32 s15, 0x60000
	s_mov_b32 s18, 0x80000
	v_cmp_ne_u32_e64 s[0:1], 1, v0
	v_add_u32_e32 v44, v2, v3
	s_mov_b32 s19, s6
	s_branch .LBB0_947

.Linvw1_skip6:
	s_barrier
.LBB0_1052:
	s_cmp_lt_i32 s30, 8
	s_cselect_b64 s[10:11], -1, 0
	s_add_u32 s8, s28, 0x548000
	s_addc_u32 s9, s29, 0
	s_and_b64 s[0:1], s[10:11], s[0:1]
	s_andn2_b64 vcc, exec, s[0:1]
	s_cbranch_vccnz .LBB0_1100
	s_waitcnt vmcnt(0)
	v_mbcnt_lo_u32_b32 v36, -1, 0
	v_mbcnt_hi_u32_b32 v36, -1, v36
	s_cmpk_lt_i32 s16, 0x100
	v_add_u32_e32 v34, s33, v36
	s_cselect_b64 s[4:5], -1, 0
	s_cmpk_gt_i32 s16, 0xff
	v_readfirstlane_b32 s40, v34
	s_cbranch_scc1 .LBB0_1056
	s_ashr_i32 s0, s16, 31
	s_lshr_b32 s0, s0, 29
	s_add_i32 s2, s16, s0
	s_and_b32 s0, s2, -8
	s_sub_i32 s3, s16, s0
	s_cmp_gt_i32 s3, -1
	s_cbranch_scc0 .LBB0_1057
	s_lshl_b32 s6, s3, 5
	s_cbranch_execz .LBB0_1058
	s_branch .LBB0_1059

.LBB0_1117:
	v_readlane_b32 s4, v254, 5
	s_lshl_b32 s4, s4, 8
	v_readlane_b32 s6, v254, 3
	v_readlane_b32 s7, v254, 4
	s_add_u32 s4, s6, s4
	s_addc_u32 s5, s7, 0
	v_mov_b32_e32 v1, 0x1000
	v_mov_b32_e32 v3, 1
	global_atomic_add v3, v1, v3, s[4:5] offset:1024 sc0
	v_cvt_f32_u32_e32 v1, v2
	v_sub_u32_e32 v4, 0, v2
	v_rcp_iflag_f32_e32 v1, v1
	s_nop 0
	v_mul_f32_e32 v1, 0x4f7ffffe, v1
	v_cvt_u32_f32_e32 v1, v1
	v_mul_lo_u32 v4, v4, v1
	v_mul_hi_u32 v4, v1, v4
	v_add_u32_e32 v1, v1, v4
	s_waitcnt vmcnt(0)
	v_mul_hi_u32 v1, v3, v1
	v_mul_lo_u32 v4, v1, v2
	v_sub_u32_e32 v4, v3, v4
	v_add_u32_e32 v5, 1, v1
	v_cmp_ge_u32_e32 vcc, v4, v2
	v_add_u32_e32 v3, 1, v3
	s_nop 0
	v_cndmask_b32_e32 v1, v1, v5, vcc
	v_sub_u32_e32 v5, v4, v2
	v_cndmask_b32_e32 v4, v4, v5, vcc
	v_add_u32_e32 v5, 1, v1
	v_cmp_ge_u32_e32 vcc, v4, v2
	s_nop 1
	v_cndmask_b32_e32 v1, v1, v5, vcc
	v_mul_lo_u32 v4, v2, v1
	v_add_u32_e32 v2, v4, v2
	v_cmp_ne_u32_e32 vcc, v3, v2
	s_and_saveexec_b64 s[6:7], vcc
	s_xor_b64 s[6:7], exec, s[6:7]
	s_cbranch_execz .LBB0_1131
	s_waitcnt lgkmcnt(0)
	s_add_u32 s14, s28, 0x7500
	s_addc_u32 s15, s29, 0
	v_mov_b32_e32 v0, 0
	global_load_dword v0, v0, s[14:15] sc1
	s_waitcnt vmcnt(0)
	v_cmp_eq_u32_e32 vcc, v0, v1
	s_and_saveexec_b64 s[10:11], vcc
	s_cbranch_execz .LBB0_1130
	s_add_u32 s12, s28, 0x4200
	s_addc_u32 s13, s29, 0
	s_mov_b32 s40, 1
	s_mov_b64 s[18:19], 0
	v_mov_b32_e32 v0, 0
	s_branch .LBB0_1121

.Linvw1_skip7:
	s_barrier
.LBB0_1150:
	s_cmp_lt_i32 s30, 9
	s_cselect_b64 s[4:5], -1, 0
	s_and_b64 s[0:1], s[4:5], s[0:1]
	s_andn2_b64 vcc, exec, s[0:1]
	s_cbranch_vccnz .LBB0_1192
	s_add_i32 s0, s17, -1
	s_cmp_lg_u32 s16, s0
	v_mbcnt_lo_u32_b32 v26, -1, 0
	v_mbcnt_hi_u32_b32 v26, -1, v26
	s_cbranch_scc1 .LBB0_1157
	s_lshl_b32 s0, s69, 1
	s_mov_b32 s1, 0
	s_lshl_b64 s[2:3], s[0:1], 12
	s_add_u32 s6, s96, s2
	v_readlane_b32 s7, v254, 23
	v_lshlrev_b32_e32 v0, 2, v26
	s_addc_u32 s7, s7, s3
	s_add_u32 s10, s8, s2
	s_waitcnt lgkmcnt(0)
	v_ashrrev_i32_e32 v1, 31, v0
	s_addc_u32 s11, s9, s3
	v_lshlrev_b64 v[0:1], 2, v[0:1]
	v_lshl_add_u64 v[24:25], s[10:11], 0, v[0:1]
	v_lshl_add_u64 v[2:3], s[6:7], 0, v[0:1]
	global_load_dwordx4 v[4:7], v[24:25], off
	global_load_dwordx4 v[8:11], v[2:3], off
	global_load_dwordx4 v[12:15], v[2:3], off offset:1024
	global_load_dwordx4 v[16:19], v[24:25], off offset:1024
	global_load_dwordx4 v[20:23], v[24:25], off offset:2048
	global_load_dwordx4 v[28:31], v[2:3], off offset:2048
	global_load_dwordx4 v[32:35], v[2:3], off offset:3072
	global_load_dwordx4 v[36:39], v[24:25], off offset:3072
	v_mbcnt_lo_u32_b32 v2, -1, 0
	v_mbcnt_hi_u32_b32 v2, -1, v2
	v_and_b32_e32 v24, 64, v2
	v_xor_b32_e32 v3, 16, v2
	v_add_u32_e32 v24, 64, v24
	v_xor_b32_e32 v25, 32, v2
	v_cmp_lt_i32_e32 vcc, v3, v24
	v_readlane_b32 s6, v254, 9
	v_readlane_b32 s7, v254, 10
	v_cndmask_b32_e32 v3, v2, v3, vcc
	v_cmp_lt_i32_e32 vcc, v25, v24
	v_lshlrev_b32_e32 v3, 2, v3
	s_add_u32 s2, s6, s2
	v_cndmask_b32_e32 v2, v2, v25, vcc
	v_lshlrev_b32_e32 v2, 2, v2
	s_addc_u32 s3, s7, s3
	v_cmp_eq_u32_e32 vcc, 0, v26
	s_waitcnt vmcnt(0)
	v_pk_add_f32 v[10:11], v[10:11], v[6:7]
	v_pk_add_f32 v[8:9], v[8:9], v[4:5]
	v_pk_add_f32 v[14:15], v[14:15], v[18:19]
	v_pk_add_f32 v[12:13], v[12:13], v[16:17]
	v_pk_add_f32 v[18:19], v[30:31], v[22:23]
	v_pk_add_f32 v[16:17], v[28:29], v[20:21]
	v_mul_f32_e32 v4, v9, v9
	v_mul_f32_e32 v5, v11, v11
	v_mul_f32_e32 v6, v13, v13
	v_mul_f32_e32 v7, v15, v15
	v_pk_add_f32 v[22:23], v[34:35], v[38:39]
	v_pk_add_f32 v[20:21], v[32:33], v[36:37]
	v_mul_f32_e32 v24, v17, v17
	v_mul_f32_e32 v25, v19, v19
	v_fmac_f32_e32 v4, v8, v8
	v_fmac_f32_e32 v5, v10, v10
	v_fmac_f32_e32 v6, v12, v12
	v_fmac_f32_e32 v7, v14, v14
	v_mul_f32_e32 v27, v21, v21
	v_mul_f32_e32 v28, v23, v23
	v_fmac_f32_e32 v24, v16, v16
	v_fmac_f32_e32 v25, v18, v18
	v_add_f32_e32 v4, v4, v5
	v_add_f32_e32 v5, v6, v7
	v_fmac_f32_e32 v27, v20, v20
	v_fmac_f32_e32 v28, v22, v22
	v_add_f32_e32 v6, v24, v25
	v_add_f32_e32 v4, v4, v5
	v_add_f32_e32 v4, v4, v6
	v_add_f32_e32 v5, v27, v28
	v_add_f32_e32 v4, v4, v5
	v_lshl_add_u64 v[6:7], s[2:3], 0, v[0:1]
	global_store_dwordx4 v[6:7], v[8:11], off
	global_store_dwordx4 v[6:7], v[12:15], off offset:1024
	global_store_dwordx4 v[6:7], v[16:19], off offset:2048
	global_store_dwordx4 v[6:7], v[20:23], off offset:3072
	v_add_f32_dpp v4, v4, v4 quad_perm:[1,0,3,2] row_mask:0xf bank_mask:0xf bound_ctrl:1
	s_nop 1
	v_add_f32_dpp v4, v4, v4 quad_perm:[2,3,0,1] row_mask:0xf bank_mask:0xf bound_ctrl:1
	s_nop 1
	v_add_f32_dpp v4, v4, v4 row_half_mirror row_mask:0xf bank_mask:0xf bound_ctrl:1
	s_nop 1
	v_add_f32_dpp v4, v4, v4 row_mirror row_mask:0xf bank_mask:0xf bound_ctrl:1
	ds_bpermute_b32 v5, v3, v4
	s_waitcnt lgkmcnt(0)
	v_add_f32_e32 v4, v4, v5
	ds_bpermute_b32 v5, v2, v4
	s_and_saveexec_b64 s[2:3], vcc
	s_cbranch_execz .LBB0_1154
	s_lshl_b32 s6, s0, 2
	s_waitcnt lgkmcnt(0)
	v_add_f32_e32 v4, v4, v5
	v_mov_b32_e32 v5, s6
	v_readlane_b32 s6, v254, 11
	v_readlane_b32 s7, v254, 12
	s_nop 4
	global_store_dword v5, v4, s[6:7]

.Linvw1_skip8:
	s_barrier
.LBB0_1242:
	s_cmp_lt_i32 s30, 10
	s_cselect_b64 s[36:37], -1, 0
	s_and_b64 s[0:1], s[36:37], s[0:1]
	s_andn2_b64 vcc, exec, s[0:1]
	s_cbranch_vccnz .LBB0_1286
	s_add_u32 s40, s28, 0xa300000
	s_addc_u32 s41, s29, 0
	s_add_u32 s52, s28, 0x6300000
	s_addc_u32 s53, s29, 0
	s_add_u32 s38, s28, 0x578000
	s_addc_u32 s39, s29, 0
	s_add_u32 s54, s28, 0x580000
	s_addc_u32 s55, s29, 0
	s_lshl_b32 s14, s69, 9
	s_add_i32 s57, s14, 0
	s_lshl_b32 s56, s69, 4
	s_add_i32 s57, s57, 0x18800
	v_readlane_b32 s19, v254, 0
	s_cmp_lt_u32 s19, 64
	s_cselect_b64 s[44:45], -1, 0
	s_cmpk_gt_u32 s19, 0x1ff
	s_cselect_b64 s[0:1], -1, 0
	s_cmpk_gt_u32 s19, 0x1bf
	s_cselect_b64 s[2:3], -1, 0
	s_cmpk_gt_u32 s19, 0x17f
	s_cselect_b64 s[4:5], -1, 0
	s_cmpk_gt_u32 s19, 0x13f
	s_cselect_b64 s[6:7], -1, 0
	s_cmpk_gt_u32 s19, 0xff
	s_cselect_b64 s[8:9], -1, 0
	s_cmpk_gt_u32 s19, 0xbf
	s_cselect_b64 s[10:11], -1, 0
	s_cmpk_gt_u32 s19, 0x7f
	s_cselect_b64 s[12:13], -1, 0
	s_add_i32 s70, 0, 0x22000
	s_add_i32 s68, s70, s14
	s_and_b32 s15, s14, 0x7ffffc00
	s_bitset1_b32 s14, 9
	s_add_i32 s58, s56, 0
	s_lshl_b32 s59, s69, 5
	s_mov_b32 s18, s69
	s_add_i32 s69, s70, s15
	s_add_i32 s70, s70, s14
	s_bitcmp1_b32 s19, 6
	s_cselect_b64 s[60:61], -1, 0
	s_abs_i32 s77, s17
	v_cvt_f32_u32_e32 v0, s77
	s_lshl_b32 s14, s18, 8
	s_add_i32 s80, s14, 0
	s_sub_i32 s14, 0, s77
	v_rcp_iflag_f32_e32 v0, v0
	s_mov_b32 s63, 0
	s_add_i32 s80, s80, 0x21800
	s_waitcnt vmcnt(0)
	v_mov_b32_e32 v65, 0
	v_mul_f32_e32 v0, 0x4f7ffffe, v0
	v_cvt_u32_f32_e32 v0, v0
	v_mov_b32_e32 v201, 0x358637bd
	s_mov_b32 s83, 0x800000
	s_mov_b32 s84, 0x3f317217
	v_readfirstlane_b32 s15, v0
	s_mul_i32 s14, s14, s15
	s_mul_hi_u32 s14, s15, s14
	s_add_i32 s81, s15, s14
	s_lshl_b32 s14, s18, 6
	s_add_i32 s82, s14, 0
	s_mov_b32 s85, 0x7f800000
	s_mov_b64 s[64:65], 0x2000
	s_movk_i32 s86, 0x2000
	s_add_i32 s87, 0, 0x12000
	s_movk_i32 s88, 0x110
	s_add_i32 s89, 0, 0x10800
	v_mov_b32_e32 v202, 0x41b17218
	s_mov_b32 s90, 0
	s_mov_b32 s91, 0
	v_mbcnt_lo_u32_b32 v200, -1, 0
	v_mbcnt_hi_u32_b32 v200, -1, v200
	s_branch .LBB0_1246

.Linvw1_skip9:
	s_barrier
.LBB0_1336:
	s_cmp_lt_i32 s30, 11
	s_cselect_b64 s[2:3], -1, 0
	s_and_b64 s[0:1], s[2:3], s[0:1]
	s_andn2_b64 vcc, exec, s[0:1]
	s_cbranch_vccnz .LBB0_1352
	v_readlane_b32 s14, v254, 8
	s_cmpk_gt_i32 s14, 0x57f
	v_mbcnt_lo_u32_b32 v0, -1, 0
	v_mbcnt_hi_u32_b32 v0, -1, v0
	s_waitcnt vmcnt(0)
	v_mbcnt_lo_u32_b32 v42, -1, 0
	v_mbcnt_hi_u32_b32 v42, -1, v42
	s_cbranch_scc1 .LBB0_1348
	v_lshlrev_b32_e32 v0, 2, v42
	s_add_u32 s4, s46, 0x1000
	v_and_b32_e32 v32, 28, v0
	s_addc_u32 s5, s47, 0
	s_lshl_b32 s0, s69, 14
	s_waitcnt lgkmcnt(0)
	v_mov_b32_e32 v1, 0
	v_lshlrev_b32_e32 v0, 2, v32
	s_add_i32 s8, s0, 0
	v_lshl_add_u64 v[2:3], s[48:49], 0, v[0:1]
	s_mov_b64 s[6:7], 0xb00000
	v_lshl_add_u64 v[36:37], v[2:3], 0, s[6:7]
	v_add_u32_e32 v2, s8, v0
	v_lshlrev_b32_e32 v0, 3, v42
	v_and_b32_e32 v34, 56, v0
	v_ashrrev_i32_e32 v43, 3, v42
	s_movk_i32 s6, 0x84
	v_lshlrev_b32_e32 v0, 1, v34
	s_cmp_lg_u64 s[46:47], 0
	v_mul_lo_u32 v3, v43, s6
	v_lshl_add_u64 v[0:1], s[28:29], 0, v[0:1]
	s_mov_b64 s[6:7], 0x2800000
	s_cselect_b64 s[0:1], -1, 0
	v_mul_u32_u24_e32 v4, 0x84, v34
	v_lshl_add_u64 v[38:39], v[0:1], 0, s[6:7]
	v_lshlrev_b32_e32 v0, 2, v43
	v_add3_u32 v44, s8, v4, v0
	s_lshl_b32 s10, s14, 5
	v_cndmask_b32_e64 v0, 0, 1, s[0:1]
	s_lshl_b32 s11, s97, 5
	s_movk_i32 s12, 0x2c00
	v_cmp_ne_u32_e64 s[0:1], 1, v0
	v_add_u32_e32 v45, v2, v3
	s_mov_b32 s13, s10
	s_branch .LBB0_1340

.Linvw1_skip10:
	s_barrier
.LBB0_1402:
	s_cmp_lt_i32 s30, 12
	s_cselect_b64 s[24:25], -1, 0
	s_and_b64 s[0:1], s[24:25], s[0:1]
	s_andn2_b64 vcc, exec, s[0:1]
	s_cbranch_vccnz .LBB0_1454
	s_add_u32 s36, s28, 0x4300000
	s_addc_u32 s37, s29, 0
	s_add_u32 s38, s28, 0xa300000
	s_addc_u32 s39, s29, 0
	s_add_u32 s44, s28, 0x6300000
	s_addc_u32 s45, s29, 0
	s_add_u32 s76, s28, 0x8300000
	s_addc_u32 s84, s29, 0
	s_add_u32 s46, s28, 0x578000
	s_addc_u32 s47, s29, 0
	s_lshl_b32 s0, s69, 9
	v_writelane_b32 v254, s96, 28
	s_add_i32 s86, s0, 0
	s_lshl_b32 s85, s69, 4
	s_add_i32 s86, s86, 0x18800
	v_readlane_b32 s15, v254, 0
	s_cmp_lt_u32 s15, 64
	s_cselect_b64 s[48:49], -1, 0
	s_cmpk_gt_u32 s15, 0x7f
	s_cselect_b64 s[0:1], -1, 0
	s_cmpk_gt_u32 s15, 0xbf
	s_cselect_b64 s[2:3], -1, 0
	s_cmpk_gt_u32 s15, 0xff
	s_cselect_b64 s[4:5], -1, 0
	s_cmpk_gt_u32 s15, 0x13f
	s_cselect_b64 s[6:7], -1, 0
	s_cmpk_gt_u32 s15, 0x17f
	s_cselect_b64 s[8:9], -1, 0
	s_cmpk_gt_u32 s15, 0x1bf
	s_cselect_b64 s[10:11], -1, 0
	s_cmpk_gt_u32 s15, 0x1ff
	s_cselect_b64 s[12:13], -1, 0
	s_lshr_b32 s15, s15, 7
	s_lshl_b32 s14, s69, 1
	s_lshl_b32 s18, s15, 5
	s_lshl_b32 s87, s69, 3
	s_and_b32 s14, s14, 2
	s_lshl_b32 s71, s15, 4
	s_add_i32 s88, s18, 0
	s_cmp_le_u32 s14, s15
	s_cselect_b64 s[50:51], -1, 0
	s_lshl_b32 s89, s14, 5
	s_lshl_b32 s90, s14, 4
	s_or_b32 s18, s14, 1
	s_cmp_lt_u32 s14, s15
	s_cselect_b64 s[60:61], -1, 0
	s_abs_i32 s91, s17
	v_cvt_f32_u32_e32 v0, s91
	s_lshl_b32 s14, s69, 5
	s_add_i32 s94, s14, 0
	s_sub_i32 s14, 0, s91
	v_rcp_iflag_f32_e32 v0, v0
	s_mov_b32 s63, 0
	s_lshl_b32 s92, s18, 5
	s_lshl_b32 s93, s18, 4
	v_mul_f32_e32 v0, 0x4f7ffffe, v0
	v_cvt_u32_f32_e32 v0, v0
	v_mov_b32_e32 v85, 0
	v_mov_b32_e32 v86, 0x358637bd
	s_mov_b32 s97, 0x800000
	v_readfirstlane_b32 s15, v0
	s_mul_i32 s14, s14, s15
	s_mul_hi_u32 s14, s15, s14
	s_add_i32 s95, s15, s14
	s_movk_i32 s77, 0x1000
	s_mov_b32 s56, 0x3f317217
	s_mov_b32 s57, 0x7f800000
	s_movk_i32 s54, 0x3000
	s_movk_i32 s55, 0x2000
	s_movk_i32 s68, 0x90
	s_add_i32 s69, 0, 0x12000
	s_movk_i32 s58, 0x110
	s_movk_i32 s59, 0x880
	s_movk_i32 s70, 0x480
	s_add_i32 s40, 0, 0x16400
	s_movk_i32 s41, 0x7fff
	s_movk_i32 s96, 0x240
	s_movk_i32 s52, 0x440
	v_mov_b32_e32 v108, 0x41b17218
	s_mov_b32 s53, 0
	s_mov_b32 s64, 0
	v_mbcnt_lo_u32_b32 v87, -1, 0
	v_mbcnt_hi_u32_b32 v87, -1, v87
	s_branch .LBB0_1406

.Linvw1_skip11:
	s_barrier
.LBB0_1504:
	s_cmp_lt_i32 s30, 13
	s_cselect_b64 s[4:5], -1, 0
	s_and_b64 s[0:1], s[4:5], s[0:1]
	s_andn2_b64 vcc, exec, s[0:1]
	s_cbranch_vccnz .LBB0_1550
	v_mbcnt_lo_u32_b32 v24, -1, 0
	v_mbcnt_hi_u32_b32 v24, -1, v24
	s_cmpk_lt_i32 s16, 0x100
	v_add_u32_e32 v0, s33, v24
	s_cselect_b64 s[6:7], -1, 0
	s_cmpk_gt_i32 s16, 0xff
	v_readfirstlane_b32 s40, v0
	s_cbranch_scc1 .LBB0_1508
	s_ashr_i32 s0, s16, 31
	s_lshr_b32 s0, s0, 29
	s_add_i32 s2, s16, s0
	s_and_b32 s0, s2, -8
	s_sub_i32 s3, s16, s0
	s_cmp_gt_i32 s3, -1
	s_cbranch_scc0 .LBB0_1509
	s_lshl_b32 s8, s3, 5
	s_cbranch_execz .LBB0_1510
	s_branch .LBB0_1511

.Linvw1_skip12:
	s_barrier
.LBB0_1600:
	s_cmp_lt_i32 s30, 14
	s_cselect_b64 s[8:9], -1, 0
	s_and_b64 s[0:1], s[8:9], s[0:1]
	s_andn2_b64 vcc, exec, s[0:1]
	s_cbranch_vccnz .LBB0_1674
	s_add_i32 s0, s17, -1
	s_cmp_lg_u32 s16, s0
	v_mbcnt_lo_u32_b32 v5, -1, 0
	v_mbcnt_hi_u32_b32 v5, -1, v5
	s_cbranch_scc1 .LBB0_1607
	s_lshl_b32 s0, s69, 1
	s_mov_b32 s1, 0
	s_lshl_b64 s[2:3], s[0:1], 12
	v_readlane_b32 s4, v254, 9
	v_readlane_b32 s5, v254, 10
	s_add_u32 s4, s4, s2
	v_lshlrev_b32_e32 v0, 2, v5
	s_addc_u32 s5, s5, s3
	v_readlane_b32 s6, v254, 21
	v_readlane_b32 s7, v254, 22
	s_add_u32 s6, s6, s2
	s_waitcnt lgkmcnt(0)
	v_ashrrev_i32_e32 v1, 31, v0
	s_addc_u32 s7, s7, s3
	v_lshlrev_b64 v[0:1], 2, v[0:1]
	s_waitcnt vmcnt(0)
	v_lshl_add_u64 v[38:39], s[6:7], 0, v[0:1]
	v_lshl_add_u64 v[2:3], s[4:5], 0, v[0:1]
	global_load_dwordx4 v[6:9], v[38:39], off
	global_load_dwordx4 v[10:13], v[2:3], off
	global_load_dwordx4 v[14:17], v[2:3], off offset:1024
	global_load_dwordx4 v[18:21], v[38:39], off offset:1024
	global_load_dwordx4 v[22:25], v[38:39], off offset:2048
	global_load_dwordx4 v[26:29], v[2:3], off offset:2048
	global_load_dwordx4 v[30:33], v[2:3], off offset:3072
	global_load_dwordx4 v[34:37], v[38:39], off offset:3072
	v_mbcnt_lo_u32_b32 v2, -1, 0
	v_mbcnt_hi_u32_b32 v2, -1, v2
	v_and_b32_e32 v4, 64, v2
	v_xor_b32_e32 v3, 16, v2
	v_add_u32_e32 v4, 64, v4
	v_xor_b32_e32 v38, 32, v2
	v_cmp_lt_i32_e32 vcc, v3, v4
	s_add_u32 s2, s96, s2
	v_readlane_b32 s4, v254, 23
	v_cndmask_b32_e32 v3, v2, v3, vcc
	v_cmp_lt_i32_e32 vcc, v38, v4
	v_lshlrev_b32_e32 v3, 2, v3
	s_addc_u32 s3, s4, s3
	v_cndmask_b32_e32 v2, v2, v38, vcc
	v_lshlrev_b32_e32 v2, 2, v2
	v_cmp_eq_u32_e32 vcc, 0, v5
	s_waitcnt vmcnt(6)
	v_pk_add_f32 v[12:13], v[12:13], v[8:9]
	v_pk_add_f32 v[10:11], v[10:11], v[6:7]
	s_waitcnt vmcnt(4)
	v_pk_add_f32 v[16:17], v[16:17], v[20:21]
	v_pk_add_f32 v[14:15], v[14:15], v[18:19]
	s_waitcnt vmcnt(2)
	v_pk_add_f32 v[20:21], v[28:29], v[24:25]
	v_pk_add_f32 v[18:19], v[26:27], v[22:23]
	v_mul_f32_e32 v4, v11, v11
	v_mul_f32_e32 v6, v13, v13
	v_mul_f32_e32 v7, v15, v15
	v_mul_f32_e32 v8, v17, v17
	s_waitcnt vmcnt(0)
	v_pk_add_f32 v[24:25], v[32:33], v[36:37]
	v_pk_add_f32 v[22:23], v[30:31], v[34:35]
	v_mul_f32_e32 v9, v19, v19
	v_mul_f32_e32 v26, v21, v21
	v_fmac_f32_e32 v4, v10, v10
	v_fmac_f32_e32 v6, v12, v12
	v_fmac_f32_e32 v7, v14, v14
	v_fmac_f32_e32 v8, v16, v16
	v_mul_f32_e32 v27, v23, v23
	v_mul_f32_e32 v28, v25, v25
	v_fmac_f32_e32 v9, v18, v18
	v_fmac_f32_e32 v26, v20, v20
	v_add_f32_e32 v4, v4, v6
	v_add_f32_e32 v6, v7, v8
	v_fmac_f32_e32 v27, v22, v22
	v_fmac_f32_e32 v28, v24, v24
	v_add_f32_e32 v7, v9, v26
	v_add_f32_e32 v4, v4, v6
	v_add_f32_e32 v4, v4, v7
	v_add_f32_e32 v6, v27, v28
	v_add_f32_e32 v4, v4, v6
	v_lshl_add_u64 v[8:9], s[2:3], 0, v[0:1]
	global_store_dwordx4 v[8:9], v[10:13], off
	global_store_dwordx4 v[8:9], v[14:17], off offset:1024
	global_store_dwordx4 v[8:9], v[18:21], off offset:2048
	global_store_dwordx4 v[8:9], v[22:25], off offset:3072
	v_add_f32_dpp v4, v4, v4 quad_perm:[1,0,3,2] row_mask:0xf bank_mask:0xf bound_ctrl:1
	s_nop 1
	v_add_f32_dpp v4, v4, v4 quad_perm:[2,3,0,1] row_mask:0xf bank_mask:0xf bound_ctrl:1
	s_nop 1
	v_add_f32_dpp v4, v4, v4 row_half_mirror row_mask:0xf bank_mask:0xf bound_ctrl:1
	s_nop 1
	v_add_f32_dpp v4, v4, v4 row_mirror row_mask:0xf bank_mask:0xf bound_ctrl:1
	ds_bpermute_b32 v6, v3, v4
	s_waitcnt lgkmcnt(0)
	v_add_f32_e32 v4, v4, v6
	ds_bpermute_b32 v6, v2, v4
	s_and_saveexec_b64 s[2:3], vcc
	s_cbranch_execz .LBB0_1604
	s_lshl_b32 s4, s0, 2
	s_waitcnt lgkmcnt(0)
	v_add_f32_e32 v4, v4, v6
	v_mov_b32_e32 v6, s4
	v_readlane_b32 s4, v254, 11
	v_readlane_b32 s5, v254, 12
	s_nop 4
	global_store_dword v6, v4, s[4:5]

.Linvw1_skip13:
	s_barrier
.LBB0_1724:
	s_cmp_lt_i32 s30, 15
	s_cselect_b64 s[10:11], -1, 0
	s_and_b64 s[0:1], s[10:11], s[0:1]
	s_andn2_b64 vcc, exec, s[0:1]
	s_cbranch_vccnz .LBB0_1808
	s_waitcnt lgkmcnt(0)
	v_mbcnt_lo_u32_b32 v1, -1, 0
	v_mbcnt_hi_u32_b32 v1, -1, v1
	s_cmpk_lg_i32 s17, 0x100
	v_add_u32_e32 v0, s33, v1
	s_cselect_b64 s[12:13], -1, 0
	s_cmpk_eq_i32 s17, 0x100
	v_readfirstlane_b32 s40, v0
	s_cbranch_scc1 .LBB0_1728
	s_mov_b64 s[0:1], 0
	s_cmpk_gt_i32 s16, 0x2bf
	s_mov_b64 s[6:7], 0
	s_cbranch_scc1 .LBB0_1729
	s_ashr_i32 s2, s16, 31
	s_lshr_b32 s2, s2, 29
	s_add_i32 s2, s16, s2
	s_ashr_i32 s3, s2, 3
	s_and_b32 s2, s2, -8
	s_sub_i32 s2, s16, s2
	s_cmp_lt_i32 s2, 0
	s_movk_i32 s4, 0x59
	s_cselect_b32 s4, s4, 0x58
	s_mul_i32 s2, s4, s2
	s_add_i32 s2, s2, s3
	s_mul_hi_i32 s3, s2, 0x2e8ba2e9
	s_lshr_b32 s4, s3, 31
	s_ashr_i32 s3, s3, 4
	s_add_i32 s3, s3, s4
	s_lshl_b32 s4, s3, 3
	s_mulk_i32 s3, 0x58
	s_sub_i32 s2, s2, s3
	s_bfe_i32 s3, s2, 0x80000
	s_bfe_u32 s3, s3, 0x3000c
	s_add_i32 s3, s2, s3
	s_bfe_i32 s5, s3, 0x80000
	s_and_b32 s3, s3, 0xf8
	s_sub_i32 s2, s2, s3
	s_sext_i32_i16 s5, s5
	s_sext_i32_i8 s2, s2
	s_add_i32 s97, s4, s2
	s_ashr_i32 s95, s5, 3
	s_lshl_b32 s4, s97, 8
	s_lshl_b32 s2, s95, 8
	s_mov_b64 s[6:7], -1
	s_branch .LBB0_1729

.LBB0_1825:
	v_readlane_b32 s4, v254, 5
	s_lshl_b32 s4, s4, 8
	v_readlane_b32 s6, v254, 3
	v_readlane_b32 s7, v254, 4
	s_add_u32 s4, s6, s4
	s_addc_u32 s5, s7, 0
	v_mov_b32_e32 v1, 0x1000
	v_mov_b32_e32 v3, 1
	global_atomic_add v3, v1, v3, s[4:5] offset:1024 sc0
	v_cvt_f32_u32_e32 v1, v2
	v_sub_u32_e32 v4, 0, v2
	v_rcp_iflag_f32_e32 v1, v1
	s_nop 0
	v_mul_f32_e32 v1, 0x4f7ffffe, v1
	v_cvt_u32_f32_e32 v1, v1
	v_mul_lo_u32 v4, v4, v1
	v_mul_hi_u32 v4, v1, v4
	v_add_u32_e32 v1, v1, v4
	s_waitcnt vmcnt(0)
	v_mul_hi_u32 v1, v3, v1
	v_mul_lo_u32 v4, v1, v2
	v_sub_u32_e32 v4, v3, v4
	v_add_u32_e32 v5, 1, v1
	v_cmp_ge_u32_e32 vcc, v4, v2
	v_add_u32_e32 v3, 1, v3
	s_nop 0
	v_cndmask_b32_e32 v1, v1, v5, vcc
	v_sub_u32_e32 v5, v4, v2
	v_cndmask_b32_e32 v4, v4, v5, vcc
	v_add_u32_e32 v5, 1, v1
	v_cmp_ge_u32_e32 vcc, v4, v2
	s_nop 1
	v_cndmask_b32_e32 v1, v1, v5, vcc
	v_mul_lo_u32 v4, v2, v1
	v_add_u32_e32 v2, v4, v2
	v_cmp_ne_u32_e32 vcc, v3, v2
	s_and_saveexec_b64 s[6:7], vcc
	s_xor_b64 s[6:7], exec, s[6:7]
	s_cbranch_execz .LBB0_1839
	s_waitcnt lgkmcnt(0)
	s_add_u32 s12, s28, 0x7500
	s_addc_u32 s13, s29, 0
	v_mov_b32_e32 v0, 0
	global_load_dword v0, v0, s[12:13] sc1
	s_waitcnt vmcnt(0)
	v_cmp_eq_u32_e32 vcc, v0, v1
	s_and_saveexec_b64 s[8:9], vcc
	s_cbranch_execz .LBB0_1838
	s_add_u32 s10, s28, 0x4200
	s_addc_u32 s11, s29, 0
	s_mov_b32 s31, 1
	s_mov_b64 s[14:15], 0
	v_mov_b32_e32 v0, 0
	s_branch .LBB0_1829

.Linvw1_skip14:
	s_barrier
.LBB0_1858:
	s_cmp_gt_i32 s30, 15
	s_cselect_b64 s[2:3], -1, 0
	s_xor_b64 s[0:1], s[0:1], -1
	s_or_b64 s[0:1], s[2:3], s[0:1]
	s_and_b64 vcc, exec, s[0:1]
	s_cbranch_vccnz .LBB0_1863
	v_mbcnt_lo_u32_b32 v8, -1, 0
	v_mbcnt_hi_u32_b32 v8, -1, v8
	s_cmpk_lt_i32 s16, 0x100
	v_add_u32_e32 v0, s33, v8
	s_cselect_b64 s[4:5], -1, 0
	s_cmpk_gt_i32 s16, 0xff
	v_readfirstlane_b32 s30, v0
	s_cbranch_scc1 .LBB0_1862
	s_ashr_i32 s0, s16, 31
	s_lshr_b32 s0, s0, 29
	s_add_i32 s6, s16, s0
	s_and_b32 s0, s6, -8
	s_sub_i32 s2, s16, s0
	s_cmp_gt_i32 s2, -1
	s_cbranch_scc0 .LBB0_1864
	s_lshl_b32 s3, s2, 5
	s_ashr_i32 s0, s6, 3
	s_cbranch_execz .LBB0_1865
	s_branch .LBB0_1866
